# v33 + residual GEMM epilogues: 16 residual-tile read-backs issued in two batches instead of a load-wait per row group
# speedup vs baseline: 1.0047x; 1.0002x over previous
.LBB0_498:
	v_and_b32_e32 v148, 64, v156
	v_xor_b32_e32 v147, 16, v156
	v_add_u32_e32 v148, 64, v148
	v_cmp_lt_i32_e32 vcc, v147, v148
	v_lshl_add_u32 v146, s68, 8, v150
	v_lshl_or_b32 v144, s24, 8, v152
	v_cndmask_b32_e32 v147, v156, v147, vcc
	v_lshlrev_b32_e32 v158, 2, v147
	v_xor_b32_e32 v147, 32, v156
	v_cmp_lt_i32_e32 vcc, v147, v148
	v_ashrrev_i32_e32 v145, 31, v144
	s_lshl_b32 s68, s24, 2
	v_cndmask_b32_e32 v147, v156, v147, vcc
	v_lshlrev_b32_e32 v157, 2, v147
	v_ashrrev_i32_e32 v147, 31, v146
	v_lshlrev_b64 v[148:149], 11, v[146:147]
	v_lshl_add_u64 v[148:149], s[48:49], 0, v[148:149]
	v_lshl_add_u64 v[148:149], v[144:145], 1, v[148:149]
	v_mov_b64_e32 v[206:207], v[148:149]
	global_load_dwordx4 v[168:171], v[148:149], off
	v_add_co_u32_e32 v204, vcc, 0x100, v148
	s_nop 1
	v_addc_co_u32_e32 v205, vcc, 0, v149, vcc
	global_load_dwordx4 v[172:175], v[204:205], off
	v_add_co_u32_e32 v204, vcc, 0x8000, v148
	s_nop 1
	v_addc_co_u32_e32 v205, vcc, 0, v149, vcc
	global_load_dwordx4 v[176:179], v[204:205], off
	v_add_co_u32_e32 v204, vcc, 0x8100, v148
	s_nop 1
	v_addc_co_u32_e32 v205, vcc, 0, v149, vcc
	global_load_dwordx4 v[180:183], v[204:205], off
	v_add_co_u32_e32 v204, vcc, 0x10000, v148
	s_nop 1
	v_addc_co_u32_e32 v205, vcc, 0, v149, vcc
	global_load_dwordx4 v[184:187], v[204:205], off
	v_add_co_u32_e32 v204, vcc, 0x10100, v148
	s_nop 1
	v_addc_co_u32_e32 v205, vcc, 0, v149, vcc
	global_load_dwordx4 v[188:191], v[204:205], off
	v_add_co_u32_e32 v204, vcc, 0x18000, v148
	s_nop 1
	v_addc_co_u32_e32 v205, vcc, 0, v149, vcc
	global_load_dwordx4 v[192:195], v[204:205], off
	v_add_co_u32_e32 v204, vcc, 0x18100, v148
	s_nop 1
	v_addc_co_u32_e32 v205, vcc, 0, v149, vcc
	global_load_dwordx4 v[196:199], v[204:205], off
	s_waitcnt vmcnt(0)
	s_nop 1
	v_mov_b64_e32 v[160:161], v[168:169]
	v_mov_b64_e32 v[162:163], v[170:171]
	s_ashr_i32 s69, s68, 31
	s_nop 1
	v_lshlrev_b32_e32 v164, 16, v160
	v_and_b32_e32 v165, 0xffff0000, v160
	v_lshlrev_b32_e32 v160, 16, v161
	v_and_b32_e32 v161, 0xffff0000, v161
	v_lshlrev_b32_e32 v166, 16, v162
	v_and_b32_e32 v167, 0xffff0000, v162
	v_lshlrev_b32_e32 v162, 16, v163
	v_and_b32_e32 v163, 0xffff0000, v163
	v_pk_add_f32 v[126:127], v[126:127], v[160:161]
	v_pk_add_f32 v[124:125], v[124:125], v[164:165]
	v_pk_add_f32 v[160:161], v[122:123], v[162:163]
	v_pk_add_f32 v[122:123], v[120:121], v[166:167]
	v_mul_f32_e32 v120, v125, v125
	v_mul_f32_e32 v121, v127, v127
	v_fmac_f32_e32 v120, v124, v124
	v_fmac_f32_e32 v121, v126, v126
	v_add_f32_e32 v120, v120, v121
	v_mul_f32_e32 v121, v123, v123
	v_fmac_f32_e32 v121, v122, v122
	v_add_f32_e32 v120, v121, v120
	v_mul_f32_e32 v121, v161, v161
	v_fmac_f32_e32 v121, v160, v160
	v_add_f32_e32 v159, v121, v120
	v_cvt_pk_bf16_f32 v120, v124, v125
	v_cvt_pk_bf16_f32 v121, v126, v127
	v_cvt_pk_bf16_f32 v122, v122, v123
	v_cvt_pk_bf16_f32 v123, v160, v161
	global_store_dwordx4 v[148:149], v[120:123], off
	s_nop 1
	v_mov_b64_e32 v[120:121], v[172:173]
	v_mov_b64_e32 v[122:123], v[174:175]
	s_nop 1
	v_lshlrev_b32_e32 v124, 16, v120
	v_and_b32_e32 v125, 0xffff0000, v120
	v_lshlrev_b32_e32 v120, 16, v121
	v_and_b32_e32 v121, 0xffff0000, v121
	v_lshlrev_b32_e32 v126, 16, v122
	v_and_b32_e32 v127, 0xffff0000, v122
	v_lshlrev_b32_e32 v122, 16, v123
	v_and_b32_e32 v123, 0xffff0000, v123
	v_pk_add_f32 v[118:119], v[118:119], v[120:121]
	v_pk_add_f32 v[116:117], v[116:117], v[124:125]
	v_pk_add_f32 v[120:121], v[114:115], v[122:123]
	v_pk_add_f32 v[114:115], v[112:113], v[126:127]
	v_mul_f32_e32 v112, v117, v117
	v_mul_f32_e32 v113, v119, v119
	v_fmac_f32_e32 v112, v116, v116
	v_fmac_f32_e32 v113, v118, v118
	v_add_f32_e32 v112, v112, v113
	v_mul_f32_e32 v113, v115, v115
	v_fmac_f32_e32 v113, v114, v114
	v_add_f32_e32 v112, v113, v112
	v_mul_f32_e32 v113, v121, v121
	v_fmac_f32_e32 v113, v120, v120
	v_add_f32_e32 v112, v113, v112
	v_add_f32_e32 v122, v159, v112
	v_cvt_pk_bf16_f32 v112, v116, v117
	v_cvt_pk_bf16_f32 v113, v118, v119
	v_cvt_pk_bf16_f32 v114, v114, v115
	v_cvt_pk_bf16_f32 v115, v120, v121
	global_store_dwordx4 v[148:149], v[112:115], off offset:256
	ds_bpermute_b32 v112, v158, v122
	s_waitcnt lgkmcnt(0)
	v_add_f32_e32 v112, v122, v112
	ds_bpermute_b32 v113, v157, v112
	s_and_saveexec_b64 s[6:7], s[4:5]
	s_cbranch_execz .LBB0_500
	s_waitcnt lgkmcnt(0)
	v_add_f32_e32 v114, v112, v113
	v_lshlrev_b64 v[112:113], 6, v[146:147]
	v_lshl_add_u64 v[112:113], s[62:63], 0, v[112:113]
	v_lshl_add_u64 v[112:113], s[68:69], 2, v[112:113]
	s_lshl_b32 s24, s57, 2
	v_lshl_add_u64 v[112:113], v[112:113], 0, s[24:25]
	global_store_dword v[112:113], v114, off
.LBB0_500:
	s_or_b64 exec, exec, s[6:7]
	v_or_b32_e32 v112, 16, v146
	s_waitcnt lgkmcnt(0)
	v_ashrrev_i32_e32 v113, 31, v112
	v_lshlrev_b64 v[114:115], 11, v[112:113]
	v_lshl_add_u64 v[114:115], s[48:49], 0, v[114:115]
	v_lshl_add_u64 v[114:115], v[144:145], 1, v[114:115]
	s_nop 1
	v_mov_b64_e32 v[116:117], v[176:177]
	v_mov_b64_e32 v[118:119], v[178:179]
	s_nop 1
	v_lshlrev_b32_e32 v120, 16, v116
	v_and_b32_e32 v121, 0xffff0000, v116
	v_lshlrev_b32_e32 v116, 16, v117
	v_and_b32_e32 v117, 0xffff0000, v117
	v_lshlrev_b32_e32 v122, 16, v118
	v_and_b32_e32 v123, 0xffff0000, v118
	v_lshlrev_b32_e32 v118, 16, v119
	v_and_b32_e32 v119, 0xffff0000, v119
	v_pk_add_f32 v[110:111], v[110:111], v[116:117]
	v_pk_add_f32 v[108:109], v[108:109], v[120:121]
	v_pk_add_f32 v[116:117], v[106:107], v[118:119]
	v_pk_add_f32 v[106:107], v[104:105], v[122:123]
	v_mul_f32_e32 v104, v109, v109
	v_mul_f32_e32 v105, v111, v111
	v_fmac_f32_e32 v104, v108, v108
	v_fmac_f32_e32 v105, v110, v110
	v_add_f32_e32 v104, v104, v105
	v_mul_f32_e32 v105, v107, v107
	v_fmac_f32_e32 v105, v106, v106
	v_add_f32_e32 v104, v105, v104
	v_mul_f32_e32 v105, v117, v117
	v_fmac_f32_e32 v105, v116, v116
	v_add_f32_e32 v118, v105, v104
	v_cvt_pk_bf16_f32 v104, v108, v109
	v_cvt_pk_bf16_f32 v105, v110, v111
	v_cvt_pk_bf16_f32 v106, v106, v107
	v_cvt_pk_bf16_f32 v107, v116, v117
	global_store_dwordx4 v[114:115], v[104:107], off
	s_nop 1
	v_mov_b64_e32 v[104:105], v[180:181]
	v_mov_b64_e32 v[106:107], v[182:183]
	s_nop 1
	v_lshlrev_b32_e32 v108, 16, v104
	v_and_b32_e32 v109, 0xffff0000, v104
	v_lshlrev_b32_e32 v104, 16, v105
	v_and_b32_e32 v105, 0xffff0000, v105
	v_lshlrev_b32_e32 v110, 16, v106
	v_and_b32_e32 v111, 0xffff0000, v106
	v_lshlrev_b32_e32 v106, 16, v107
	v_and_b32_e32 v107, 0xffff0000, v107
	v_pk_add_f32 v[102:103], v[102:103], v[104:105]
	v_pk_add_f32 v[100:101], v[100:101], v[108:109]
	v_pk_add_f32 v[104:105], v[98:99], v[106:107]
	v_pk_add_f32 v[98:99], v[96:97], v[110:111]
	v_mul_f32_e32 v96, v101, v101
	v_mul_f32_e32 v97, v103, v103
	v_fmac_f32_e32 v96, v100, v100
	v_fmac_f32_e32 v97, v102, v102
	v_add_f32_e32 v96, v96, v97
	v_mul_f32_e32 v97, v99, v99
	v_fmac_f32_e32 v97, v98, v98
	v_add_f32_e32 v96, v97, v96
	v_mul_f32_e32 v97, v105, v105
	v_fmac_f32_e32 v97, v104, v104
	v_add_f32_e32 v96, v97, v96
	v_add_f32_e32 v106, v118, v96
	v_cvt_pk_bf16_f32 v96, v100, v101
	v_cvt_pk_bf16_f32 v97, v102, v103
	v_cvt_pk_bf16_f32 v98, v98, v99
	v_cvt_pk_bf16_f32 v99, v104, v105
	global_store_dwordx4 v[114:115], v[96:99], off offset:256
	ds_bpermute_b32 v96, v158, v106
	s_waitcnt lgkmcnt(0)
	v_add_f32_e32 v96, v106, v96
	ds_bpermute_b32 v97, v157, v96
	s_and_saveexec_b64 s[6:7], s[4:5]
	s_cbranch_execz .LBB0_502
	s_waitcnt lgkmcnt(0)
	v_add_f32_e32 v98, v96, v97
	v_lshlrev_b64 v[96:97], 6, v[112:113]
	v_lshl_add_u64 v[96:97], s[62:63], 0, v[96:97]
	v_lshl_add_u64 v[96:97], s[68:69], 2, v[96:97]
	s_lshl_b32 s24, s57, 2
	v_lshl_add_u64 v[96:97], v[96:97], 0, s[24:25]
	global_store_dword v[96:97], v98, off
.LBB0_502:
	s_or_b64 exec, exec, s[6:7]
	v_or_b32_e32 v96, 32, v146
	s_waitcnt lgkmcnt(0)
	v_ashrrev_i32_e32 v97, 31, v96
	v_lshlrev_b64 v[98:99], 11, v[96:97]
	v_lshl_add_u64 v[98:99], s[48:49], 0, v[98:99]
	v_lshl_add_u64 v[98:99], v[144:145], 1, v[98:99]
	s_nop 1
	v_mov_b64_e32 v[100:101], v[184:185]
	v_mov_b64_e32 v[102:103], v[186:187]
	s_nop 1
	v_lshlrev_b32_e32 v104, 16, v100
	v_and_b32_e32 v105, 0xffff0000, v100
	v_lshlrev_b32_e32 v100, 16, v101
	v_and_b32_e32 v101, 0xffff0000, v101
	v_lshlrev_b32_e32 v106, 16, v102
	v_and_b32_e32 v107, 0xffff0000, v102
	v_lshlrev_b32_e32 v102, 16, v103
	v_and_b32_e32 v103, 0xffff0000, v103
	v_pk_add_f32 v[94:95], v[94:95], v[100:101]
	v_pk_add_f32 v[92:93], v[92:93], v[104:105]
	v_pk_add_f32 v[100:101], v[90:91], v[102:103]
	v_pk_add_f32 v[90:91], v[88:89], v[106:107]
	v_mul_f32_e32 v88, v93, v93
	v_mul_f32_e32 v89, v95, v95
	v_fmac_f32_e32 v88, v92, v92
	v_fmac_f32_e32 v89, v94, v94
	v_add_f32_e32 v88, v88, v89
	v_mul_f32_e32 v89, v91, v91
	v_fmac_f32_e32 v89, v90, v90
	v_add_f32_e32 v88, v89, v88
	v_mul_f32_e32 v89, v101, v101
	v_fmac_f32_e32 v89, v100, v100
	v_add_f32_e32 v102, v89, v88
	v_cvt_pk_bf16_f32 v88, v92, v93
	v_cvt_pk_bf16_f32 v89, v94, v95
	v_cvt_pk_bf16_f32 v90, v90, v91
	v_cvt_pk_bf16_f32 v91, v100, v101
	global_store_dwordx4 v[98:99], v[88:91], off
	s_nop 1
	v_mov_b64_e32 v[88:89], v[188:189]
	v_mov_b64_e32 v[90:91], v[190:191]
	s_nop 1
	v_lshlrev_b32_e32 v92, 16, v88
	v_and_b32_e32 v93, 0xffff0000, v88
	v_lshlrev_b32_e32 v88, 16, v89
	v_and_b32_e32 v89, 0xffff0000, v89
	v_lshlrev_b32_e32 v94, 16, v90
	v_and_b32_e32 v95, 0xffff0000, v90
	v_lshlrev_b32_e32 v90, 16, v91
	v_and_b32_e32 v91, 0xffff0000, v91
	v_pk_add_f32 v[86:87], v[86:87], v[88:89]
	v_pk_add_f32 v[84:85], v[84:85], v[92:93]
	v_pk_add_f32 v[88:89], v[82:83], v[90:91]
	v_pk_add_f32 v[82:83], v[80:81], v[94:95]
	v_mul_f32_e32 v80, v85, v85
	v_mul_f32_e32 v81, v87, v87
	v_fmac_f32_e32 v80, v84, v84
	v_fmac_f32_e32 v81, v86, v86
	v_add_f32_e32 v80, v80, v81
	v_mul_f32_e32 v81, v83, v83
	v_fmac_f32_e32 v81, v82, v82
	v_add_f32_e32 v80, v81, v80
	v_mul_f32_e32 v81, v89, v89
	v_fmac_f32_e32 v81, v88, v88
	v_add_f32_e32 v80, v81, v80
	v_add_f32_e32 v90, v102, v80
	v_cvt_pk_bf16_f32 v80, v84, v85
	v_cvt_pk_bf16_f32 v81, v86, v87
	v_cvt_pk_bf16_f32 v82, v82, v83
	v_cvt_pk_bf16_f32 v83, v88, v89
	global_store_dwordx4 v[98:99], v[80:83], off offset:256
	ds_bpermute_b32 v80, v158, v90
	s_waitcnt lgkmcnt(0)
	v_add_f32_e32 v80, v90, v80
	ds_bpermute_b32 v81, v157, v80
	s_and_saveexec_b64 s[6:7], s[4:5]
	s_cbranch_execz .LBB0_504
	s_waitcnt lgkmcnt(0)
	v_add_f32_e32 v82, v80, v81
	v_lshlrev_b64 v[80:81], 6, v[96:97]
	v_lshl_add_u64 v[80:81], s[62:63], 0, v[80:81]
	v_lshl_add_u64 v[80:81], s[68:69], 2, v[80:81]
	s_lshl_b32 s24, s57, 2
	v_lshl_add_u64 v[80:81], v[80:81], 0, s[24:25]
	global_store_dword v[80:81], v82, off
.LBB0_504:
	s_or_b64 exec, exec, s[6:7]
	v_or_b32_e32 v80, 48, v146
	s_waitcnt lgkmcnt(0)
	v_ashrrev_i32_e32 v81, 31, v80
	v_lshlrev_b64 v[82:83], 11, v[80:81]
	v_lshl_add_u64 v[82:83], s[48:49], 0, v[82:83]
	v_lshl_add_u64 v[82:83], v[144:145], 1, v[82:83]
	s_nop 1
	v_mov_b64_e32 v[84:85], v[192:193]
	v_mov_b64_e32 v[86:87], v[194:195]
	s_nop 1
	v_lshlrev_b32_e32 v88, 16, v84
	v_and_b32_e32 v89, 0xffff0000, v84
	v_lshlrev_b32_e32 v84, 16, v85
	v_and_b32_e32 v85, 0xffff0000, v85
	v_lshlrev_b32_e32 v90, 16, v86
	v_and_b32_e32 v91, 0xffff0000, v86
	v_lshlrev_b32_e32 v86, 16, v87
	v_and_b32_e32 v87, 0xffff0000, v87
	v_pk_add_f32 v[78:79], v[78:79], v[84:85]
	v_pk_add_f32 v[76:77], v[76:77], v[88:89]
	v_pk_add_f32 v[84:85], v[74:75], v[86:87]
	v_pk_add_f32 v[74:75], v[72:73], v[90:91]
	v_mul_f32_e32 v72, v77, v77
	v_mul_f32_e32 v73, v79, v79
	v_fmac_f32_e32 v72, v76, v76
	v_fmac_f32_e32 v73, v78, v78
	v_add_f32_e32 v72, v72, v73
	v_mul_f32_e32 v73, v75, v75
	v_fmac_f32_e32 v73, v74, v74
	v_add_f32_e32 v72, v73, v72
	v_mul_f32_e32 v73, v85, v85
	v_fmac_f32_e32 v73, v84, v84
	v_add_f32_e32 v86, v73, v72
	v_cvt_pk_bf16_f32 v72, v76, v77
	v_cvt_pk_bf16_f32 v73, v78, v79
	v_cvt_pk_bf16_f32 v74, v74, v75
	v_cvt_pk_bf16_f32 v75, v84, v85
	global_store_dwordx4 v[82:83], v[72:75], off
	s_nop 1
	v_mov_b64_e32 v[72:73], v[196:197]
	v_mov_b64_e32 v[74:75], v[198:199]
	s_nop 1
	v_lshlrev_b32_e32 v76, 16, v72
	v_and_b32_e32 v77, 0xffff0000, v72
	v_lshlrev_b32_e32 v72, 16, v73
	v_and_b32_e32 v73, 0xffff0000, v73
	v_lshlrev_b32_e32 v78, 16, v74
	v_and_b32_e32 v79, 0xffff0000, v74
	v_lshlrev_b32_e32 v74, 16, v75
	v_and_b32_e32 v75, 0xffff0000, v75
	v_pk_add_f32 v[70:71], v[70:71], v[72:73]
	v_pk_add_f32 v[68:69], v[68:69], v[76:77]
	v_pk_add_f32 v[72:73], v[66:67], v[74:75]
	v_pk_add_f32 v[66:67], v[64:65], v[78:79]
	v_mul_f32_e32 v64, v69, v69
	v_mul_f32_e32 v65, v71, v71
	v_fmac_f32_e32 v64, v68, v68
	v_fmac_f32_e32 v65, v70, v70
	v_add_f32_e32 v64, v64, v65
	v_mul_f32_e32 v65, v67, v67
	v_fmac_f32_e32 v65, v66, v66
	v_add_f32_e32 v64, v65, v64
	v_mul_f32_e32 v65, v73, v73
	v_fmac_f32_e32 v65, v72, v72
	v_add_f32_e32 v64, v65, v64
	v_add_f32_e32 v74, v86, v64
	v_cvt_pk_bf16_f32 v64, v68, v69
	v_cvt_pk_bf16_f32 v65, v70, v71
	v_cvt_pk_bf16_f32 v66, v66, v67
	v_cvt_pk_bf16_f32 v67, v72, v73
	global_store_dwordx4 v[82:83], v[64:67], off offset:256
	ds_bpermute_b32 v64, v158, v74
	s_waitcnt lgkmcnt(0)
	v_add_f32_e32 v64, v74, v64
	ds_bpermute_b32 v65, v157, v64
	s_and_saveexec_b64 s[6:7], s[4:5]
	s_cbranch_execz .LBB0_506
	s_waitcnt lgkmcnt(0)
	v_add_f32_e32 v66, v64, v65
	v_lshlrev_b64 v[64:65], 6, v[80:81]
	v_lshl_add_u64 v[64:65], s[62:63], 0, v[64:65]
	v_lshl_add_u64 v[64:65], s[68:69], 2, v[64:65]
	s_lshl_b32 s24, s57, 2
	v_lshl_add_u64 v[64:65], v[64:65], 0, s[24:25]
	global_store_dword v[64:65], v66, off
.LBB0_506:
	s_or_b64 exec, exec, s[6:7]
	v_add_u32_e32 v64, 0x80, v146
	s_waitcnt lgkmcnt(0)
	v_ashrrev_i32_e32 v65, 31, v64
	v_lshlrev_b64 v[66:67], 11, v[64:65]
	v_lshl_add_u64 v[66:67], s[48:49], 0, v[66:67]
	v_lshl_add_u64 v[66:67], v[144:145], 1, v[66:67]
	v_add_co_u32_e32 v204, vcc, 0x40000, v206
	s_nop 1
	v_addc_co_u32_e32 v205, vcc, 0, v207, vcc
	global_load_dwordx4 v[168:171], v[204:205], off
	v_add_co_u32_e32 v204, vcc, 0x40100, v206
	s_nop 1
	v_addc_co_u32_e32 v205, vcc, 0, v207, vcc
	global_load_dwordx4 v[172:175], v[204:205], off
	v_add_co_u32_e32 v204, vcc, 0x48000, v206
	s_nop 1
	v_addc_co_u32_e32 v205, vcc, 0, v207, vcc
	global_load_dwordx4 v[176:179], v[204:205], off
	v_add_co_u32_e32 v204, vcc, 0x48100, v206
	s_nop 1
	v_addc_co_u32_e32 v205, vcc, 0, v207, vcc
	global_load_dwordx4 v[180:183], v[204:205], off
	v_add_co_u32_e32 v204, vcc, 0x50000, v206
	s_nop 1
	v_addc_co_u32_e32 v205, vcc, 0, v207, vcc
	global_load_dwordx4 v[184:187], v[204:205], off
	v_add_co_u32_e32 v204, vcc, 0x50100, v206
	s_nop 1
	v_addc_co_u32_e32 v205, vcc, 0, v207, vcc
	global_load_dwordx4 v[188:191], v[204:205], off
	v_add_co_u32_e32 v204, vcc, 0x58000, v206
	s_nop 1
	v_addc_co_u32_e32 v205, vcc, 0, v207, vcc
	global_load_dwordx4 v[192:195], v[204:205], off
	v_add_co_u32_e32 v204, vcc, 0x58100, v206
	s_nop 1
	v_addc_co_u32_e32 v205, vcc, 0, v207, vcc
	global_load_dwordx4 v[196:199], v[204:205], off
	s_waitcnt vmcnt(0)
	s_nop 1
	v_mov_b64_e32 v[68:69], v[168:169]
	v_mov_b64_e32 v[70:71], v[170:171]
	s_nop 1
	v_lshlrev_b32_e32 v72, 16, v68
	v_and_b32_e32 v73, 0xffff0000, v68
	v_lshlrev_b32_e32 v68, 16, v69
	v_and_b32_e32 v69, 0xffff0000, v69
	v_lshlrev_b32_e32 v74, 16, v70
	v_and_b32_e32 v75, 0xffff0000, v70
	v_lshlrev_b32_e32 v70, 16, v71
	v_and_b32_e32 v71, 0xffff0000, v71
	v_pk_add_f32 v[62:63], v[62:63], v[68:69]
	v_pk_add_f32 v[60:61], v[60:61], v[72:73]
	v_pk_add_f32 v[68:69], v[58:59], v[70:71]
	v_pk_add_f32 v[58:59], v[56:57], v[74:75]
	v_mul_f32_e32 v56, v61, v61
	v_mul_f32_e32 v57, v63, v63
	v_fmac_f32_e32 v56, v60, v60
	v_fmac_f32_e32 v57, v62, v62
	v_add_f32_e32 v56, v56, v57
	v_mul_f32_e32 v57, v59, v59
	v_fmac_f32_e32 v57, v58, v58
	v_add_f32_e32 v56, v57, v56
	v_mul_f32_e32 v57, v69, v69
	v_fmac_f32_e32 v57, v68, v68
	v_add_f32_e32 v70, v57, v56
	v_cvt_pk_bf16_f32 v56, v60, v61
	v_cvt_pk_bf16_f32 v57, v62, v63
	v_cvt_pk_bf16_f32 v58, v58, v59
	v_cvt_pk_bf16_f32 v59, v68, v69
	global_store_dwordx4 v[66:67], v[56:59], off
	s_nop 1
	v_mov_b64_e32 v[56:57], v[172:173]
	v_mov_b64_e32 v[58:59], v[174:175]
	s_nop 1
	v_lshlrev_b32_e32 v60, 16, v56
	v_and_b32_e32 v61, 0xffff0000, v56
	v_lshlrev_b32_e32 v56, 16, v57
	v_and_b32_e32 v57, 0xffff0000, v57
	v_lshlrev_b32_e32 v62, 16, v58
	v_and_b32_e32 v63, 0xffff0000, v58
	v_lshlrev_b32_e32 v58, 16, v59
	v_and_b32_e32 v59, 0xffff0000, v59
	v_pk_add_f32 v[54:55], v[54:55], v[56:57]
	v_pk_add_f32 v[52:53], v[52:53], v[60:61]
	v_pk_add_f32 v[56:57], v[50:51], v[58:59]
	v_pk_add_f32 v[50:51], v[48:49], v[62:63]
	v_mul_f32_e32 v48, v53, v53
	v_mul_f32_e32 v49, v55, v55
	v_fmac_f32_e32 v48, v52, v52
	v_fmac_f32_e32 v49, v54, v54
	v_add_f32_e32 v48, v48, v49
	v_mul_f32_e32 v49, v51, v51
	v_fmac_f32_e32 v49, v50, v50
	v_add_f32_e32 v48, v49, v48
	v_mul_f32_e32 v49, v57, v57
	v_fmac_f32_e32 v49, v56, v56
	v_add_f32_e32 v48, v49, v48
	v_add_f32_e32 v58, v70, v48
	v_cvt_pk_bf16_f32 v48, v52, v53
	v_cvt_pk_bf16_f32 v49, v54, v55
	v_cvt_pk_bf16_f32 v50, v50, v51
	v_cvt_pk_bf16_f32 v51, v56, v57
	global_store_dwordx4 v[66:67], v[48:51], off offset:256
	ds_bpermute_b32 v48, v158, v58
	s_waitcnt lgkmcnt(0)
	v_add_f32_e32 v48, v58, v48
	ds_bpermute_b32 v49, v157, v48
	s_and_saveexec_b64 s[6:7], s[4:5]
	s_cbranch_execz .LBB0_508
	s_waitcnt lgkmcnt(0)
	v_add_f32_e32 v50, v48, v49
	v_lshlrev_b64 v[48:49], 6, v[64:65]
	v_lshl_add_u64 v[48:49], s[62:63], 0, v[48:49]
	v_lshl_add_u64 v[48:49], s[68:69], 2, v[48:49]
	s_lshl_b32 s24, s57, 2
	v_lshl_add_u64 v[48:49], v[48:49], 0, s[24:25]
	global_store_dword v[48:49], v50, off
.LBB0_508:
	s_or_b64 exec, exec, s[6:7]
	v_add_u32_e32 v48, 0x90, v146
	s_waitcnt lgkmcnt(0)
	v_ashrrev_i32_e32 v49, 31, v48
	v_lshlrev_b64 v[50:51], 11, v[48:49]
	v_lshl_add_u64 v[50:51], s[48:49], 0, v[50:51]
	v_lshl_add_u64 v[50:51], v[144:145], 1, v[50:51]
	s_nop 1
	v_mov_b64_e32 v[52:53], v[176:177]
	v_mov_b64_e32 v[54:55], v[178:179]
	s_nop 1
	v_lshlrev_b32_e32 v56, 16, v52
	v_and_b32_e32 v57, 0xffff0000, v52
	v_lshlrev_b32_e32 v52, 16, v53
	v_and_b32_e32 v53, 0xffff0000, v53
	v_lshlrev_b32_e32 v58, 16, v54
	v_and_b32_e32 v59, 0xffff0000, v54
	v_lshlrev_b32_e32 v54, 16, v55
	v_and_b32_e32 v55, 0xffff0000, v55
	v_pk_add_f32 v[46:47], v[46:47], v[52:53]
	v_pk_add_f32 v[44:45], v[44:45], v[56:57]
	v_pk_add_f32 v[52:53], v[42:43], v[54:55]
	v_pk_add_f32 v[42:43], v[40:41], v[58:59]
	v_mul_f32_e32 v40, v45, v45
	v_mul_f32_e32 v41, v47, v47
	v_fmac_f32_e32 v40, v44, v44
	v_fmac_f32_e32 v41, v46, v46
	v_add_f32_e32 v40, v40, v41
	v_mul_f32_e32 v41, v43, v43
	v_fmac_f32_e32 v41, v42, v42
	v_add_f32_e32 v40, v41, v40
	v_mul_f32_e32 v41, v53, v53
	v_fmac_f32_e32 v41, v52, v52
	v_add_f32_e32 v54, v41, v40
	v_cvt_pk_bf16_f32 v40, v44, v45
	v_cvt_pk_bf16_f32 v41, v46, v47
	v_cvt_pk_bf16_f32 v42, v42, v43
	v_cvt_pk_bf16_f32 v43, v52, v53
	global_store_dwordx4 v[50:51], v[40:43], off
	s_nop 1
	v_mov_b64_e32 v[40:41], v[180:181]
	v_mov_b64_e32 v[42:43], v[182:183]
	s_nop 1
	v_lshlrev_b32_e32 v44, 16, v40
	v_and_b32_e32 v45, 0xffff0000, v40
	v_lshlrev_b32_e32 v40, 16, v41
	v_and_b32_e32 v41, 0xffff0000, v41
	v_lshlrev_b32_e32 v46, 16, v42
	v_and_b32_e32 v47, 0xffff0000, v42
	v_lshlrev_b32_e32 v42, 16, v43
	v_and_b32_e32 v43, 0xffff0000, v43
	v_pk_add_f32 v[38:39], v[38:39], v[40:41]
	v_pk_add_f32 v[36:37], v[36:37], v[44:45]
	v_pk_add_f32 v[40:41], v[34:35], v[42:43]
	v_pk_add_f32 v[34:35], v[32:33], v[46:47]
	v_mul_f32_e32 v32, v37, v37
	v_mul_f32_e32 v33, v39, v39
	v_fmac_f32_e32 v32, v36, v36
	v_fmac_f32_e32 v33, v38, v38
	v_add_f32_e32 v32, v32, v33
	v_mul_f32_e32 v33, v35, v35
	v_fmac_f32_e32 v33, v34, v34
	v_add_f32_e32 v32, v33, v32
	v_mul_f32_e32 v33, v41, v41
	v_fmac_f32_e32 v33, v40, v40
	v_add_f32_e32 v32, v33, v32
	v_add_f32_e32 v42, v54, v32
	v_cvt_pk_bf16_f32 v32, v36, v37
	v_cvt_pk_bf16_f32 v33, v38, v39
	v_cvt_pk_bf16_f32 v34, v34, v35
	v_cvt_pk_bf16_f32 v35, v40, v41
	global_store_dwordx4 v[50:51], v[32:35], off offset:256
	ds_bpermute_b32 v32, v158, v42
	s_waitcnt lgkmcnt(0)
	v_add_f32_e32 v32, v42, v32
	ds_bpermute_b32 v33, v157, v32
	s_and_saveexec_b64 s[6:7], s[4:5]
	s_cbranch_execz .LBB0_510
	s_waitcnt lgkmcnt(0)
	v_add_f32_e32 v34, v32, v33
	v_lshlrev_b64 v[32:33], 6, v[48:49]
	v_lshl_add_u64 v[32:33], s[62:63], 0, v[32:33]
	v_lshl_add_u64 v[32:33], s[68:69], 2, v[32:33]
	s_lshl_b32 s24, s57, 2
	v_lshl_add_u64 v[32:33], v[32:33], 0, s[24:25]
	global_store_dword v[32:33], v34, off
.LBB0_510:
	s_or_b64 exec, exec, s[6:7]
	v_add_u32_e32 v32, 0xa0, v146
	s_waitcnt lgkmcnt(0)
	v_ashrrev_i32_e32 v33, 31, v32
	v_lshlrev_b64 v[34:35], 11, v[32:33]
	v_lshl_add_u64 v[34:35], s[48:49], 0, v[34:35]
	v_lshl_add_u64 v[34:35], v[144:145], 1, v[34:35]
	s_nop 1
	v_mov_b64_e32 v[36:37], v[184:185]
	v_mov_b64_e32 v[38:39], v[186:187]
	s_nop 1
	v_lshlrev_b32_e32 v40, 16, v36
	v_and_b32_e32 v41, 0xffff0000, v36
	v_lshlrev_b32_e32 v36, 16, v37
	v_and_b32_e32 v37, 0xffff0000, v37
	v_lshlrev_b32_e32 v42, 16, v38
	v_and_b32_e32 v43, 0xffff0000, v38
	v_lshlrev_b32_e32 v38, 16, v39
	v_and_b32_e32 v39, 0xffff0000, v39
	v_pk_add_f32 v[30:31], v[30:31], v[36:37]
	v_pk_add_f32 v[28:29], v[28:29], v[40:41]
	v_pk_add_f32 v[36:37], v[26:27], v[38:39]
	v_pk_add_f32 v[26:27], v[24:25], v[42:43]
	v_mul_f32_e32 v24, v29, v29
	v_mul_f32_e32 v25, v31, v31
	v_fmac_f32_e32 v24, v28, v28
	v_fmac_f32_e32 v25, v30, v30
	v_add_f32_e32 v24, v24, v25
	v_mul_f32_e32 v25, v27, v27
	v_fmac_f32_e32 v25, v26, v26
	v_add_f32_e32 v24, v25, v24
	v_mul_f32_e32 v25, v37, v37
	v_fmac_f32_e32 v25, v36, v36
	v_add_f32_e32 v38, v25, v24
	v_cvt_pk_bf16_f32 v24, v28, v29
	v_cvt_pk_bf16_f32 v25, v30, v31
	v_cvt_pk_bf16_f32 v26, v26, v27
	v_cvt_pk_bf16_f32 v27, v36, v37
	global_store_dwordx4 v[34:35], v[24:27], off
	s_nop 1
	v_mov_b64_e32 v[24:25], v[188:189]
	v_mov_b64_e32 v[26:27], v[190:191]
	s_nop 1
	v_lshlrev_b32_e32 v28, 16, v24
	v_and_b32_e32 v29, 0xffff0000, v24
	v_lshlrev_b32_e32 v24, 16, v25
	v_and_b32_e32 v25, 0xffff0000, v25
	v_lshlrev_b32_e32 v30, 16, v26
	v_and_b32_e32 v31, 0xffff0000, v26
	v_lshlrev_b32_e32 v26, 16, v27
	v_and_b32_e32 v27, 0xffff0000, v27
	v_pk_add_f32 v[22:23], v[22:23], v[24:25]
	v_pk_add_f32 v[20:21], v[20:21], v[28:29]
	v_pk_add_f32 v[24:25], v[18:19], v[26:27]
	v_pk_add_f32 v[18:19], v[16:17], v[30:31]
	v_mul_f32_e32 v16, v21, v21
	v_mul_f32_e32 v17, v23, v23
	v_fmac_f32_e32 v16, v20, v20
	v_fmac_f32_e32 v17, v22, v22
	v_add_f32_e32 v16, v16, v17
	v_mul_f32_e32 v17, v19, v19
	v_fmac_f32_e32 v17, v18, v18
	v_add_f32_e32 v16, v17, v16
	v_mul_f32_e32 v17, v25, v25
	v_fmac_f32_e32 v17, v24, v24
	v_add_f32_e32 v16, v17, v16
	v_add_f32_e32 v26, v38, v16
	v_cvt_pk_bf16_f32 v16, v20, v21
	v_cvt_pk_bf16_f32 v17, v22, v23
	v_cvt_pk_bf16_f32 v18, v18, v19
	v_cvt_pk_bf16_f32 v19, v24, v25
	global_store_dwordx4 v[34:35], v[16:19], off offset:256
	ds_bpermute_b32 v16, v158, v26
	s_waitcnt lgkmcnt(0)
	v_add_f32_e32 v16, v26, v16
	ds_bpermute_b32 v17, v157, v16
	s_and_saveexec_b64 s[6:7], s[4:5]
	s_cbranch_execz .LBB0_512
	s_waitcnt lgkmcnt(0)
	v_add_f32_e32 v18, v16, v17
	v_lshlrev_b64 v[16:17], 6, v[32:33]
	v_lshl_add_u64 v[16:17], s[62:63], 0, v[16:17]
	v_lshl_add_u64 v[16:17], s[68:69], 2, v[16:17]
	s_lshl_b32 s24, s57, 2
	v_lshl_add_u64 v[16:17], v[16:17], 0, s[24:25]
	global_store_dword v[16:17], v18, off
.LBB0_512:
	s_or_b64 exec, exec, s[6:7]
	v_add_u32_e32 v16, 0xb0, v146
	s_waitcnt lgkmcnt(0)
	v_ashrrev_i32_e32 v17, 31, v16
	v_lshlrev_b64 v[18:19], 11, v[16:17]
	v_lshl_add_u64 v[18:19], s[48:49], 0, v[18:19]
	v_lshl_add_u64 v[18:19], v[144:145], 1, v[18:19]
	s_nop 1
	v_mov_b64_e32 v[20:21], v[192:193]
	v_mov_b64_e32 v[22:23], v[194:195]
	s_nop 1
	v_lshlrev_b32_e32 v24, 16, v20
	v_and_b32_e32 v25, 0xffff0000, v20
	v_lshlrev_b32_e32 v20, 16, v21
	v_and_b32_e32 v21, 0xffff0000, v21
	v_lshlrev_b32_e32 v26, 16, v22
	v_and_b32_e32 v27, 0xffff0000, v22
	v_lshlrev_b32_e32 v22, 16, v23
	v_and_b32_e32 v23, 0xffff0000, v23
	v_pk_add_f32 v[14:15], v[14:15], v[20:21]
	v_pk_add_f32 v[12:13], v[12:13], v[24:25]
	v_pk_add_f32 v[20:21], v[10:11], v[22:23]
	v_pk_add_f32 v[10:11], v[8:9], v[26:27]
	v_mul_f32_e32 v8, v13, v13
	v_mul_f32_e32 v9, v15, v15
	v_fmac_f32_e32 v8, v12, v12
	v_fmac_f32_e32 v9, v14, v14
	v_add_f32_e32 v8, v8, v9
	v_mul_f32_e32 v9, v11, v11
	v_fmac_f32_e32 v9, v10, v10
	v_add_f32_e32 v8, v9, v8
	v_mul_f32_e32 v9, v21, v21
	v_fmac_f32_e32 v9, v20, v20
	v_add_f32_e32 v22, v9, v8
	v_cvt_pk_bf16_f32 v8, v12, v13
	v_cvt_pk_bf16_f32 v9, v14, v15
	v_cvt_pk_bf16_f32 v10, v10, v11
	v_cvt_pk_bf16_f32 v11, v20, v21
	global_store_dwordx4 v[18:19], v[8:11], off
	s_nop 1
	v_mov_b64_e32 v[8:9], v[196:197]
	v_mov_b64_e32 v[10:11], v[198:199]
	s_nop 1
	v_lshlrev_b32_e32 v12, 16, v8
	v_and_b32_e32 v13, 0xffff0000, v8
	v_lshlrev_b32_e32 v8, 16, v9
	v_and_b32_e32 v9, 0xffff0000, v9
	v_lshlrev_b32_e32 v14, 16, v10
	v_and_b32_e32 v15, 0xffff0000, v10
	v_lshlrev_b32_e32 v10, 16, v11
	v_and_b32_e32 v11, 0xffff0000, v11
	v_pk_add_f32 v[6:7], v[6:7], v[8:9]
	v_pk_add_f32 v[4:5], v[4:5], v[12:13]
	v_pk_add_f32 v[8:9], v[2:3], v[10:11]
	v_pk_add_f32 v[2:3], v[0:1], v[14:15]
	v_mul_f32_e32 v0, v5, v5
	v_mul_f32_e32 v1, v7, v7
	v_fmac_f32_e32 v0, v4, v4
	v_fmac_f32_e32 v1, v6, v6
	v_add_f32_e32 v0, v0, v1
	v_mul_f32_e32 v1, v3, v3
	v_fmac_f32_e32 v1, v2, v2
	v_add_f32_e32 v0, v1, v0
	v_mul_f32_e32 v1, v9, v9
	v_fmac_f32_e32 v1, v8, v8
	v_add_f32_e32 v0, v1, v0
	v_add_f32_e32 v10, v22, v0
	v_cvt_pk_bf16_f32 v0, v4, v5
	v_cvt_pk_bf16_f32 v1, v6, v7
	v_cvt_pk_bf16_f32 v2, v2, v3
	v_cvt_pk_bf16_f32 v3, v8, v9
	global_store_dwordx4 v[18:19], v[0:3], off offset:256
	ds_bpermute_b32 v0, v158, v10
	s_waitcnt lgkmcnt(0)
	v_add_f32_e32 v0, v10, v0
	ds_bpermute_b32 v1, v157, v0
	s_and_saveexec_b64 s[6:7], s[4:5]
	s_cbranch_execz .LBB0_514
	s_waitcnt lgkmcnt(0)
	v_add_f32_e32 v2, v0, v1
	v_lshlrev_b64 v[0:1], 6, v[16:17]
	v_lshl_add_u64 v[0:1], s[62:63], 0, v[0:1]
	v_lshl_add_u64 v[0:1], s[68:69], 2, v[0:1]
	s_lshl_b32 s24, s57, 2
	v_lshl_add_u64 v[0:1], v[0:1], 0, s[24:25]
	global_store_dword v[0:1], v2, off

.LBB0_720:
	v_and_b32_e32 v148, 64, v156
	v_xor_b32_e32 v147, 16, v156
	v_add_u32_e32 v148, 64, v148
	v_cmp_lt_i32_e32 vcc, v147, v148
	v_lshl_add_u32 v146, s68, 8, v150
	v_lshl_or_b32 v144, s24, 8, v152
	v_cndmask_b32_e32 v147, v156, v147, vcc
	v_lshlrev_b32_e32 v158, 2, v147
	v_xor_b32_e32 v147, 32, v156
	v_cmp_lt_i32_e32 vcc, v147, v148
	v_ashrrev_i32_e32 v145, 31, v144
	s_lshl_b32 s68, s24, 2
	v_cndmask_b32_e32 v147, v156, v147, vcc
	v_lshlrev_b32_e32 v157, 2, v147
	v_ashrrev_i32_e32 v147, 31, v146
	v_lshlrev_b64 v[148:149], 11, v[146:147]
	v_lshl_add_u64 v[148:149], s[48:49], 0, v[148:149]
	v_lshl_add_u64 v[148:149], v[144:145], 1, v[148:149]
	v_mov_b64_e32 v[206:207], v[148:149]
	global_load_dwordx4 v[168:171], v[148:149], off
	v_add_co_u32_e32 v204, vcc, 0x100, v148
	s_nop 1
	v_addc_co_u32_e32 v205, vcc, 0, v149, vcc
	global_load_dwordx4 v[172:175], v[204:205], off
	v_add_co_u32_e32 v204, vcc, 0x8000, v148
	s_nop 1
	v_addc_co_u32_e32 v205, vcc, 0, v149, vcc
	global_load_dwordx4 v[176:179], v[204:205], off
	v_add_co_u32_e32 v204, vcc, 0x8100, v148
	s_nop 1
	v_addc_co_u32_e32 v205, vcc, 0, v149, vcc
	global_load_dwordx4 v[180:183], v[204:205], off
	v_add_co_u32_e32 v204, vcc, 0x10000, v148
	s_nop 1
	v_addc_co_u32_e32 v205, vcc, 0, v149, vcc
	global_load_dwordx4 v[184:187], v[204:205], off
	v_add_co_u32_e32 v204, vcc, 0x10100, v148
	s_nop 1
	v_addc_co_u32_e32 v205, vcc, 0, v149, vcc
	global_load_dwordx4 v[188:191], v[204:205], off
	v_add_co_u32_e32 v204, vcc, 0x18000, v148
	s_nop 1
	v_addc_co_u32_e32 v205, vcc, 0, v149, vcc
	global_load_dwordx4 v[192:195], v[204:205], off
	v_add_co_u32_e32 v204, vcc, 0x18100, v148
	s_nop 1
	v_addc_co_u32_e32 v205, vcc, 0, v149, vcc
	global_load_dwordx4 v[196:199], v[204:205], off
	s_waitcnt vmcnt(0)
	s_nop 1
	v_mov_b64_e32 v[160:161], v[168:169]
	v_mov_b64_e32 v[162:163], v[170:171]
	s_ashr_i32 s69, s68, 31
	s_nop 1
	v_lshlrev_b32_e32 v164, 16, v160
	v_and_b32_e32 v165, 0xffff0000, v160
	v_lshlrev_b32_e32 v160, 16, v161
	v_and_b32_e32 v161, 0xffff0000, v161
	v_lshlrev_b32_e32 v166, 16, v162
	v_and_b32_e32 v167, 0xffff0000, v162
	v_lshlrev_b32_e32 v162, 16, v163
	v_and_b32_e32 v163, 0xffff0000, v163
	v_pk_add_f32 v[126:127], v[126:127], v[160:161]
	v_pk_add_f32 v[124:125], v[124:125], v[164:165]
	v_pk_add_f32 v[160:161], v[122:123], v[162:163]
	v_pk_add_f32 v[122:123], v[120:121], v[166:167]
	v_mul_f32_e32 v120, v125, v125
	v_mul_f32_e32 v121, v127, v127
	v_fmac_f32_e32 v120, v124, v124
	v_fmac_f32_e32 v121, v126, v126
	v_add_f32_e32 v120, v120, v121
	v_mul_f32_e32 v121, v123, v123
	v_fmac_f32_e32 v121, v122, v122
	v_add_f32_e32 v120, v121, v120
	v_mul_f32_e32 v121, v161, v161
	v_fmac_f32_e32 v121, v160, v160
	v_add_f32_e32 v159, v121, v120
	v_cvt_pk_bf16_f32 v120, v124, v125
	v_cvt_pk_bf16_f32 v121, v126, v127
	v_cvt_pk_bf16_f32 v122, v122, v123
	v_cvt_pk_bf16_f32 v123, v160, v161
	global_store_dwordx4 v[148:149], v[120:123], off
	s_nop 1
	v_mov_b64_e32 v[120:121], v[172:173]
	v_mov_b64_e32 v[122:123], v[174:175]
	s_nop 1
	v_lshlrev_b32_e32 v124, 16, v120
	v_and_b32_e32 v125, 0xffff0000, v120
	v_lshlrev_b32_e32 v120, 16, v121
	v_and_b32_e32 v121, 0xffff0000, v121
	v_lshlrev_b32_e32 v126, 16, v122
	v_and_b32_e32 v127, 0xffff0000, v122
	v_lshlrev_b32_e32 v122, 16, v123
	v_and_b32_e32 v123, 0xffff0000, v123
	v_pk_add_f32 v[118:119], v[118:119], v[120:121]
	v_pk_add_f32 v[116:117], v[116:117], v[124:125]
	v_pk_add_f32 v[120:121], v[114:115], v[122:123]
	v_pk_add_f32 v[114:115], v[112:113], v[126:127]
	v_mul_f32_e32 v112, v117, v117
	v_mul_f32_e32 v113, v119, v119
	v_fmac_f32_e32 v112, v116, v116
	v_fmac_f32_e32 v113, v118, v118
	v_add_f32_e32 v112, v112, v113
	v_mul_f32_e32 v113, v115, v115
	v_fmac_f32_e32 v113, v114, v114
	v_add_f32_e32 v112, v113, v112
	v_mul_f32_e32 v113, v121, v121
	v_fmac_f32_e32 v113, v120, v120
	v_add_f32_e32 v112, v113, v112
	v_add_f32_e32 v122, v159, v112
	v_cvt_pk_bf16_f32 v112, v116, v117
	v_cvt_pk_bf16_f32 v113, v118, v119
	v_cvt_pk_bf16_f32 v114, v114, v115
	v_cvt_pk_bf16_f32 v115, v120, v121
	global_store_dwordx4 v[148:149], v[112:115], off offset:256
	ds_bpermute_b32 v112, v158, v122
	s_waitcnt lgkmcnt(0)
	v_add_f32_e32 v112, v122, v112
	ds_bpermute_b32 v113, v157, v112
	s_and_saveexec_b64 s[4:5], s[10:11]
	s_cbranch_execz .LBB0_722
	s_waitcnt lgkmcnt(0)
	v_add_f32_e32 v114, v112, v113
	v_lshlrev_b64 v[112:113], 6, v[146:147]
	v_lshl_add_u64 v[112:113], s[62:63], 0, v[112:113]
	v_lshl_add_u64 v[112:113], s[68:69], 2, v[112:113]
	s_lshl_b32 s24, s55, 2
	v_lshl_add_u64 v[112:113], v[112:113], 0, s[24:25]
	global_store_dword v[112:113], v114, off
.LBB0_722:
	s_or_b64 exec, exec, s[4:5]
	v_or_b32_e32 v112, 16, v146
	s_waitcnt lgkmcnt(0)
	v_ashrrev_i32_e32 v113, 31, v112
	v_lshlrev_b64 v[114:115], 11, v[112:113]
	v_lshl_add_u64 v[114:115], s[48:49], 0, v[114:115]
	v_lshl_add_u64 v[114:115], v[144:145], 1, v[114:115]
	s_nop 1
	v_mov_b64_e32 v[116:117], v[176:177]
	v_mov_b64_e32 v[118:119], v[178:179]
	s_nop 1
	v_lshlrev_b32_e32 v120, 16, v116
	v_and_b32_e32 v121, 0xffff0000, v116
	v_lshlrev_b32_e32 v116, 16, v117
	v_and_b32_e32 v117, 0xffff0000, v117
	v_lshlrev_b32_e32 v122, 16, v118
	v_and_b32_e32 v123, 0xffff0000, v118
	v_lshlrev_b32_e32 v118, 16, v119
	v_and_b32_e32 v119, 0xffff0000, v119
	v_pk_add_f32 v[110:111], v[110:111], v[116:117]
	v_pk_add_f32 v[108:109], v[108:109], v[120:121]
	v_pk_add_f32 v[116:117], v[106:107], v[118:119]
	v_pk_add_f32 v[106:107], v[104:105], v[122:123]
	v_mul_f32_e32 v104, v109, v109
	v_mul_f32_e32 v105, v111, v111
	v_fmac_f32_e32 v104, v108, v108
	v_fmac_f32_e32 v105, v110, v110
	v_add_f32_e32 v104, v104, v105
	v_mul_f32_e32 v105, v107, v107
	v_fmac_f32_e32 v105, v106, v106
	v_add_f32_e32 v104, v105, v104
	v_mul_f32_e32 v105, v117, v117
	v_fmac_f32_e32 v105, v116, v116
	v_add_f32_e32 v118, v105, v104
	v_cvt_pk_bf16_f32 v104, v108, v109
	v_cvt_pk_bf16_f32 v105, v110, v111
	v_cvt_pk_bf16_f32 v106, v106, v107
	v_cvt_pk_bf16_f32 v107, v116, v117
	global_store_dwordx4 v[114:115], v[104:107], off
	s_nop 1
	v_mov_b64_e32 v[104:105], v[180:181]
	v_mov_b64_e32 v[106:107], v[182:183]
	s_nop 1
	v_lshlrev_b32_e32 v108, 16, v104
	v_and_b32_e32 v109, 0xffff0000, v104
	v_lshlrev_b32_e32 v104, 16, v105
	v_and_b32_e32 v105, 0xffff0000, v105
	v_lshlrev_b32_e32 v110, 16, v106
	v_and_b32_e32 v111, 0xffff0000, v106
	v_lshlrev_b32_e32 v106, 16, v107
	v_and_b32_e32 v107, 0xffff0000, v107
	v_pk_add_f32 v[102:103], v[102:103], v[104:105]
	v_pk_add_f32 v[100:101], v[100:101], v[108:109]
	v_pk_add_f32 v[104:105], v[98:99], v[106:107]
	v_pk_add_f32 v[98:99], v[96:97], v[110:111]
	v_mul_f32_e32 v96, v101, v101
	v_mul_f32_e32 v97, v103, v103
	v_fmac_f32_e32 v96, v100, v100
	v_fmac_f32_e32 v97, v102, v102
	v_add_f32_e32 v96, v96, v97
	v_mul_f32_e32 v97, v99, v99
	v_fmac_f32_e32 v97, v98, v98
	v_add_f32_e32 v96, v97, v96
	v_mul_f32_e32 v97, v105, v105
	v_fmac_f32_e32 v97, v104, v104
	v_add_f32_e32 v96, v97, v96
	v_add_f32_e32 v106, v118, v96
	v_cvt_pk_bf16_f32 v96, v100, v101
	v_cvt_pk_bf16_f32 v97, v102, v103
	v_cvt_pk_bf16_f32 v98, v98, v99
	v_cvt_pk_bf16_f32 v99, v104, v105
	global_store_dwordx4 v[114:115], v[96:99], off offset:256
	ds_bpermute_b32 v96, v158, v106
	s_waitcnt lgkmcnt(0)
	v_add_f32_e32 v96, v106, v96
	ds_bpermute_b32 v97, v157, v96
	s_and_saveexec_b64 s[4:5], s[10:11]
	s_cbranch_execz .LBB0_724
	s_waitcnt lgkmcnt(0)
	v_add_f32_e32 v98, v96, v97
	v_lshlrev_b64 v[96:97], 6, v[112:113]
	v_lshl_add_u64 v[96:97], s[62:63], 0, v[96:97]
	v_lshl_add_u64 v[96:97], s[68:69], 2, v[96:97]
	s_lshl_b32 s24, s55, 2
	v_lshl_add_u64 v[96:97], v[96:97], 0, s[24:25]
	global_store_dword v[96:97], v98, off
.LBB0_724:
	s_or_b64 exec, exec, s[4:5]
	v_or_b32_e32 v96, 32, v146
	s_waitcnt lgkmcnt(0)
	v_ashrrev_i32_e32 v97, 31, v96
	v_lshlrev_b64 v[98:99], 11, v[96:97]
	v_lshl_add_u64 v[98:99], s[48:49], 0, v[98:99]
	v_lshl_add_u64 v[98:99], v[144:145], 1, v[98:99]
	s_nop 1
	v_mov_b64_e32 v[100:101], v[184:185]
	v_mov_b64_e32 v[102:103], v[186:187]
	s_nop 1
	v_lshlrev_b32_e32 v104, 16, v100
	v_and_b32_e32 v105, 0xffff0000, v100
	v_lshlrev_b32_e32 v100, 16, v101
	v_and_b32_e32 v101, 0xffff0000, v101
	v_lshlrev_b32_e32 v106, 16, v102
	v_and_b32_e32 v107, 0xffff0000, v102
	v_lshlrev_b32_e32 v102, 16, v103
	v_and_b32_e32 v103, 0xffff0000, v103
	v_pk_add_f32 v[94:95], v[94:95], v[100:101]
	v_pk_add_f32 v[92:93], v[92:93], v[104:105]
	v_pk_add_f32 v[100:101], v[90:91], v[102:103]
	v_pk_add_f32 v[90:91], v[88:89], v[106:107]
	v_mul_f32_e32 v88, v93, v93
	v_mul_f32_e32 v89, v95, v95
	v_fmac_f32_e32 v88, v92, v92
	v_fmac_f32_e32 v89, v94, v94
	v_add_f32_e32 v88, v88, v89
	v_mul_f32_e32 v89, v91, v91
	v_fmac_f32_e32 v89, v90, v90
	v_add_f32_e32 v88, v89, v88
	v_mul_f32_e32 v89, v101, v101
	v_fmac_f32_e32 v89, v100, v100
	v_add_f32_e32 v102, v89, v88
	v_cvt_pk_bf16_f32 v88, v92, v93
	v_cvt_pk_bf16_f32 v89, v94, v95
	v_cvt_pk_bf16_f32 v90, v90, v91
	v_cvt_pk_bf16_f32 v91, v100, v101
	global_store_dwordx4 v[98:99], v[88:91], off
	s_nop 1
	v_mov_b64_e32 v[88:89], v[188:189]
	v_mov_b64_e32 v[90:91], v[190:191]
	s_nop 1
	v_lshlrev_b32_e32 v92, 16, v88
	v_and_b32_e32 v93, 0xffff0000, v88
	v_lshlrev_b32_e32 v88, 16, v89
	v_and_b32_e32 v89, 0xffff0000, v89
	v_lshlrev_b32_e32 v94, 16, v90
	v_and_b32_e32 v95, 0xffff0000, v90
	v_lshlrev_b32_e32 v90, 16, v91
	v_and_b32_e32 v91, 0xffff0000, v91
	v_pk_add_f32 v[86:87], v[86:87], v[88:89]
	v_pk_add_f32 v[84:85], v[84:85], v[92:93]
	v_pk_add_f32 v[88:89], v[82:83], v[90:91]
	v_pk_add_f32 v[82:83], v[80:81], v[94:95]
	v_mul_f32_e32 v80, v85, v85
	v_mul_f32_e32 v81, v87, v87
	v_fmac_f32_e32 v80, v84, v84
	v_fmac_f32_e32 v81, v86, v86
	v_add_f32_e32 v80, v80, v81
	v_mul_f32_e32 v81, v83, v83
	v_fmac_f32_e32 v81, v82, v82
	v_add_f32_e32 v80, v81, v80
	v_mul_f32_e32 v81, v89, v89
	v_fmac_f32_e32 v81, v88, v88
	v_add_f32_e32 v80, v81, v80
	v_add_f32_e32 v90, v102, v80
	v_cvt_pk_bf16_f32 v80, v84, v85
	v_cvt_pk_bf16_f32 v81, v86, v87
	v_cvt_pk_bf16_f32 v82, v82, v83
	v_cvt_pk_bf16_f32 v83, v88, v89
	global_store_dwordx4 v[98:99], v[80:83], off offset:256
	ds_bpermute_b32 v80, v158, v90
	s_waitcnt lgkmcnt(0)
	v_add_f32_e32 v80, v90, v80
	ds_bpermute_b32 v81, v157, v80
	s_and_saveexec_b64 s[4:5], s[10:11]
	s_cbranch_execz .LBB0_726
	s_waitcnt lgkmcnt(0)
	v_add_f32_e32 v82, v80, v81
	v_lshlrev_b64 v[80:81], 6, v[96:97]
	v_lshl_add_u64 v[80:81], s[62:63], 0, v[80:81]
	v_lshl_add_u64 v[80:81], s[68:69], 2, v[80:81]
	s_lshl_b32 s24, s55, 2
	v_lshl_add_u64 v[80:81], v[80:81], 0, s[24:25]
	global_store_dword v[80:81], v82, off
.LBB0_726:
	s_or_b64 exec, exec, s[4:5]
	v_or_b32_e32 v80, 48, v146
	s_waitcnt lgkmcnt(0)
	v_ashrrev_i32_e32 v81, 31, v80
	v_lshlrev_b64 v[82:83], 11, v[80:81]
	v_lshl_add_u64 v[82:83], s[48:49], 0, v[82:83]
	v_lshl_add_u64 v[82:83], v[144:145], 1, v[82:83]
	s_nop 1
	v_mov_b64_e32 v[84:85], v[192:193]
	v_mov_b64_e32 v[86:87], v[194:195]
	s_nop 1
	v_lshlrev_b32_e32 v88, 16, v84
	v_and_b32_e32 v89, 0xffff0000, v84
	v_lshlrev_b32_e32 v84, 16, v85
	v_and_b32_e32 v85, 0xffff0000, v85
	v_lshlrev_b32_e32 v90, 16, v86
	v_and_b32_e32 v91, 0xffff0000, v86
	v_lshlrev_b32_e32 v86, 16, v87
	v_and_b32_e32 v87, 0xffff0000, v87
	v_pk_add_f32 v[78:79], v[78:79], v[84:85]
	v_pk_add_f32 v[76:77], v[76:77], v[88:89]
	v_pk_add_f32 v[84:85], v[74:75], v[86:87]
	v_pk_add_f32 v[74:75], v[72:73], v[90:91]
	v_mul_f32_e32 v72, v77, v77
	v_mul_f32_e32 v73, v79, v79
	v_fmac_f32_e32 v72, v76, v76
	v_fmac_f32_e32 v73, v78, v78
	v_add_f32_e32 v72, v72, v73
	v_mul_f32_e32 v73, v75, v75
	v_fmac_f32_e32 v73, v74, v74
	v_add_f32_e32 v72, v73, v72
	v_mul_f32_e32 v73, v85, v85
	v_fmac_f32_e32 v73, v84, v84
	v_add_f32_e32 v86, v73, v72
	v_cvt_pk_bf16_f32 v72, v76, v77
	v_cvt_pk_bf16_f32 v73, v78, v79
	v_cvt_pk_bf16_f32 v74, v74, v75
	v_cvt_pk_bf16_f32 v75, v84, v85
	global_store_dwordx4 v[82:83], v[72:75], off
	s_nop 1
	v_mov_b64_e32 v[72:73], v[196:197]
	v_mov_b64_e32 v[74:75], v[198:199]
	s_nop 1
	v_lshlrev_b32_e32 v76, 16, v72
	v_and_b32_e32 v77, 0xffff0000, v72
	v_lshlrev_b32_e32 v72, 16, v73
	v_and_b32_e32 v73, 0xffff0000, v73
	v_lshlrev_b32_e32 v78, 16, v74
	v_and_b32_e32 v79, 0xffff0000, v74
	v_lshlrev_b32_e32 v74, 16, v75
	v_and_b32_e32 v75, 0xffff0000, v75
	v_pk_add_f32 v[70:71], v[70:71], v[72:73]
	v_pk_add_f32 v[68:69], v[68:69], v[76:77]
	v_pk_add_f32 v[72:73], v[66:67], v[74:75]
	v_pk_add_f32 v[66:67], v[64:65], v[78:79]
	v_mul_f32_e32 v64, v69, v69
	v_mul_f32_e32 v65, v71, v71
	v_fmac_f32_e32 v64, v68, v68
	v_fmac_f32_e32 v65, v70, v70
	v_add_f32_e32 v64, v64, v65
	v_mul_f32_e32 v65, v67, v67
	v_fmac_f32_e32 v65, v66, v66
	v_add_f32_e32 v64, v65, v64
	v_mul_f32_e32 v65, v73, v73
	v_fmac_f32_e32 v65, v72, v72
	v_add_f32_e32 v64, v65, v64
	v_add_f32_e32 v74, v86, v64
	v_cvt_pk_bf16_f32 v64, v68, v69
	v_cvt_pk_bf16_f32 v65, v70, v71
	v_cvt_pk_bf16_f32 v66, v66, v67
	v_cvt_pk_bf16_f32 v67, v72, v73
	global_store_dwordx4 v[82:83], v[64:67], off offset:256
	ds_bpermute_b32 v64, v158, v74
	s_waitcnt lgkmcnt(0)
	v_add_f32_e32 v64, v74, v64
	ds_bpermute_b32 v65, v157, v64
	s_and_saveexec_b64 s[4:5], s[10:11]
	s_cbranch_execz .LBB0_728
	s_waitcnt lgkmcnt(0)
	v_add_f32_e32 v66, v64, v65
	v_lshlrev_b64 v[64:65], 6, v[80:81]
	v_lshl_add_u64 v[64:65], s[62:63], 0, v[64:65]
	v_lshl_add_u64 v[64:65], s[68:69], 2, v[64:65]
	s_lshl_b32 s24, s55, 2
	v_lshl_add_u64 v[64:65], v[64:65], 0, s[24:25]
	global_store_dword v[64:65], v66, off
.LBB0_728:
	s_or_b64 exec, exec, s[4:5]
	v_add_u32_e32 v64, 0x80, v146
	s_waitcnt lgkmcnt(0)
	v_ashrrev_i32_e32 v65, 31, v64
	v_lshlrev_b64 v[66:67], 11, v[64:65]
	v_lshl_add_u64 v[66:67], s[48:49], 0, v[66:67]
	v_lshl_add_u64 v[66:67], v[144:145], 1, v[66:67]
	v_add_co_u32_e32 v204, vcc, 0x40000, v206
	s_nop 1
	v_addc_co_u32_e32 v205, vcc, 0, v207, vcc
	global_load_dwordx4 v[168:171], v[204:205], off
	v_add_co_u32_e32 v204, vcc, 0x40100, v206
	s_nop 1
	v_addc_co_u32_e32 v205, vcc, 0, v207, vcc
	global_load_dwordx4 v[172:175], v[204:205], off
	v_add_co_u32_e32 v204, vcc, 0x48000, v206
	s_nop 1
	v_addc_co_u32_e32 v205, vcc, 0, v207, vcc
	global_load_dwordx4 v[176:179], v[204:205], off
	v_add_co_u32_e32 v204, vcc, 0x48100, v206
	s_nop 1
	v_addc_co_u32_e32 v205, vcc, 0, v207, vcc
	global_load_dwordx4 v[180:183], v[204:205], off
	v_add_co_u32_e32 v204, vcc, 0x50000, v206
	s_nop 1
	v_addc_co_u32_e32 v205, vcc, 0, v207, vcc
	global_load_dwordx4 v[184:187], v[204:205], off
	v_add_co_u32_e32 v204, vcc, 0x50100, v206
	s_nop 1
	v_addc_co_u32_e32 v205, vcc, 0, v207, vcc
	global_load_dwordx4 v[188:191], v[204:205], off
	v_add_co_u32_e32 v204, vcc, 0x58000, v206
	s_nop 1
	v_addc_co_u32_e32 v205, vcc, 0, v207, vcc
	global_load_dwordx4 v[192:195], v[204:205], off
	v_add_co_u32_e32 v204, vcc, 0x58100, v206
	s_nop 1
	v_addc_co_u32_e32 v205, vcc, 0, v207, vcc
	global_load_dwordx4 v[196:199], v[204:205], off
	s_waitcnt vmcnt(0)
	s_nop 1
	v_mov_b64_e32 v[68:69], v[168:169]
	v_mov_b64_e32 v[70:71], v[170:171]
	s_nop 1
	v_lshlrev_b32_e32 v72, 16, v68
	v_and_b32_e32 v73, 0xffff0000, v68
	v_lshlrev_b32_e32 v68, 16, v69
	v_and_b32_e32 v69, 0xffff0000, v69
	v_lshlrev_b32_e32 v74, 16, v70
	v_and_b32_e32 v75, 0xffff0000, v70
	v_lshlrev_b32_e32 v70, 16, v71
	v_and_b32_e32 v71, 0xffff0000, v71
	v_pk_add_f32 v[62:63], v[62:63], v[68:69]
	v_pk_add_f32 v[60:61], v[60:61], v[72:73]
	v_pk_add_f32 v[68:69], v[58:59], v[70:71]
	v_pk_add_f32 v[58:59], v[56:57], v[74:75]
	v_mul_f32_e32 v56, v61, v61
	v_mul_f32_e32 v57, v63, v63
	v_fmac_f32_e32 v56, v60, v60
	v_fmac_f32_e32 v57, v62, v62
	v_add_f32_e32 v56, v56, v57
	v_mul_f32_e32 v57, v59, v59
	v_fmac_f32_e32 v57, v58, v58
	v_add_f32_e32 v56, v57, v56
	v_mul_f32_e32 v57, v69, v69
	v_fmac_f32_e32 v57, v68, v68
	v_add_f32_e32 v70, v57, v56
	v_cvt_pk_bf16_f32 v56, v60, v61
	v_cvt_pk_bf16_f32 v57, v62, v63
	v_cvt_pk_bf16_f32 v58, v58, v59
	v_cvt_pk_bf16_f32 v59, v68, v69
	global_store_dwordx4 v[66:67], v[56:59], off
	s_nop 1
	v_mov_b64_e32 v[56:57], v[172:173]
	v_mov_b64_e32 v[58:59], v[174:175]
	s_nop 1
	v_lshlrev_b32_e32 v60, 16, v56
	v_and_b32_e32 v61, 0xffff0000, v56
	v_lshlrev_b32_e32 v56, 16, v57
	v_and_b32_e32 v57, 0xffff0000, v57
	v_lshlrev_b32_e32 v62, 16, v58
	v_and_b32_e32 v63, 0xffff0000, v58
	v_lshlrev_b32_e32 v58, 16, v59
	v_and_b32_e32 v59, 0xffff0000, v59
	v_pk_add_f32 v[54:55], v[54:55], v[56:57]
	v_pk_add_f32 v[52:53], v[52:53], v[60:61]
	v_pk_add_f32 v[56:57], v[50:51], v[58:59]
	v_pk_add_f32 v[50:51], v[48:49], v[62:63]
	v_mul_f32_e32 v48, v53, v53
	v_mul_f32_e32 v49, v55, v55
	v_fmac_f32_e32 v48, v52, v52
	v_fmac_f32_e32 v49, v54, v54
	v_add_f32_e32 v48, v48, v49
	v_mul_f32_e32 v49, v51, v51
	v_fmac_f32_e32 v49, v50, v50
	v_add_f32_e32 v48, v49, v48
	v_mul_f32_e32 v49, v57, v57
	v_fmac_f32_e32 v49, v56, v56
	v_add_f32_e32 v48, v49, v48
	v_add_f32_e32 v58, v70, v48
	v_cvt_pk_bf16_f32 v48, v52, v53
	v_cvt_pk_bf16_f32 v49, v54, v55
	v_cvt_pk_bf16_f32 v50, v50, v51
	v_cvt_pk_bf16_f32 v51, v56, v57
	global_store_dwordx4 v[66:67], v[48:51], off offset:256
	ds_bpermute_b32 v48, v158, v58
	s_waitcnt lgkmcnt(0)
	v_add_f32_e32 v48, v58, v48
	ds_bpermute_b32 v49, v157, v48
	s_and_saveexec_b64 s[4:5], s[10:11]
	s_cbranch_execz .LBB0_730
	s_waitcnt lgkmcnt(0)
	v_add_f32_e32 v50, v48, v49
	v_lshlrev_b64 v[48:49], 6, v[64:65]
	v_lshl_add_u64 v[48:49], s[62:63], 0, v[48:49]
	v_lshl_add_u64 v[48:49], s[68:69], 2, v[48:49]
	s_lshl_b32 s24, s55, 2
	v_lshl_add_u64 v[48:49], v[48:49], 0, s[24:25]
	global_store_dword v[48:49], v50, off
.LBB0_730:
	s_or_b64 exec, exec, s[4:5]
	v_add_u32_e32 v48, 0x90, v146
	s_waitcnt lgkmcnt(0)
	v_ashrrev_i32_e32 v49, 31, v48
	v_lshlrev_b64 v[50:51], 11, v[48:49]
	v_lshl_add_u64 v[50:51], s[48:49], 0, v[50:51]
	v_lshl_add_u64 v[50:51], v[144:145], 1, v[50:51]
	s_nop 1
	v_mov_b64_e32 v[52:53], v[176:177]
	v_mov_b64_e32 v[54:55], v[178:179]
	s_nop 1
	v_lshlrev_b32_e32 v56, 16, v52
	v_and_b32_e32 v57, 0xffff0000, v52
	v_lshlrev_b32_e32 v52, 16, v53
	v_and_b32_e32 v53, 0xffff0000, v53
	v_lshlrev_b32_e32 v58, 16, v54
	v_and_b32_e32 v59, 0xffff0000, v54
	v_lshlrev_b32_e32 v54, 16, v55
	v_and_b32_e32 v55, 0xffff0000, v55
	v_pk_add_f32 v[46:47], v[46:47], v[52:53]
	v_pk_add_f32 v[44:45], v[44:45], v[56:57]
	v_pk_add_f32 v[52:53], v[42:43], v[54:55]
	v_pk_add_f32 v[42:43], v[40:41], v[58:59]
	v_mul_f32_e32 v40, v45, v45
	v_mul_f32_e32 v41, v47, v47
	v_fmac_f32_e32 v40, v44, v44
	v_fmac_f32_e32 v41, v46, v46
	v_add_f32_e32 v40, v40, v41
	v_mul_f32_e32 v41, v43, v43
	v_fmac_f32_e32 v41, v42, v42
	v_add_f32_e32 v40, v41, v40
	v_mul_f32_e32 v41, v53, v53
	v_fmac_f32_e32 v41, v52, v52
	v_add_f32_e32 v54, v41, v40
	v_cvt_pk_bf16_f32 v40, v44, v45
	v_cvt_pk_bf16_f32 v41, v46, v47
	v_cvt_pk_bf16_f32 v42, v42, v43
	v_cvt_pk_bf16_f32 v43, v52, v53
	global_store_dwordx4 v[50:51], v[40:43], off
	s_nop 1
	v_mov_b64_e32 v[40:41], v[180:181]
	v_mov_b64_e32 v[42:43], v[182:183]
	s_nop 1
	v_lshlrev_b32_e32 v44, 16, v40
	v_and_b32_e32 v45, 0xffff0000, v40
	v_lshlrev_b32_e32 v40, 16, v41
	v_and_b32_e32 v41, 0xffff0000, v41
	v_lshlrev_b32_e32 v46, 16, v42
	v_and_b32_e32 v47, 0xffff0000, v42
	v_lshlrev_b32_e32 v42, 16, v43
	v_and_b32_e32 v43, 0xffff0000, v43
	v_pk_add_f32 v[38:39], v[38:39], v[40:41]
	v_pk_add_f32 v[36:37], v[36:37], v[44:45]
	v_pk_add_f32 v[40:41], v[34:35], v[42:43]
	v_pk_add_f32 v[34:35], v[32:33], v[46:47]
	v_mul_f32_e32 v32, v37, v37
	v_mul_f32_e32 v33, v39, v39
	v_fmac_f32_e32 v32, v36, v36
	v_fmac_f32_e32 v33, v38, v38
	v_add_f32_e32 v32, v32, v33
	v_mul_f32_e32 v33, v35, v35
	v_fmac_f32_e32 v33, v34, v34
	v_add_f32_e32 v32, v33, v32
	v_mul_f32_e32 v33, v41, v41
	v_fmac_f32_e32 v33, v40, v40
	v_add_f32_e32 v32, v33, v32
	v_add_f32_e32 v42, v54, v32
	v_cvt_pk_bf16_f32 v32, v36, v37
	v_cvt_pk_bf16_f32 v33, v38, v39
	v_cvt_pk_bf16_f32 v34, v34, v35
	v_cvt_pk_bf16_f32 v35, v40, v41
	global_store_dwordx4 v[50:51], v[32:35], off offset:256
	ds_bpermute_b32 v32, v158, v42
	s_waitcnt lgkmcnt(0)
	v_add_f32_e32 v32, v42, v32
	ds_bpermute_b32 v33, v157, v32
	s_and_saveexec_b64 s[4:5], s[10:11]
	s_cbranch_execz .LBB0_732
	s_waitcnt lgkmcnt(0)
	v_add_f32_e32 v34, v32, v33
	v_lshlrev_b64 v[32:33], 6, v[48:49]
	v_lshl_add_u64 v[32:33], s[62:63], 0, v[32:33]
	v_lshl_add_u64 v[32:33], s[68:69], 2, v[32:33]
	s_lshl_b32 s24, s55, 2
	v_lshl_add_u64 v[32:33], v[32:33], 0, s[24:25]
	global_store_dword v[32:33], v34, off
.LBB0_732:
	s_or_b64 exec, exec, s[4:5]
	v_add_u32_e32 v32, 0xa0, v146
	s_waitcnt lgkmcnt(0)
	v_ashrrev_i32_e32 v33, 31, v32
	v_lshlrev_b64 v[34:35], 11, v[32:33]
	v_lshl_add_u64 v[34:35], s[48:49], 0, v[34:35]
	v_lshl_add_u64 v[34:35], v[144:145], 1, v[34:35]
	s_nop 1
	v_mov_b64_e32 v[36:37], v[184:185]
	v_mov_b64_e32 v[38:39], v[186:187]
	s_nop 1
	v_lshlrev_b32_e32 v40, 16, v36
	v_and_b32_e32 v41, 0xffff0000, v36
	v_lshlrev_b32_e32 v36, 16, v37
	v_and_b32_e32 v37, 0xffff0000, v37
	v_lshlrev_b32_e32 v42, 16, v38
	v_and_b32_e32 v43, 0xffff0000, v38
	v_lshlrev_b32_e32 v38, 16, v39
	v_and_b32_e32 v39, 0xffff0000, v39
	v_pk_add_f32 v[30:31], v[30:31], v[36:37]
	v_pk_add_f32 v[28:29], v[28:29], v[40:41]
	v_pk_add_f32 v[36:37], v[26:27], v[38:39]
	v_pk_add_f32 v[26:27], v[24:25], v[42:43]
	v_mul_f32_e32 v24, v29, v29
	v_mul_f32_e32 v25, v31, v31
	v_fmac_f32_e32 v24, v28, v28
	v_fmac_f32_e32 v25, v30, v30
	v_add_f32_e32 v24, v24, v25
	v_mul_f32_e32 v25, v27, v27
	v_fmac_f32_e32 v25, v26, v26
	v_add_f32_e32 v24, v25, v24
	v_mul_f32_e32 v25, v37, v37
	v_fmac_f32_e32 v25, v36, v36
	v_add_f32_e32 v38, v25, v24
	v_cvt_pk_bf16_f32 v24, v28, v29
	v_cvt_pk_bf16_f32 v25, v30, v31
	v_cvt_pk_bf16_f32 v26, v26, v27
	v_cvt_pk_bf16_f32 v27, v36, v37
	global_store_dwordx4 v[34:35], v[24:27], off
	s_nop 1
	v_mov_b64_e32 v[24:25], v[188:189]
	v_mov_b64_e32 v[26:27], v[190:191]
	s_nop 1
	v_lshlrev_b32_e32 v28, 16, v24
	v_and_b32_e32 v29, 0xffff0000, v24
	v_lshlrev_b32_e32 v24, 16, v25
	v_and_b32_e32 v25, 0xffff0000, v25
	v_lshlrev_b32_e32 v30, 16, v26
	v_and_b32_e32 v31, 0xffff0000, v26
	v_lshlrev_b32_e32 v26, 16, v27
	v_and_b32_e32 v27, 0xffff0000, v27
	v_pk_add_f32 v[22:23], v[22:23], v[24:25]
	v_pk_add_f32 v[20:21], v[20:21], v[28:29]
	v_pk_add_f32 v[24:25], v[18:19], v[26:27]
	v_pk_add_f32 v[18:19], v[16:17], v[30:31]
	v_mul_f32_e32 v16, v21, v21
	v_mul_f32_e32 v17, v23, v23
	v_fmac_f32_e32 v16, v20, v20
	v_fmac_f32_e32 v17, v22, v22
	v_add_f32_e32 v16, v16, v17
	v_mul_f32_e32 v17, v19, v19
	v_fmac_f32_e32 v17, v18, v18
	v_add_f32_e32 v16, v17, v16
	v_mul_f32_e32 v17, v25, v25
	v_fmac_f32_e32 v17, v24, v24
	v_add_f32_e32 v16, v17, v16
	v_add_f32_e32 v26, v38, v16
	v_cvt_pk_bf16_f32 v16, v20, v21
	v_cvt_pk_bf16_f32 v17, v22, v23
	v_cvt_pk_bf16_f32 v18, v18, v19
	v_cvt_pk_bf16_f32 v19, v24, v25
	global_store_dwordx4 v[34:35], v[16:19], off offset:256
	ds_bpermute_b32 v16, v158, v26
	s_waitcnt lgkmcnt(0)
	v_add_f32_e32 v16, v26, v16
	ds_bpermute_b32 v17, v157, v16
	s_and_saveexec_b64 s[4:5], s[10:11]
	s_cbranch_execz .LBB0_734
	s_waitcnt lgkmcnt(0)
	v_add_f32_e32 v18, v16, v17
	v_lshlrev_b64 v[16:17], 6, v[32:33]
	v_lshl_add_u64 v[16:17], s[62:63], 0, v[16:17]
	v_lshl_add_u64 v[16:17], s[68:69], 2, v[16:17]
	s_lshl_b32 s24, s55, 2
	v_lshl_add_u64 v[16:17], v[16:17], 0, s[24:25]
	global_store_dword v[16:17], v18, off
.LBB0_734:
	s_or_b64 exec, exec, s[4:5]
	v_add_u32_e32 v16, 0xb0, v146
	s_waitcnt lgkmcnt(0)
	v_ashrrev_i32_e32 v17, 31, v16
	v_lshlrev_b64 v[18:19], 11, v[16:17]
	v_lshl_add_u64 v[18:19], s[48:49], 0, v[18:19]
	v_lshl_add_u64 v[18:19], v[144:145], 1, v[18:19]
	s_nop 1
	v_mov_b64_e32 v[20:21], v[192:193]
	v_mov_b64_e32 v[22:23], v[194:195]
	s_nop 1
	v_lshlrev_b32_e32 v24, 16, v20
	v_and_b32_e32 v25, 0xffff0000, v20
	v_lshlrev_b32_e32 v20, 16, v21
	v_and_b32_e32 v21, 0xffff0000, v21
	v_lshlrev_b32_e32 v26, 16, v22
	v_and_b32_e32 v27, 0xffff0000, v22
	v_lshlrev_b32_e32 v22, 16, v23
	v_and_b32_e32 v23, 0xffff0000, v23
	v_pk_add_f32 v[14:15], v[14:15], v[20:21]
	v_pk_add_f32 v[12:13], v[12:13], v[24:25]
	v_pk_add_f32 v[20:21], v[10:11], v[22:23]
	v_pk_add_f32 v[10:11], v[8:9], v[26:27]
	v_mul_f32_e32 v8, v13, v13
	v_mul_f32_e32 v9, v15, v15
	v_fmac_f32_e32 v8, v12, v12
	v_fmac_f32_e32 v9, v14, v14
	v_add_f32_e32 v8, v8, v9
	v_mul_f32_e32 v9, v11, v11
	v_fmac_f32_e32 v9, v10, v10
	v_add_f32_e32 v8, v9, v8
	v_mul_f32_e32 v9, v21, v21
	v_fmac_f32_e32 v9, v20, v20
	v_add_f32_e32 v22, v9, v8
	v_cvt_pk_bf16_f32 v8, v12, v13
	v_cvt_pk_bf16_f32 v9, v14, v15
	v_cvt_pk_bf16_f32 v10, v10, v11
	v_cvt_pk_bf16_f32 v11, v20, v21
	global_store_dwordx4 v[18:19], v[8:11], off
	s_nop 1
	v_mov_b64_e32 v[8:9], v[196:197]
	v_mov_b64_e32 v[10:11], v[198:199]
	s_nop 1
	v_lshlrev_b32_e32 v12, 16, v8
	v_and_b32_e32 v13, 0xffff0000, v8
	v_lshlrev_b32_e32 v8, 16, v9
	v_and_b32_e32 v9, 0xffff0000, v9
	v_lshlrev_b32_e32 v14, 16, v10
	v_and_b32_e32 v15, 0xffff0000, v10
	v_lshlrev_b32_e32 v10, 16, v11
	v_and_b32_e32 v11, 0xffff0000, v11
	v_pk_add_f32 v[6:7], v[6:7], v[8:9]
	v_pk_add_f32 v[4:5], v[4:5], v[12:13]
	v_pk_add_f32 v[8:9], v[2:3], v[10:11]
	v_pk_add_f32 v[2:3], v[0:1], v[14:15]
	v_mul_f32_e32 v0, v5, v5
	v_mul_f32_e32 v1, v7, v7
	v_fmac_f32_e32 v0, v4, v4
	v_fmac_f32_e32 v1, v6, v6
	v_add_f32_e32 v0, v0, v1
	v_mul_f32_e32 v1, v3, v3
	v_fmac_f32_e32 v1, v2, v2
	v_add_f32_e32 v0, v1, v0
	v_mul_f32_e32 v1, v9, v9
	v_fmac_f32_e32 v1, v8, v8
	v_add_f32_e32 v0, v1, v0
	v_add_f32_e32 v10, v22, v0
	v_cvt_pk_bf16_f32 v0, v4, v5
	v_cvt_pk_bf16_f32 v1, v6, v7
	v_cvt_pk_bf16_f32 v2, v2, v3
	v_cvt_pk_bf16_f32 v3, v8, v9
	global_store_dwordx4 v[18:19], v[0:3], off offset:256
	ds_bpermute_b32 v0, v158, v10
	s_waitcnt lgkmcnt(0)
	v_add_f32_e32 v0, v10, v0
	ds_bpermute_b32 v1, v157, v0
	s_and_saveexec_b64 s[4:5], s[10:11]
	s_cbranch_execz .LBB0_736
	s_waitcnt lgkmcnt(0)
	v_add_f32_e32 v2, v0, v1
	v_lshlrev_b64 v[0:1], 6, v[16:17]
	v_lshl_add_u64 v[0:1], s[62:63], 0, v[0:1]
	v_lshl_add_u64 v[0:1], s[68:69], 2, v[0:1]
	s_lshl_b32 s24, s55, 2
	v_lshl_add_u64 v[0:1], v[0:1], 0, s[24:25]
	global_store_dword v[0:1], v2, off

.LBB0_1072:
	v_and_b32_e32 v148, 64, v156
	v_xor_b32_e32 v147, 16, v156
	v_add_u32_e32 v148, 64, v148
	v_cmp_lt_i32_e32 vcc, v147, v148
	v_lshl_add_u32 v146, s68, 8, v150
	v_lshl_or_b32 v144, s24, 8, v152
	v_cndmask_b32_e32 v147, v156, v147, vcc
	v_lshlrev_b32_e32 v158, 2, v147
	v_xor_b32_e32 v147, 32, v156
	v_cmp_lt_i32_e32 vcc, v147, v148
	v_ashrrev_i32_e32 v145, 31, v144
	s_lshl_b32 s68, s24, 2
	v_cndmask_b32_e32 v147, v156, v147, vcc
	v_lshlrev_b32_e32 v157, 2, v147
	v_ashrrev_i32_e32 v147, 31, v146
	v_lshlrev_b64 v[148:149], 11, v[146:147]
	v_lshl_add_u64 v[148:149], s[48:49], 0, v[148:149]
	v_lshl_add_u64 v[148:149], v[144:145], 1, v[148:149]
	v_mov_b64_e32 v[206:207], v[148:149]
	global_load_dwordx4 v[168:171], v[148:149], off
	v_add_co_u32_e32 v204, vcc, 0x100, v148
	s_nop 1
	v_addc_co_u32_e32 v205, vcc, 0, v149, vcc
	global_load_dwordx4 v[172:175], v[204:205], off
	v_add_co_u32_e32 v204, vcc, 0x8000, v148
	s_nop 1
	v_addc_co_u32_e32 v205, vcc, 0, v149, vcc
	global_load_dwordx4 v[176:179], v[204:205], off
	v_add_co_u32_e32 v204, vcc, 0x8100, v148
	s_nop 1
	v_addc_co_u32_e32 v205, vcc, 0, v149, vcc
	global_load_dwordx4 v[180:183], v[204:205], off
	v_add_co_u32_e32 v204, vcc, 0x10000, v148
	s_nop 1
	v_addc_co_u32_e32 v205, vcc, 0, v149, vcc
	global_load_dwordx4 v[184:187], v[204:205], off
	v_add_co_u32_e32 v204, vcc, 0x10100, v148
	s_nop 1
	v_addc_co_u32_e32 v205, vcc, 0, v149, vcc
	global_load_dwordx4 v[188:191], v[204:205], off
	v_add_co_u32_e32 v204, vcc, 0x18000, v148
	s_nop 1
	v_addc_co_u32_e32 v205, vcc, 0, v149, vcc
	global_load_dwordx4 v[192:195], v[204:205], off
	v_add_co_u32_e32 v204, vcc, 0x18100, v148
	s_nop 1
	v_addc_co_u32_e32 v205, vcc, 0, v149, vcc
	global_load_dwordx4 v[196:199], v[204:205], off
	s_waitcnt vmcnt(0)
	s_nop 1
	v_mov_b64_e32 v[160:161], v[168:169]
	v_mov_b64_e32 v[162:163], v[170:171]
	s_ashr_i32 s69, s68, 31
	s_nop 1
	v_lshlrev_b32_e32 v164, 16, v160
	v_and_b32_e32 v165, 0xffff0000, v160
	v_lshlrev_b32_e32 v160, 16, v161
	v_and_b32_e32 v161, 0xffff0000, v161
	v_lshlrev_b32_e32 v166, 16, v162
	v_and_b32_e32 v167, 0xffff0000, v162
	v_lshlrev_b32_e32 v162, 16, v163
	v_and_b32_e32 v163, 0xffff0000, v163
	v_pk_add_f32 v[126:127], v[126:127], v[160:161]
	v_pk_add_f32 v[124:125], v[124:125], v[164:165]
	v_pk_add_f32 v[160:161], v[122:123], v[162:163]
	v_pk_add_f32 v[122:123], v[120:121], v[166:167]
	v_mul_f32_e32 v120, v125, v125
	v_mul_f32_e32 v121, v127, v127
	v_fmac_f32_e32 v120, v124, v124
	v_fmac_f32_e32 v121, v126, v126
	v_add_f32_e32 v120, v120, v121
	v_mul_f32_e32 v121, v123, v123
	v_fmac_f32_e32 v121, v122, v122
	v_add_f32_e32 v120, v121, v120
	v_mul_f32_e32 v121, v161, v161
	v_fmac_f32_e32 v121, v160, v160
	v_add_f32_e32 v159, v121, v120
	v_cvt_pk_bf16_f32 v120, v124, v125
	v_cvt_pk_bf16_f32 v121, v126, v127
	v_cvt_pk_bf16_f32 v122, v122, v123
	v_cvt_pk_bf16_f32 v123, v160, v161
	global_store_dwordx4 v[148:149], v[120:123], off
	s_nop 1
	v_mov_b64_e32 v[120:121], v[172:173]
	v_mov_b64_e32 v[122:123], v[174:175]
	s_nop 1
	v_lshlrev_b32_e32 v124, 16, v120
	v_and_b32_e32 v125, 0xffff0000, v120
	v_lshlrev_b32_e32 v120, 16, v121
	v_and_b32_e32 v121, 0xffff0000, v121
	v_lshlrev_b32_e32 v126, 16, v122
	v_and_b32_e32 v127, 0xffff0000, v122
	v_lshlrev_b32_e32 v122, 16, v123
	v_and_b32_e32 v123, 0xffff0000, v123
	v_pk_add_f32 v[118:119], v[118:119], v[120:121]
	v_pk_add_f32 v[116:117], v[116:117], v[124:125]
	v_pk_add_f32 v[120:121], v[114:115], v[122:123]
	v_pk_add_f32 v[114:115], v[112:113], v[126:127]
	v_mul_f32_e32 v112, v117, v117
	v_mul_f32_e32 v113, v119, v119
	v_fmac_f32_e32 v112, v116, v116
	v_fmac_f32_e32 v113, v118, v118
	v_add_f32_e32 v112, v112, v113
	v_mul_f32_e32 v113, v115, v115
	v_fmac_f32_e32 v113, v114, v114
	v_add_f32_e32 v112, v113, v112
	v_mul_f32_e32 v113, v121, v121
	v_fmac_f32_e32 v113, v120, v120
	v_add_f32_e32 v112, v113, v112
	v_add_f32_e32 v122, v159, v112
	v_cvt_pk_bf16_f32 v112, v116, v117
	v_cvt_pk_bf16_f32 v113, v118, v119
	v_cvt_pk_bf16_f32 v114, v114, v115
	v_cvt_pk_bf16_f32 v115, v120, v121
	global_store_dwordx4 v[148:149], v[112:115], off offset:256
	ds_bpermute_b32 v112, v158, v122
	s_waitcnt lgkmcnt(0)
	v_add_f32_e32 v112, v122, v112
	ds_bpermute_b32 v113, v157, v112
	s_and_saveexec_b64 s[4:5], s[10:11]
	s_cbranch_execz .LBB0_1074
	s_waitcnt lgkmcnt(0)
	v_add_f32_e32 v114, v112, v113
	v_lshlrev_b64 v[112:113], 6, v[146:147]
	v_lshl_add_u64 v[112:113], s[62:63], 0, v[112:113]
	v_lshl_add_u64 v[112:113], s[68:69], 2, v[112:113]
	s_lshl_b32 s24, s57, 2
	v_lshl_add_u64 v[112:113], v[112:113], 0, s[24:25]
	global_store_dword v[112:113], v114, off
.LBB0_1074:
	s_or_b64 exec, exec, s[4:5]
	v_or_b32_e32 v112, 16, v146
	s_waitcnt lgkmcnt(0)
	v_ashrrev_i32_e32 v113, 31, v112
	v_lshlrev_b64 v[114:115], 11, v[112:113]
	v_lshl_add_u64 v[114:115], s[48:49], 0, v[114:115]
	v_lshl_add_u64 v[114:115], v[144:145], 1, v[114:115]
	s_nop 1
	v_mov_b64_e32 v[116:117], v[176:177]
	v_mov_b64_e32 v[118:119], v[178:179]
	s_nop 1
	v_lshlrev_b32_e32 v120, 16, v116
	v_and_b32_e32 v121, 0xffff0000, v116
	v_lshlrev_b32_e32 v116, 16, v117
	v_and_b32_e32 v117, 0xffff0000, v117
	v_lshlrev_b32_e32 v122, 16, v118
	v_and_b32_e32 v123, 0xffff0000, v118
	v_lshlrev_b32_e32 v118, 16, v119
	v_and_b32_e32 v119, 0xffff0000, v119
	v_pk_add_f32 v[110:111], v[110:111], v[116:117]
	v_pk_add_f32 v[108:109], v[108:109], v[120:121]
	v_pk_add_f32 v[116:117], v[106:107], v[118:119]
	v_pk_add_f32 v[106:107], v[104:105], v[122:123]
	v_mul_f32_e32 v104, v109, v109
	v_mul_f32_e32 v105, v111, v111
	v_fmac_f32_e32 v104, v108, v108
	v_fmac_f32_e32 v105, v110, v110
	v_add_f32_e32 v104, v104, v105
	v_mul_f32_e32 v105, v107, v107
	v_fmac_f32_e32 v105, v106, v106
	v_add_f32_e32 v104, v105, v104
	v_mul_f32_e32 v105, v117, v117
	v_fmac_f32_e32 v105, v116, v116
	v_add_f32_e32 v118, v105, v104
	v_cvt_pk_bf16_f32 v104, v108, v109
	v_cvt_pk_bf16_f32 v105, v110, v111
	v_cvt_pk_bf16_f32 v106, v106, v107
	v_cvt_pk_bf16_f32 v107, v116, v117
	global_store_dwordx4 v[114:115], v[104:107], off
	s_nop 1
	v_mov_b64_e32 v[104:105], v[180:181]
	v_mov_b64_e32 v[106:107], v[182:183]
	s_nop 1
	v_lshlrev_b32_e32 v108, 16, v104
	v_and_b32_e32 v109, 0xffff0000, v104
	v_lshlrev_b32_e32 v104, 16, v105
	v_and_b32_e32 v105, 0xffff0000, v105
	v_lshlrev_b32_e32 v110, 16, v106
	v_and_b32_e32 v111, 0xffff0000, v106
	v_lshlrev_b32_e32 v106, 16, v107
	v_and_b32_e32 v107, 0xffff0000, v107
	v_pk_add_f32 v[102:103], v[102:103], v[104:105]
	v_pk_add_f32 v[100:101], v[100:101], v[108:109]
	v_pk_add_f32 v[104:105], v[98:99], v[106:107]
	v_pk_add_f32 v[98:99], v[96:97], v[110:111]
	v_mul_f32_e32 v96, v101, v101
	v_mul_f32_e32 v97, v103, v103
	v_fmac_f32_e32 v96, v100, v100
	v_fmac_f32_e32 v97, v102, v102
	v_add_f32_e32 v96, v96, v97
	v_mul_f32_e32 v97, v99, v99
	v_fmac_f32_e32 v97, v98, v98
	v_add_f32_e32 v96, v97, v96
	v_mul_f32_e32 v97, v105, v105
	v_fmac_f32_e32 v97, v104, v104
	v_add_f32_e32 v96, v97, v96
	v_add_f32_e32 v106, v118, v96
	v_cvt_pk_bf16_f32 v96, v100, v101
	v_cvt_pk_bf16_f32 v97, v102, v103
	v_cvt_pk_bf16_f32 v98, v98, v99
	v_cvt_pk_bf16_f32 v99, v104, v105
	global_store_dwordx4 v[114:115], v[96:99], off offset:256
	ds_bpermute_b32 v96, v158, v106
	s_waitcnt lgkmcnt(0)
	v_add_f32_e32 v96, v106, v96
	ds_bpermute_b32 v97, v157, v96
	s_and_saveexec_b64 s[4:5], s[10:11]
	s_cbranch_execz .LBB0_1076
	s_waitcnt lgkmcnt(0)
	v_add_f32_e32 v98, v96, v97
	v_lshlrev_b64 v[96:97], 6, v[112:113]
	v_lshl_add_u64 v[96:97], s[62:63], 0, v[96:97]
	v_lshl_add_u64 v[96:97], s[68:69], 2, v[96:97]
	s_lshl_b32 s24, s57, 2
	v_lshl_add_u64 v[96:97], v[96:97], 0, s[24:25]
	global_store_dword v[96:97], v98, off
.LBB0_1076:
	s_or_b64 exec, exec, s[4:5]
	v_or_b32_e32 v96, 32, v146
	s_waitcnt lgkmcnt(0)
	v_ashrrev_i32_e32 v97, 31, v96
	v_lshlrev_b64 v[98:99], 11, v[96:97]
	v_lshl_add_u64 v[98:99], s[48:49], 0, v[98:99]
	v_lshl_add_u64 v[98:99], v[144:145], 1, v[98:99]
	s_nop 1
	v_mov_b64_e32 v[100:101], v[184:185]
	v_mov_b64_e32 v[102:103], v[186:187]
	s_nop 1
	v_lshlrev_b32_e32 v104, 16, v100
	v_and_b32_e32 v105, 0xffff0000, v100
	v_lshlrev_b32_e32 v100, 16, v101
	v_and_b32_e32 v101, 0xffff0000, v101
	v_lshlrev_b32_e32 v106, 16, v102
	v_and_b32_e32 v107, 0xffff0000, v102
	v_lshlrev_b32_e32 v102, 16, v103
	v_and_b32_e32 v103, 0xffff0000, v103
	v_pk_add_f32 v[94:95], v[94:95], v[100:101]
	v_pk_add_f32 v[92:93], v[92:93], v[104:105]
	v_pk_add_f32 v[100:101], v[90:91], v[102:103]
	v_pk_add_f32 v[90:91], v[88:89], v[106:107]
	v_mul_f32_e32 v88, v93, v93
	v_mul_f32_e32 v89, v95, v95
	v_fmac_f32_e32 v88, v92, v92
	v_fmac_f32_e32 v89, v94, v94
	v_add_f32_e32 v88, v88, v89
	v_mul_f32_e32 v89, v91, v91
	v_fmac_f32_e32 v89, v90, v90
	v_add_f32_e32 v88, v89, v88
	v_mul_f32_e32 v89, v101, v101
	v_fmac_f32_e32 v89, v100, v100
	v_add_f32_e32 v102, v89, v88
	v_cvt_pk_bf16_f32 v88, v92, v93
	v_cvt_pk_bf16_f32 v89, v94, v95
	v_cvt_pk_bf16_f32 v90, v90, v91
	v_cvt_pk_bf16_f32 v91, v100, v101
	global_store_dwordx4 v[98:99], v[88:91], off
	s_nop 1
	v_mov_b64_e32 v[88:89], v[188:189]
	v_mov_b64_e32 v[90:91], v[190:191]
	s_nop 1
	v_lshlrev_b32_e32 v92, 16, v88
	v_and_b32_e32 v93, 0xffff0000, v88
	v_lshlrev_b32_e32 v88, 16, v89
	v_and_b32_e32 v89, 0xffff0000, v89
	v_lshlrev_b32_e32 v94, 16, v90
	v_and_b32_e32 v95, 0xffff0000, v90
	v_lshlrev_b32_e32 v90, 16, v91
	v_and_b32_e32 v91, 0xffff0000, v91
	v_pk_add_f32 v[86:87], v[86:87], v[88:89]
	v_pk_add_f32 v[84:85], v[84:85], v[92:93]
	v_pk_add_f32 v[88:89], v[82:83], v[90:91]
	v_pk_add_f32 v[82:83], v[80:81], v[94:95]
	v_mul_f32_e32 v80, v85, v85
	v_mul_f32_e32 v81, v87, v87
	v_fmac_f32_e32 v80, v84, v84
	v_fmac_f32_e32 v81, v86, v86
	v_add_f32_e32 v80, v80, v81
	v_mul_f32_e32 v81, v83, v83
	v_fmac_f32_e32 v81, v82, v82
	v_add_f32_e32 v80, v81, v80
	v_mul_f32_e32 v81, v89, v89
	v_fmac_f32_e32 v81, v88, v88
	v_add_f32_e32 v80, v81, v80
	v_add_f32_e32 v90, v102, v80
	v_cvt_pk_bf16_f32 v80, v84, v85
	v_cvt_pk_bf16_f32 v81, v86, v87
	v_cvt_pk_bf16_f32 v82, v82, v83
	v_cvt_pk_bf16_f32 v83, v88, v89
	global_store_dwordx4 v[98:99], v[80:83], off offset:256
	ds_bpermute_b32 v80, v158, v90
	s_waitcnt lgkmcnt(0)
	v_add_f32_e32 v80, v90, v80
	ds_bpermute_b32 v81, v157, v80
	s_and_saveexec_b64 s[4:5], s[10:11]
	s_cbranch_execz .LBB0_1078
	s_waitcnt lgkmcnt(0)
	v_add_f32_e32 v82, v80, v81
	v_lshlrev_b64 v[80:81], 6, v[96:97]
	v_lshl_add_u64 v[80:81], s[62:63], 0, v[80:81]
	v_lshl_add_u64 v[80:81], s[68:69], 2, v[80:81]
	s_lshl_b32 s24, s57, 2
	v_lshl_add_u64 v[80:81], v[80:81], 0, s[24:25]
	global_store_dword v[80:81], v82, off
.LBB0_1078:
	s_or_b64 exec, exec, s[4:5]
	v_or_b32_e32 v80, 48, v146
	s_waitcnt lgkmcnt(0)
	v_ashrrev_i32_e32 v81, 31, v80
	v_lshlrev_b64 v[82:83], 11, v[80:81]
	v_lshl_add_u64 v[82:83], s[48:49], 0, v[82:83]
	v_lshl_add_u64 v[82:83], v[144:145], 1, v[82:83]
	s_nop 1
	v_mov_b64_e32 v[84:85], v[192:193]
	v_mov_b64_e32 v[86:87], v[194:195]
	s_nop 1
	v_lshlrev_b32_e32 v88, 16, v84
	v_and_b32_e32 v89, 0xffff0000, v84
	v_lshlrev_b32_e32 v84, 16, v85
	v_and_b32_e32 v85, 0xffff0000, v85
	v_lshlrev_b32_e32 v90, 16, v86
	v_and_b32_e32 v91, 0xffff0000, v86
	v_lshlrev_b32_e32 v86, 16, v87
	v_and_b32_e32 v87, 0xffff0000, v87
	v_pk_add_f32 v[78:79], v[78:79], v[84:85]
	v_pk_add_f32 v[76:77], v[76:77], v[88:89]
	v_pk_add_f32 v[84:85], v[74:75], v[86:87]
	v_pk_add_f32 v[74:75], v[72:73], v[90:91]
	v_mul_f32_e32 v72, v77, v77
	v_mul_f32_e32 v73, v79, v79
	v_fmac_f32_e32 v72, v76, v76
	v_fmac_f32_e32 v73, v78, v78
	v_add_f32_e32 v72, v72, v73
	v_mul_f32_e32 v73, v75, v75
	v_fmac_f32_e32 v73, v74, v74
	v_add_f32_e32 v72, v73, v72
	v_mul_f32_e32 v73, v85, v85
	v_fmac_f32_e32 v73, v84, v84
	v_add_f32_e32 v86, v73, v72
	v_cvt_pk_bf16_f32 v72, v76, v77
	v_cvt_pk_bf16_f32 v73, v78, v79
	v_cvt_pk_bf16_f32 v74, v74, v75
	v_cvt_pk_bf16_f32 v75, v84, v85
	global_store_dwordx4 v[82:83], v[72:75], off
	s_nop 1
	v_mov_b64_e32 v[72:73], v[196:197]
	v_mov_b64_e32 v[74:75], v[198:199]
	s_nop 1
	v_lshlrev_b32_e32 v76, 16, v72
	v_and_b32_e32 v77, 0xffff0000, v72
	v_lshlrev_b32_e32 v72, 16, v73
	v_and_b32_e32 v73, 0xffff0000, v73
	v_lshlrev_b32_e32 v78, 16, v74
	v_and_b32_e32 v79, 0xffff0000, v74
	v_lshlrev_b32_e32 v74, 16, v75
	v_and_b32_e32 v75, 0xffff0000, v75
	v_pk_add_f32 v[70:71], v[70:71], v[72:73]
	v_pk_add_f32 v[68:69], v[68:69], v[76:77]
	v_pk_add_f32 v[72:73], v[66:67], v[74:75]
	v_pk_add_f32 v[66:67], v[64:65], v[78:79]
	v_mul_f32_e32 v64, v69, v69
	v_mul_f32_e32 v65, v71, v71
	v_fmac_f32_e32 v64, v68, v68
	v_fmac_f32_e32 v65, v70, v70
	v_add_f32_e32 v64, v64, v65
	v_mul_f32_e32 v65, v67, v67
	v_fmac_f32_e32 v65, v66, v66
	v_add_f32_e32 v64, v65, v64
	v_mul_f32_e32 v65, v73, v73
	v_fmac_f32_e32 v65, v72, v72
	v_add_f32_e32 v64, v65, v64
	v_add_f32_e32 v74, v86, v64
	v_cvt_pk_bf16_f32 v64, v68, v69
	v_cvt_pk_bf16_f32 v65, v70, v71
	v_cvt_pk_bf16_f32 v66, v66, v67
	v_cvt_pk_bf16_f32 v67, v72, v73
	global_store_dwordx4 v[82:83], v[64:67], off offset:256
	ds_bpermute_b32 v64, v158, v74
	s_waitcnt lgkmcnt(0)
	v_add_f32_e32 v64, v74, v64
	ds_bpermute_b32 v65, v157, v64
	s_and_saveexec_b64 s[4:5], s[10:11]
	s_cbranch_execz .LBB0_1080
	s_waitcnt lgkmcnt(0)
	v_add_f32_e32 v66, v64, v65
	v_lshlrev_b64 v[64:65], 6, v[80:81]
	v_lshl_add_u64 v[64:65], s[62:63], 0, v[64:65]
	v_lshl_add_u64 v[64:65], s[68:69], 2, v[64:65]
	s_lshl_b32 s24, s57, 2
	v_lshl_add_u64 v[64:65], v[64:65], 0, s[24:25]
	global_store_dword v[64:65], v66, off
.LBB0_1080:
	s_or_b64 exec, exec, s[4:5]
	v_add_u32_e32 v64, 0x80, v146
	s_waitcnt lgkmcnt(0)
	v_ashrrev_i32_e32 v65, 31, v64
	v_lshlrev_b64 v[66:67], 11, v[64:65]
	v_lshl_add_u64 v[66:67], s[48:49], 0, v[66:67]
	v_lshl_add_u64 v[66:67], v[144:145], 1, v[66:67]
	v_add_co_u32_e32 v204, vcc, 0x40000, v206
	s_nop 1
	v_addc_co_u32_e32 v205, vcc, 0, v207, vcc
	global_load_dwordx4 v[168:171], v[204:205], off
	v_add_co_u32_e32 v204, vcc, 0x40100, v206
	s_nop 1
	v_addc_co_u32_e32 v205, vcc, 0, v207, vcc
	global_load_dwordx4 v[172:175], v[204:205], off
	v_add_co_u32_e32 v204, vcc, 0x48000, v206
	s_nop 1
	v_addc_co_u32_e32 v205, vcc, 0, v207, vcc
	global_load_dwordx4 v[176:179], v[204:205], off
	v_add_co_u32_e32 v204, vcc, 0x48100, v206
	s_nop 1
	v_addc_co_u32_e32 v205, vcc, 0, v207, vcc
	global_load_dwordx4 v[180:183], v[204:205], off
	v_add_co_u32_e32 v204, vcc, 0x50000, v206
	s_nop 1
	v_addc_co_u32_e32 v205, vcc, 0, v207, vcc
	global_load_dwordx4 v[184:187], v[204:205], off
	v_add_co_u32_e32 v204, vcc, 0x50100, v206
	s_nop 1
	v_addc_co_u32_e32 v205, vcc, 0, v207, vcc
	global_load_dwordx4 v[188:191], v[204:205], off
	v_add_co_u32_e32 v204, vcc, 0x58000, v206
	s_nop 1
	v_addc_co_u32_e32 v205, vcc, 0, v207, vcc
	global_load_dwordx4 v[192:195], v[204:205], off
	v_add_co_u32_e32 v204, vcc, 0x58100, v206
	s_nop 1
	v_addc_co_u32_e32 v205, vcc, 0, v207, vcc
	global_load_dwordx4 v[196:199], v[204:205], off
	s_waitcnt vmcnt(0)
	s_nop 1
	v_mov_b64_e32 v[68:69], v[168:169]
	v_mov_b64_e32 v[70:71], v[170:171]
	s_nop 1
	v_lshlrev_b32_e32 v72, 16, v68
	v_and_b32_e32 v73, 0xffff0000, v68
	v_lshlrev_b32_e32 v68, 16, v69
	v_and_b32_e32 v69, 0xffff0000, v69
	v_lshlrev_b32_e32 v74, 16, v70
	v_and_b32_e32 v75, 0xffff0000, v70
	v_lshlrev_b32_e32 v70, 16, v71
	v_and_b32_e32 v71, 0xffff0000, v71
	v_pk_add_f32 v[62:63], v[62:63], v[68:69]
	v_pk_add_f32 v[60:61], v[60:61], v[72:73]
	v_pk_add_f32 v[68:69], v[58:59], v[70:71]
	v_pk_add_f32 v[58:59], v[56:57], v[74:75]
	v_mul_f32_e32 v56, v61, v61
	v_mul_f32_e32 v57, v63, v63
	v_fmac_f32_e32 v56, v60, v60
	v_fmac_f32_e32 v57, v62, v62
	v_add_f32_e32 v56, v56, v57
	v_mul_f32_e32 v57, v59, v59
	v_fmac_f32_e32 v57, v58, v58
	v_add_f32_e32 v56, v57, v56
	v_mul_f32_e32 v57, v69, v69
	v_fmac_f32_e32 v57, v68, v68
	v_add_f32_e32 v70, v57, v56
	v_cvt_pk_bf16_f32 v56, v60, v61
	v_cvt_pk_bf16_f32 v57, v62, v63
	v_cvt_pk_bf16_f32 v58, v58, v59
	v_cvt_pk_bf16_f32 v59, v68, v69
	global_store_dwordx4 v[66:67], v[56:59], off
	s_nop 1
	v_mov_b64_e32 v[56:57], v[172:173]
	v_mov_b64_e32 v[58:59], v[174:175]
	s_nop 1
	v_lshlrev_b32_e32 v60, 16, v56
	v_and_b32_e32 v61, 0xffff0000, v56
	v_lshlrev_b32_e32 v56, 16, v57
	v_and_b32_e32 v57, 0xffff0000, v57
	v_lshlrev_b32_e32 v62, 16, v58
	v_and_b32_e32 v63, 0xffff0000, v58
	v_lshlrev_b32_e32 v58, 16, v59
	v_and_b32_e32 v59, 0xffff0000, v59
	v_pk_add_f32 v[54:55], v[54:55], v[56:57]
	v_pk_add_f32 v[52:53], v[52:53], v[60:61]
	v_pk_add_f32 v[56:57], v[50:51], v[58:59]
	v_pk_add_f32 v[50:51], v[48:49], v[62:63]
	v_mul_f32_e32 v48, v53, v53
	v_mul_f32_e32 v49, v55, v55
	v_fmac_f32_e32 v48, v52, v52
	v_fmac_f32_e32 v49, v54, v54
	v_add_f32_e32 v48, v48, v49
	v_mul_f32_e32 v49, v51, v51
	v_fmac_f32_e32 v49, v50, v50
	v_add_f32_e32 v48, v49, v48
	v_mul_f32_e32 v49, v57, v57
	v_fmac_f32_e32 v49, v56, v56
	v_add_f32_e32 v48, v49, v48
	v_add_f32_e32 v58, v70, v48
	v_cvt_pk_bf16_f32 v48, v52, v53
	v_cvt_pk_bf16_f32 v49, v54, v55
	v_cvt_pk_bf16_f32 v50, v50, v51
	v_cvt_pk_bf16_f32 v51, v56, v57
	global_store_dwordx4 v[66:67], v[48:51], off offset:256
	ds_bpermute_b32 v48, v158, v58
	s_waitcnt lgkmcnt(0)
	v_add_f32_e32 v48, v58, v48
	ds_bpermute_b32 v49, v157, v48
	s_and_saveexec_b64 s[4:5], s[10:11]
	s_cbranch_execz .LBB0_1082
	s_waitcnt lgkmcnt(0)
	v_add_f32_e32 v50, v48, v49
	v_lshlrev_b64 v[48:49], 6, v[64:65]
	v_lshl_add_u64 v[48:49], s[62:63], 0, v[48:49]
	v_lshl_add_u64 v[48:49], s[68:69], 2, v[48:49]
	s_lshl_b32 s24, s57, 2
	v_lshl_add_u64 v[48:49], v[48:49], 0, s[24:25]
	global_store_dword v[48:49], v50, off
.LBB0_1082:
	s_or_b64 exec, exec, s[4:5]
	v_add_u32_e32 v48, 0x90, v146
	s_waitcnt lgkmcnt(0)
	v_ashrrev_i32_e32 v49, 31, v48
	v_lshlrev_b64 v[50:51], 11, v[48:49]
	v_lshl_add_u64 v[50:51], s[48:49], 0, v[50:51]
	v_lshl_add_u64 v[50:51], v[144:145], 1, v[50:51]
	s_nop 1
	v_mov_b64_e32 v[52:53], v[176:177]
	v_mov_b64_e32 v[54:55], v[178:179]
	s_nop 1
	v_lshlrev_b32_e32 v56, 16, v52
	v_and_b32_e32 v57, 0xffff0000, v52
	v_lshlrev_b32_e32 v52, 16, v53
	v_and_b32_e32 v53, 0xffff0000, v53
	v_lshlrev_b32_e32 v58, 16, v54
	v_and_b32_e32 v59, 0xffff0000, v54
	v_lshlrev_b32_e32 v54, 16, v55
	v_and_b32_e32 v55, 0xffff0000, v55
	v_pk_add_f32 v[46:47], v[46:47], v[52:53]
	v_pk_add_f32 v[44:45], v[44:45], v[56:57]
	v_pk_add_f32 v[52:53], v[42:43], v[54:55]
	v_pk_add_f32 v[42:43], v[40:41], v[58:59]
	v_mul_f32_e32 v40, v45, v45
	v_mul_f32_e32 v41, v47, v47
	v_fmac_f32_e32 v40, v44, v44
	v_fmac_f32_e32 v41, v46, v46
	v_add_f32_e32 v40, v40, v41
	v_mul_f32_e32 v41, v43, v43
	v_fmac_f32_e32 v41, v42, v42
	v_add_f32_e32 v40, v41, v40
	v_mul_f32_e32 v41, v53, v53
	v_fmac_f32_e32 v41, v52, v52
	v_add_f32_e32 v54, v41, v40
	v_cvt_pk_bf16_f32 v40, v44, v45
	v_cvt_pk_bf16_f32 v41, v46, v47
	v_cvt_pk_bf16_f32 v42, v42, v43
	v_cvt_pk_bf16_f32 v43, v52, v53
	global_store_dwordx4 v[50:51], v[40:43], off
	s_nop 1
	v_mov_b64_e32 v[40:41], v[180:181]
	v_mov_b64_e32 v[42:43], v[182:183]
	s_nop 1
	v_lshlrev_b32_e32 v44, 16, v40
	v_and_b32_e32 v45, 0xffff0000, v40
	v_lshlrev_b32_e32 v40, 16, v41
	v_and_b32_e32 v41, 0xffff0000, v41
	v_lshlrev_b32_e32 v46, 16, v42
	v_and_b32_e32 v47, 0xffff0000, v42
	v_lshlrev_b32_e32 v42, 16, v43
	v_and_b32_e32 v43, 0xffff0000, v43
	v_pk_add_f32 v[38:39], v[38:39], v[40:41]
	v_pk_add_f32 v[36:37], v[36:37], v[44:45]
	v_pk_add_f32 v[40:41], v[34:35], v[42:43]
	v_pk_add_f32 v[34:35], v[32:33], v[46:47]
	v_mul_f32_e32 v32, v37, v37
	v_mul_f32_e32 v33, v39, v39
	v_fmac_f32_e32 v32, v36, v36
	v_fmac_f32_e32 v33, v38, v38
	v_add_f32_e32 v32, v32, v33
	v_mul_f32_e32 v33, v35, v35
	v_fmac_f32_e32 v33, v34, v34
	v_add_f32_e32 v32, v33, v32
	v_mul_f32_e32 v33, v41, v41
	v_fmac_f32_e32 v33, v40, v40
	v_add_f32_e32 v32, v33, v32
	v_add_f32_e32 v42, v54, v32
	v_cvt_pk_bf16_f32 v32, v36, v37
	v_cvt_pk_bf16_f32 v33, v38, v39
	v_cvt_pk_bf16_f32 v34, v34, v35
	v_cvt_pk_bf16_f32 v35, v40, v41
	global_store_dwordx4 v[50:51], v[32:35], off offset:256
	ds_bpermute_b32 v32, v158, v42
	s_waitcnt lgkmcnt(0)
	v_add_f32_e32 v32, v42, v32
	ds_bpermute_b32 v33, v157, v32
	s_and_saveexec_b64 s[4:5], s[10:11]
	s_cbranch_execz .LBB0_1084
	s_waitcnt lgkmcnt(0)
	v_add_f32_e32 v34, v32, v33
	v_lshlrev_b64 v[32:33], 6, v[48:49]
	v_lshl_add_u64 v[32:33], s[62:63], 0, v[32:33]
	v_lshl_add_u64 v[32:33], s[68:69], 2, v[32:33]
	s_lshl_b32 s24, s57, 2
	v_lshl_add_u64 v[32:33], v[32:33], 0, s[24:25]
	global_store_dword v[32:33], v34, off
.LBB0_1084:
	s_or_b64 exec, exec, s[4:5]
	v_add_u32_e32 v32, 0xa0, v146
	s_waitcnt lgkmcnt(0)
	v_ashrrev_i32_e32 v33, 31, v32
	v_lshlrev_b64 v[34:35], 11, v[32:33]
	v_lshl_add_u64 v[34:35], s[48:49], 0, v[34:35]
	v_lshl_add_u64 v[34:35], v[144:145], 1, v[34:35]
	s_nop 1
	v_mov_b64_e32 v[36:37], v[184:185]
	v_mov_b64_e32 v[38:39], v[186:187]
	s_nop 1
	v_lshlrev_b32_e32 v40, 16, v36
	v_and_b32_e32 v41, 0xffff0000, v36
	v_lshlrev_b32_e32 v36, 16, v37
	v_and_b32_e32 v37, 0xffff0000, v37
	v_lshlrev_b32_e32 v42, 16, v38
	v_and_b32_e32 v43, 0xffff0000, v38
	v_lshlrev_b32_e32 v38, 16, v39
	v_and_b32_e32 v39, 0xffff0000, v39
	v_pk_add_f32 v[30:31], v[30:31], v[36:37]
	v_pk_add_f32 v[28:29], v[28:29], v[40:41]
	v_pk_add_f32 v[36:37], v[26:27], v[38:39]
	v_pk_add_f32 v[26:27], v[24:25], v[42:43]
	v_mul_f32_e32 v24, v29, v29
	v_mul_f32_e32 v25, v31, v31
	v_fmac_f32_e32 v24, v28, v28
	v_fmac_f32_e32 v25, v30, v30
	v_add_f32_e32 v24, v24, v25
	v_mul_f32_e32 v25, v27, v27
	v_fmac_f32_e32 v25, v26, v26
	v_add_f32_e32 v24, v25, v24
	v_mul_f32_e32 v25, v37, v37
	v_fmac_f32_e32 v25, v36, v36
	v_add_f32_e32 v38, v25, v24
	v_cvt_pk_bf16_f32 v24, v28, v29
	v_cvt_pk_bf16_f32 v25, v30, v31
	v_cvt_pk_bf16_f32 v26, v26, v27
	v_cvt_pk_bf16_f32 v27, v36, v37
	global_store_dwordx4 v[34:35], v[24:27], off
	s_nop 1
	v_mov_b64_e32 v[24:25], v[188:189]
	v_mov_b64_e32 v[26:27], v[190:191]
	s_nop 1
	v_lshlrev_b32_e32 v28, 16, v24
	v_and_b32_e32 v29, 0xffff0000, v24
	v_lshlrev_b32_e32 v24, 16, v25
	v_and_b32_e32 v25, 0xffff0000, v25
	v_lshlrev_b32_e32 v30, 16, v26
	v_and_b32_e32 v31, 0xffff0000, v26
	v_lshlrev_b32_e32 v26, 16, v27
	v_and_b32_e32 v27, 0xffff0000, v27
	v_pk_add_f32 v[22:23], v[22:23], v[24:25]
	v_pk_add_f32 v[20:21], v[20:21], v[28:29]
	v_pk_add_f32 v[24:25], v[18:19], v[26:27]
	v_pk_add_f32 v[18:19], v[16:17], v[30:31]
	v_mul_f32_e32 v16, v21, v21
	v_mul_f32_e32 v17, v23, v23
	v_fmac_f32_e32 v16, v20, v20
	v_fmac_f32_e32 v17, v22, v22
	v_add_f32_e32 v16, v16, v17
	v_mul_f32_e32 v17, v19, v19
	v_fmac_f32_e32 v17, v18, v18
	v_add_f32_e32 v16, v17, v16
	v_mul_f32_e32 v17, v25, v25
	v_fmac_f32_e32 v17, v24, v24
	v_add_f32_e32 v16, v17, v16
	v_add_f32_e32 v26, v38, v16
	v_cvt_pk_bf16_f32 v16, v20, v21
	v_cvt_pk_bf16_f32 v17, v22, v23
	v_cvt_pk_bf16_f32 v18, v18, v19
	v_cvt_pk_bf16_f32 v19, v24, v25
	global_store_dwordx4 v[34:35], v[16:19], off offset:256
	ds_bpermute_b32 v16, v158, v26
	s_waitcnt lgkmcnt(0)
	v_add_f32_e32 v16, v26, v16
	ds_bpermute_b32 v17, v157, v16
	s_and_saveexec_b64 s[4:5], s[10:11]
	s_cbranch_execz .LBB0_1086
	s_waitcnt lgkmcnt(0)
	v_add_f32_e32 v18, v16, v17
	v_lshlrev_b64 v[16:17], 6, v[32:33]
	v_lshl_add_u64 v[16:17], s[62:63], 0, v[16:17]
	v_lshl_add_u64 v[16:17], s[68:69], 2, v[16:17]
	s_lshl_b32 s24, s57, 2
	v_lshl_add_u64 v[16:17], v[16:17], 0, s[24:25]
	global_store_dword v[16:17], v18, off
.LBB0_1086:
	s_or_b64 exec, exec, s[4:5]
	v_add_u32_e32 v16, 0xb0, v146
	s_waitcnt lgkmcnt(0)
	v_ashrrev_i32_e32 v17, 31, v16
	v_lshlrev_b64 v[18:19], 11, v[16:17]
	v_lshl_add_u64 v[18:19], s[48:49], 0, v[18:19]
	v_lshl_add_u64 v[18:19], v[144:145], 1, v[18:19]
	s_nop 1
	v_mov_b64_e32 v[20:21], v[192:193]
	v_mov_b64_e32 v[22:23], v[194:195]
	s_nop 1
	v_lshlrev_b32_e32 v24, 16, v20
	v_and_b32_e32 v25, 0xffff0000, v20
	v_lshlrev_b32_e32 v20, 16, v21
	v_and_b32_e32 v21, 0xffff0000, v21
	v_lshlrev_b32_e32 v26, 16, v22
	v_and_b32_e32 v27, 0xffff0000, v22
	v_lshlrev_b32_e32 v22, 16, v23
	v_and_b32_e32 v23, 0xffff0000, v23
	v_pk_add_f32 v[14:15], v[14:15], v[20:21]
	v_pk_add_f32 v[12:13], v[12:13], v[24:25]
	v_pk_add_f32 v[20:21], v[10:11], v[22:23]
	v_pk_add_f32 v[10:11], v[8:9], v[26:27]
	v_mul_f32_e32 v8, v13, v13
	v_mul_f32_e32 v9, v15, v15
	v_fmac_f32_e32 v8, v12, v12
	v_fmac_f32_e32 v9, v14, v14
	v_add_f32_e32 v8, v8, v9
	v_mul_f32_e32 v9, v11, v11
	v_fmac_f32_e32 v9, v10, v10
	v_add_f32_e32 v8, v9, v8
	v_mul_f32_e32 v9, v21, v21
	v_fmac_f32_e32 v9, v20, v20
	v_add_f32_e32 v22, v9, v8
	v_cvt_pk_bf16_f32 v8, v12, v13
	v_cvt_pk_bf16_f32 v9, v14, v15
	v_cvt_pk_bf16_f32 v10, v10, v11
	v_cvt_pk_bf16_f32 v11, v20, v21
	global_store_dwordx4 v[18:19], v[8:11], off
	s_nop 1
	v_mov_b64_e32 v[8:9], v[196:197]
	v_mov_b64_e32 v[10:11], v[198:199]
	s_nop 1
	v_lshlrev_b32_e32 v12, 16, v8
	v_and_b32_e32 v13, 0xffff0000, v8
	v_lshlrev_b32_e32 v8, 16, v9
	v_and_b32_e32 v9, 0xffff0000, v9
	v_lshlrev_b32_e32 v14, 16, v10
	v_and_b32_e32 v15, 0xffff0000, v10
	v_lshlrev_b32_e32 v10, 16, v11
	v_and_b32_e32 v11, 0xffff0000, v11
	v_pk_add_f32 v[6:7], v[6:7], v[8:9]
	v_pk_add_f32 v[4:5], v[4:5], v[12:13]
	v_pk_add_f32 v[8:9], v[2:3], v[10:11]
	v_pk_add_f32 v[2:3], v[0:1], v[14:15]
	v_mul_f32_e32 v0, v5, v5
	v_mul_f32_e32 v1, v7, v7
	v_fmac_f32_e32 v0, v4, v4
	v_fmac_f32_e32 v1, v6, v6
	v_add_f32_e32 v0, v0, v1
	v_mul_f32_e32 v1, v3, v3
	v_fmac_f32_e32 v1, v2, v2
	v_add_f32_e32 v0, v1, v0
	v_mul_f32_e32 v1, v9, v9
	v_fmac_f32_e32 v1, v8, v8
	v_add_f32_e32 v0, v1, v0
	v_add_f32_e32 v10, v22, v0
	v_cvt_pk_bf16_f32 v0, v4, v5
	v_cvt_pk_bf16_f32 v1, v6, v7
	v_cvt_pk_bf16_f32 v2, v2, v3
	v_cvt_pk_bf16_f32 v3, v8, v9
	global_store_dwordx4 v[18:19], v[0:3], off offset:256
	ds_bpermute_b32 v0, v158, v10
	s_waitcnt lgkmcnt(0)
	v_add_f32_e32 v0, v10, v0
	ds_bpermute_b32 v1, v157, v0
	s_and_saveexec_b64 s[4:5], s[10:11]
	s_cbranch_execz .LBB0_1088
	s_waitcnt lgkmcnt(0)
	v_add_f32_e32 v2, v0, v1
	v_lshlrev_b64 v[0:1], 6, v[16:17]
	v_lshl_add_u64 v[0:1], s[62:63], 0, v[0:1]
	v_lshl_add_u64 v[0:1], s[68:69], 2, v[0:1]
	s_lshl_b32 s24, s57, 2
	v_lshl_add_u64 v[0:1], v[0:1], 0, s[24:25]
	global_store_dword v[0:1], v2, off

.LBB0_1690:
	v_lshl_add_u32 v146, s54, 8, v148
	v_ashrrev_i32_e32 v147, 31, v146
	v_lshl_or_b32 v144, s20, 8, v150
	v_lshlrev_b64 v[156:157], 11, v[146:147]
	v_ashrrev_i32_e32 v145, 31, v144
	v_lshl_add_u64 v[156:157], s[48:49], 0, v[156:157]
	v_lshl_add_u64 v[166:167], v[144:145], 1, v[156:157]
	v_mov_b64_e32 v[214:215], v[166:167]
	global_load_dwordx4 v[176:179], v[166:167], off
	v_add_co_u32_e32 v212, vcc, 0x100, v166
	s_nop 1
	v_addc_co_u32_e32 v213, vcc, 0, v167, vcc
	global_load_dwordx4 v[180:183], v[212:213], off
	v_add_co_u32_e32 v212, vcc, 0x8000, v166
	s_nop 1
	v_addc_co_u32_e32 v213, vcc, 0, v167, vcc
	global_load_dwordx4 v[184:187], v[212:213], off
	v_add_co_u32_e32 v212, vcc, 0x8100, v166
	s_nop 1
	v_addc_co_u32_e32 v213, vcc, 0, v167, vcc
	global_load_dwordx4 v[188:191], v[212:213], off
	v_add_co_u32_e32 v212, vcc, 0x10000, v166
	s_nop 1
	v_addc_co_u32_e32 v213, vcc, 0, v167, vcc
	global_load_dwordx4 v[192:195], v[212:213], off
	v_add_co_u32_e32 v212, vcc, 0x10100, v166
	s_nop 1
	v_addc_co_u32_e32 v213, vcc, 0, v167, vcc
	global_load_dwordx4 v[196:199], v[212:213], off
	v_add_co_u32_e32 v212, vcc, 0x18000, v166
	s_nop 1
	v_addc_co_u32_e32 v213, vcc, 0, v167, vcc
	global_load_dwordx4 v[204:207], v[212:213], off
	v_add_co_u32_e32 v212, vcc, 0x18100, v166
	s_nop 1
	v_addc_co_u32_e32 v213, vcc, 0, v167, vcc
	global_load_dwordx4 v[208:211], v[212:213], off
	s_waitcnt vmcnt(0)
	s_nop 1
	v_mov_b64_e32 v[158:159], v[176:177]
	v_mov_b64_e32 v[160:161], v[178:179]
	s_nop 1
	v_mov_b64_e32 v[162:163], v[180:181]
	v_mov_b64_e32 v[164:165], v[182:183]
	v_and_b32_e32 v156, 64, v154
	v_xor_b32_e32 v155, 16, v154
	v_add_u32_e32 v156, 64, v156
	v_xor_b32_e32 v157, 32, v154
	v_cmp_lt_i32_e32 vcc, v155, v156
	s_lshl_b32 s54, s20, 2
	s_ashr_i32 s55, s54, 31
	v_cndmask_b32_e32 v155, v154, v155, vcc
	v_cmp_lt_i32_e32 vcc, v157, v156
	v_lshlrev_b32_e32 v156, 2, v155
	s_nop 1
	v_lshlrev_b32_e32 v168, 16, v158
	v_and_b32_e32 v169, 0xffff0000, v158
	v_lshlrev_b32_e32 v158, 16, v159
	v_and_b32_e32 v159, 0xffff0000, v159
	v_lshlrev_b32_e32 v172, 16, v162
	v_and_b32_e32 v173, 0xffff0000, v162
	v_lshlrev_b32_e32 v162, 16, v163
	v_and_b32_e32 v163, 0xffff0000, v163
	v_lshlrev_b32_e32 v170, 16, v160
	v_and_b32_e32 v171, 0xffff0000, v160
	v_lshlrev_b32_e32 v160, 16, v161
	v_and_b32_e32 v161, 0xffff0000, v161
	v_lshlrev_b32_e32 v174, 16, v164
	v_and_b32_e32 v175, 0xffff0000, v164
	v_lshlrev_b32_e32 v164, 16, v165
	v_and_b32_e32 v165, 0xffff0000, v165
	v_pk_add_f32 v[126:127], v[126:127], v[158:159]
	v_pk_add_f32 v[124:125], v[124:125], v[168:169]
	v_pk_add_f32 v[118:119], v[118:119], v[162:163]
	v_pk_add_f32 v[116:117], v[116:117], v[172:173]
	v_cndmask_b32_e32 v157, v154, v157, vcc
	v_pk_add_f32 v[122:123], v[122:123], v[160:161]
	v_pk_add_f32 v[120:121], v[120:121], v[170:171]
	v_pk_add_f32 v[158:159], v[114:115], v[164:165]
	v_pk_add_f32 v[160:161], v[112:113], v[174:175]
	v_mul_f32_e32 v114, v125, v125
	v_mul_f32_e32 v115, v127, v127
	v_cvt_pk_bf16_f32 v112, v124, v125
	v_cvt_pk_bf16_f32 v113, v126, v127
	v_mul_f32_e32 v125, v117, v117
	v_mul_f32_e32 v127, v119, v119
	v_lshlrev_b32_e32 v155, 2, v157
	v_mul_f32_e32 v157, v121, v121
	v_mul_f32_e32 v163, v161, v161
	v_fmac_f32_e32 v114, v124, v124
	v_fmac_f32_e32 v115, v126, v126
	v_fmac_f32_e32 v125, v116, v116
	v_fmac_f32_e32 v127, v118, v118
	v_mul_f32_e32 v162, v123, v123
	v_mul_f32_e32 v164, v159, v159
	v_fmac_f32_e32 v157, v120, v120
	v_fmac_f32_e32 v163, v160, v160
	v_add_f32_e32 v114, v114, v115
	v_add_f32_e32 v115, v125, v127
	v_fmac_f32_e32 v162, v122, v122
	v_fmac_f32_e32 v164, v158, v158
	v_add_f32_e32 v114, v157, v114
	v_add_f32_e32 v115, v163, v115
	v_add_f32_e32 v114, v162, v114
	v_add_f32_e32 v115, v164, v115
	v_add_f32_e32 v124, v114, v115
	ds_bpermute_b32 v125, v156, v124
	v_cvt_pk_bf16_f32 v114, v120, v121
	v_cvt_pk_bf16_f32 v115, v122, v123
	global_store_dwordx4 v[166:167], v[112:115], off
	s_waitcnt lgkmcnt(0)
	s_nop 0
	v_add_f32_e32 v112, v124, v125
	ds_bpermute_b32 v113, v155, v112
	v_cvt_pk_bf16_f32 v114, v116, v117
	v_cvt_pk_bf16_f32 v115, v118, v119
	v_cvt_pk_bf16_f32 v116, v160, v161
	v_cvt_pk_bf16_f32 v117, v158, v159
	global_store_dwordx4 v[166:167], v[114:117], off offset:256
	s_and_saveexec_b64 s[4:5], s[6:7]
	s_cbranch_execz .LBB0_1692
	s_waitcnt lgkmcnt(0)
	v_add_f32_e32 v114, v112, v113
	v_lshlrev_b64 v[112:113], 6, v[146:147]
	v_lshl_add_u64 v[112:113], s[62:63], 0, v[112:113]
	v_lshl_add_u64 v[112:113], s[54:55], 2, v[112:113]
	s_lshl_b32 s20, s59, 2
	v_lshl_add_u64 v[112:113], v[112:113], 0, s[20:21]
	global_store_dword v[112:113], v114, off
.LBB0_1692:
	s_or_b64 exec, exec, s[4:5]
	v_or_b32_e32 v112, 16, v146
	s_waitcnt lgkmcnt(0)
	v_ashrrev_i32_e32 v113, 31, v112
	v_lshlrev_b64 v[114:115], 11, v[112:113]
	v_lshl_add_u64 v[114:115], s[48:49], 0, v[114:115]
	v_lshl_add_u64 v[122:123], v[144:145], 1, v[114:115]
	s_nop 1
	v_mov_b64_e32 v[114:115], v[184:185]
	v_mov_b64_e32 v[116:117], v[186:187]
	s_nop 1
	v_mov_b64_e32 v[118:119], v[188:189]
	v_mov_b64_e32 v[120:121], v[190:191]
	s_nop 1
	v_lshlrev_b32_e32 v124, 16, v114
	v_and_b32_e32 v125, 0xffff0000, v114
	v_lshlrev_b32_e32 v114, 16, v115
	v_and_b32_e32 v115, 0xffff0000, v115
	s_nop 1
	v_lshlrev_b32_e32 v158, 16, v118
	v_and_b32_e32 v159, 0xffff0000, v118
	v_lshlrev_b32_e32 v118, 16, v119
	v_and_b32_e32 v119, 0xffff0000, v119
	v_lshlrev_b32_e32 v126, 16, v116
	v_and_b32_e32 v127, 0xffff0000, v116
	v_lshlrev_b32_e32 v116, 16, v117
	v_and_b32_e32 v117, 0xffff0000, v117
	v_lshlrev_b32_e32 v160, 16, v120
	v_and_b32_e32 v161, 0xffff0000, v120
	v_lshlrev_b32_e32 v120, 16, v121
	v_and_b32_e32 v121, 0xffff0000, v121
	v_pk_add_f32 v[110:111], v[110:111], v[114:115]
	v_pk_add_f32 v[108:109], v[108:109], v[124:125]
	v_pk_add_f32 v[102:103], v[102:103], v[118:119]
	v_pk_add_f32 v[100:101], v[100:101], v[158:159]
	v_pk_add_f32 v[106:107], v[106:107], v[116:117]
	v_pk_add_f32 v[104:105], v[104:105], v[126:127]
	v_pk_add_f32 v[114:115], v[98:99], v[120:121]
	v_pk_add_f32 v[116:117], v[96:97], v[160:161]
	v_mul_f32_e32 v98, v109, v109
	v_mul_f32_e32 v99, v111, v111
	v_cvt_pk_bf16_f32 v96, v108, v109
	v_cvt_pk_bf16_f32 v97, v110, v111
	v_mul_f32_e32 v109, v101, v101
	v_mul_f32_e32 v111, v103, v103
	v_mul_f32_e32 v118, v105, v105
	v_mul_f32_e32 v120, v117, v117
	v_fmac_f32_e32 v98, v108, v108
	v_fmac_f32_e32 v99, v110, v110
	v_fmac_f32_e32 v109, v100, v100
	v_fmac_f32_e32 v111, v102, v102
	v_mul_f32_e32 v119, v107, v107
	v_mul_f32_e32 v121, v115, v115
	v_fmac_f32_e32 v118, v104, v104
	v_fmac_f32_e32 v120, v116, v116
	v_add_f32_e32 v98, v98, v99
	v_add_f32_e32 v99, v109, v111
	v_fmac_f32_e32 v119, v106, v106
	v_fmac_f32_e32 v121, v114, v114
	v_add_f32_e32 v98, v118, v98
	v_add_f32_e32 v99, v120, v99
	v_add_f32_e32 v98, v119, v98
	v_add_f32_e32 v99, v121, v99
	v_add_f32_e32 v108, v98, v99
	ds_bpermute_b32 v109, v156, v108
	v_cvt_pk_bf16_f32 v98, v104, v105
	v_cvt_pk_bf16_f32 v99, v106, v107
	global_store_dwordx4 v[122:123], v[96:99], off
	s_waitcnt lgkmcnt(0)
	s_nop 0
	v_add_f32_e32 v96, v108, v109
	ds_bpermute_b32 v97, v155, v96
	v_cvt_pk_bf16_f32 v98, v100, v101
	v_cvt_pk_bf16_f32 v99, v102, v103
	v_cvt_pk_bf16_f32 v100, v116, v117
	v_cvt_pk_bf16_f32 v101, v114, v115
	global_store_dwordx4 v[122:123], v[98:101], off offset:256
	s_and_saveexec_b64 s[4:5], s[6:7]
	s_cbranch_execz .LBB0_1694
	s_waitcnt lgkmcnt(0)
	v_add_f32_e32 v98, v96, v97
	v_lshlrev_b64 v[96:97], 6, v[112:113]
	v_lshl_add_u64 v[96:97], s[62:63], 0, v[96:97]
	v_lshl_add_u64 v[96:97], s[54:55], 2, v[96:97]
	s_lshl_b32 s20, s59, 2
	v_lshl_add_u64 v[96:97], v[96:97], 0, s[20:21]
	global_store_dword v[96:97], v98, off
.LBB0_1694:
	s_or_b64 exec, exec, s[4:5]
	v_or_b32_e32 v96, 32, v146
	s_waitcnt lgkmcnt(0)
	v_ashrrev_i32_e32 v97, 31, v96
	v_lshlrev_b64 v[98:99], 11, v[96:97]
	v_lshl_add_u64 v[98:99], s[48:49], 0, v[98:99]
	v_lshl_add_u64 v[106:107], v[144:145], 1, v[98:99]
	s_nop 1
	v_mov_b64_e32 v[98:99], v[192:193]
	v_mov_b64_e32 v[100:101], v[194:195]
	s_nop 1
	v_mov_b64_e32 v[102:103], v[196:197]
	v_mov_b64_e32 v[104:105], v[198:199]
	s_nop 1
	v_lshlrev_b32_e32 v108, 16, v98
	v_and_b32_e32 v109, 0xffff0000, v98
	v_lshlrev_b32_e32 v98, 16, v99
	v_and_b32_e32 v99, 0xffff0000, v99
	s_nop 1
	v_lshlrev_b32_e32 v112, 16, v102
	v_and_b32_e32 v113, 0xffff0000, v102
	v_lshlrev_b32_e32 v102, 16, v103
	v_and_b32_e32 v103, 0xffff0000, v103
	v_lshlrev_b32_e32 v110, 16, v100
	v_and_b32_e32 v111, 0xffff0000, v100
	v_lshlrev_b32_e32 v100, 16, v101
	v_and_b32_e32 v101, 0xffff0000, v101
	v_lshlrev_b32_e32 v114, 16, v104
	v_and_b32_e32 v115, 0xffff0000, v104
	v_lshlrev_b32_e32 v104, 16, v105
	v_and_b32_e32 v105, 0xffff0000, v105
	v_pk_add_f32 v[94:95], v[94:95], v[98:99]
	v_pk_add_f32 v[92:93], v[92:93], v[108:109]
	v_pk_add_f32 v[86:87], v[86:87], v[102:103]
	v_pk_add_f32 v[84:85], v[84:85], v[112:113]
	v_pk_add_f32 v[90:91], v[90:91], v[100:101]
	v_pk_add_f32 v[88:89], v[88:89], v[110:111]
	v_pk_add_f32 v[98:99], v[82:83], v[104:105]
	v_pk_add_f32 v[100:101], v[80:81], v[114:115]
	v_mul_f32_e32 v82, v93, v93
	v_mul_f32_e32 v83, v95, v95
	v_cvt_pk_bf16_f32 v80, v92, v93
	v_cvt_pk_bf16_f32 v81, v94, v95
	v_mul_f32_e32 v93, v85, v85
	v_mul_f32_e32 v95, v87, v87
	v_mul_f32_e32 v102, v89, v89
	v_mul_f32_e32 v104, v101, v101
	v_fmac_f32_e32 v82, v92, v92
	v_fmac_f32_e32 v83, v94, v94
	v_fmac_f32_e32 v93, v84, v84
	v_fmac_f32_e32 v95, v86, v86
	v_mul_f32_e32 v103, v91, v91
	v_mul_f32_e32 v105, v99, v99
	v_fmac_f32_e32 v102, v88, v88
	v_fmac_f32_e32 v104, v100, v100
	v_add_f32_e32 v82, v82, v83
	v_add_f32_e32 v83, v93, v95
	v_fmac_f32_e32 v103, v90, v90
	v_fmac_f32_e32 v105, v98, v98
	v_add_f32_e32 v82, v102, v82
	v_add_f32_e32 v83, v104, v83
	v_add_f32_e32 v82, v103, v82
	v_add_f32_e32 v83, v105, v83
	v_add_f32_e32 v92, v82, v83
	ds_bpermute_b32 v93, v156, v92
	v_cvt_pk_bf16_f32 v82, v88, v89
	v_cvt_pk_bf16_f32 v83, v90, v91
	global_store_dwordx4 v[106:107], v[80:83], off
	s_waitcnt lgkmcnt(0)
	s_nop 0
	v_add_f32_e32 v80, v92, v93
	ds_bpermute_b32 v81, v155, v80
	v_cvt_pk_bf16_f32 v82, v84, v85
	v_cvt_pk_bf16_f32 v83, v86, v87
	v_cvt_pk_bf16_f32 v84, v100, v101
	v_cvt_pk_bf16_f32 v85, v98, v99
	global_store_dwordx4 v[106:107], v[82:85], off offset:256
	s_and_saveexec_b64 s[4:5], s[6:7]
	s_cbranch_execz .LBB0_1696
	s_waitcnt lgkmcnt(0)
	v_add_f32_e32 v82, v80, v81
	v_lshlrev_b64 v[80:81], 6, v[96:97]
	v_lshl_add_u64 v[80:81], s[62:63], 0, v[80:81]
	v_lshl_add_u64 v[80:81], s[54:55], 2, v[80:81]
	s_lshl_b32 s20, s59, 2
	v_lshl_add_u64 v[80:81], v[80:81], 0, s[20:21]
	global_store_dword v[80:81], v82, off
.LBB0_1696:
	s_or_b64 exec, exec, s[4:5]
	v_or_b32_e32 v80, 48, v146
	s_waitcnt lgkmcnt(0)
	v_ashrrev_i32_e32 v81, 31, v80
	v_lshlrev_b64 v[82:83], 11, v[80:81]
	v_lshl_add_u64 v[82:83], s[48:49], 0, v[82:83]
	v_lshl_add_u64 v[90:91], v[144:145], 1, v[82:83]
	s_nop 1
	v_mov_b64_e32 v[82:83], v[204:205]
	v_mov_b64_e32 v[84:85], v[206:207]
	s_nop 1
	v_mov_b64_e32 v[86:87], v[208:209]
	v_mov_b64_e32 v[88:89], v[210:211]
	s_nop 1
	v_lshlrev_b32_e32 v92, 16, v82
	v_and_b32_e32 v93, 0xffff0000, v82
	v_lshlrev_b32_e32 v82, 16, v83
	v_and_b32_e32 v83, 0xffff0000, v83
	s_nop 1
	v_lshlrev_b32_e32 v96, 16, v86
	v_and_b32_e32 v97, 0xffff0000, v86
	v_lshlrev_b32_e32 v86, 16, v87
	v_and_b32_e32 v87, 0xffff0000, v87
	v_lshlrev_b32_e32 v94, 16, v84
	v_and_b32_e32 v95, 0xffff0000, v84
	v_lshlrev_b32_e32 v84, 16, v85
	v_and_b32_e32 v85, 0xffff0000, v85
	v_lshlrev_b32_e32 v98, 16, v88
	v_and_b32_e32 v99, 0xffff0000, v88
	v_lshlrev_b32_e32 v88, 16, v89
	v_and_b32_e32 v89, 0xffff0000, v89
	v_pk_add_f32 v[78:79], v[78:79], v[82:83]
	v_pk_add_f32 v[76:77], v[76:77], v[92:93]
	v_pk_add_f32 v[70:71], v[70:71], v[86:87]
	v_pk_add_f32 v[68:69], v[68:69], v[96:97]
	v_pk_add_f32 v[74:75], v[74:75], v[84:85]
	v_pk_add_f32 v[72:73], v[72:73], v[94:95]
	v_pk_add_f32 v[82:83], v[66:67], v[88:89]
	v_pk_add_f32 v[84:85], v[64:65], v[98:99]
	v_mul_f32_e32 v66, v77, v77
	v_mul_f32_e32 v67, v79, v79
	v_cvt_pk_bf16_f32 v64, v76, v77
	v_cvt_pk_bf16_f32 v65, v78, v79
	v_mul_f32_e32 v77, v69, v69
	v_mul_f32_e32 v79, v71, v71
	v_mul_f32_e32 v86, v73, v73
	v_mul_f32_e32 v88, v85, v85
	v_fmac_f32_e32 v66, v76, v76
	v_fmac_f32_e32 v67, v78, v78
	v_fmac_f32_e32 v77, v68, v68
	v_fmac_f32_e32 v79, v70, v70
	v_mul_f32_e32 v87, v75, v75
	v_mul_f32_e32 v89, v83, v83
	v_fmac_f32_e32 v86, v72, v72
	v_fmac_f32_e32 v88, v84, v84
	v_add_f32_e32 v66, v66, v67
	v_add_f32_e32 v67, v77, v79
	v_fmac_f32_e32 v87, v74, v74
	v_fmac_f32_e32 v89, v82, v82
	v_add_f32_e32 v66, v86, v66
	v_add_f32_e32 v67, v88, v67
	v_add_f32_e32 v66, v87, v66
	v_add_f32_e32 v67, v89, v67
	v_add_f32_e32 v76, v66, v67
	ds_bpermute_b32 v77, v156, v76
	v_cvt_pk_bf16_f32 v66, v72, v73
	v_cvt_pk_bf16_f32 v67, v74, v75
	global_store_dwordx4 v[90:91], v[64:67], off
	s_waitcnt lgkmcnt(0)
	s_nop 0
	v_add_f32_e32 v64, v76, v77
	ds_bpermute_b32 v65, v155, v64
	v_cvt_pk_bf16_f32 v66, v68, v69
	v_cvt_pk_bf16_f32 v67, v70, v71
	v_cvt_pk_bf16_f32 v68, v84, v85
	v_cvt_pk_bf16_f32 v69, v82, v83
	global_store_dwordx4 v[90:91], v[66:69], off offset:256
	s_and_saveexec_b64 s[4:5], s[6:7]
	s_cbranch_execz .LBB0_1698
	s_waitcnt lgkmcnt(0)
	v_add_f32_e32 v66, v64, v65
	v_lshlrev_b64 v[64:65], 6, v[80:81]
	v_lshl_add_u64 v[64:65], s[62:63], 0, v[64:65]
	v_lshl_add_u64 v[64:65], s[54:55], 2, v[64:65]
	s_lshl_b32 s20, s59, 2
	v_lshl_add_u64 v[64:65], v[64:65], 0, s[20:21]
	global_store_dword v[64:65], v66, off
.LBB0_1698:
	s_or_b64 exec, exec, s[4:5]
	v_add_u32_e32 v64, 0x80, v146
	s_waitcnt lgkmcnt(0)
	v_ashrrev_i32_e32 v65, 31, v64
	v_lshlrev_b64 v[66:67], 11, v[64:65]
	v_lshl_add_u64 v[66:67], s[48:49], 0, v[66:67]
	v_lshl_add_u64 v[74:75], v[144:145], 1, v[66:67]
	v_add_co_u32_e32 v212, vcc, 0x40000, v214
	s_nop 1
	v_addc_co_u32_e32 v213, vcc, 0, v215, vcc
	global_load_dwordx4 v[176:179], v[212:213], off
	v_add_co_u32_e32 v212, vcc, 0x40100, v214
	s_nop 1
	v_addc_co_u32_e32 v213, vcc, 0, v215, vcc
	global_load_dwordx4 v[180:183], v[212:213], off
	v_add_co_u32_e32 v212, vcc, 0x48000, v214
	s_nop 1
	v_addc_co_u32_e32 v213, vcc, 0, v215, vcc
	global_load_dwordx4 v[184:187], v[212:213], off
	v_add_co_u32_e32 v212, vcc, 0x48100, v214
	s_nop 1
	v_addc_co_u32_e32 v213, vcc, 0, v215, vcc
	global_load_dwordx4 v[188:191], v[212:213], off
	v_add_co_u32_e32 v212, vcc, 0x50000, v214
	s_nop 1
	v_addc_co_u32_e32 v213, vcc, 0, v215, vcc
	global_load_dwordx4 v[192:195], v[212:213], off
	v_add_co_u32_e32 v212, vcc, 0x50100, v214
	s_nop 1
	v_addc_co_u32_e32 v213, vcc, 0, v215, vcc
	global_load_dwordx4 v[196:199], v[212:213], off
	v_add_co_u32_e32 v212, vcc, 0x58000, v214
	s_nop 1
	v_addc_co_u32_e32 v213, vcc, 0, v215, vcc
	global_load_dwordx4 v[204:207], v[212:213], off
	v_add_co_u32_e32 v212, vcc, 0x58100, v214
	s_nop 1
	v_addc_co_u32_e32 v213, vcc, 0, v215, vcc
	global_load_dwordx4 v[208:211], v[212:213], off
	s_waitcnt vmcnt(0)
	s_nop 1
	v_mov_b64_e32 v[66:67], v[176:177]
	v_mov_b64_e32 v[68:69], v[178:179]
	s_nop 1
	v_mov_b64_e32 v[70:71], v[180:181]
	v_mov_b64_e32 v[72:73], v[182:183]
	s_nop 1
	v_lshlrev_b32_e32 v76, 16, v66
	v_and_b32_e32 v77, 0xffff0000, v66
	v_lshlrev_b32_e32 v66, 16, v67
	v_and_b32_e32 v67, 0xffff0000, v67
	s_nop 1
	v_lshlrev_b32_e32 v80, 16, v70
	v_and_b32_e32 v81, 0xffff0000, v70
	v_lshlrev_b32_e32 v70, 16, v71
	v_and_b32_e32 v71, 0xffff0000, v71
	v_lshlrev_b32_e32 v78, 16, v68
	v_and_b32_e32 v79, 0xffff0000, v68
	v_lshlrev_b32_e32 v68, 16, v69
	v_and_b32_e32 v69, 0xffff0000, v69
	v_lshlrev_b32_e32 v82, 16, v72
	v_and_b32_e32 v83, 0xffff0000, v72
	v_lshlrev_b32_e32 v72, 16, v73
	v_and_b32_e32 v73, 0xffff0000, v73
	v_pk_add_f32 v[62:63], v[62:63], v[66:67]
	v_pk_add_f32 v[60:61], v[60:61], v[76:77]
	v_pk_add_f32 v[54:55], v[54:55], v[70:71]
	v_pk_add_f32 v[52:53], v[52:53], v[80:81]
	v_pk_add_f32 v[58:59], v[58:59], v[68:69]
	v_pk_add_f32 v[56:57], v[56:57], v[78:79]
	v_pk_add_f32 v[66:67], v[50:51], v[72:73]
	v_pk_add_f32 v[68:69], v[48:49], v[82:83]
	v_mul_f32_e32 v50, v61, v61
	v_mul_f32_e32 v51, v63, v63
	v_cvt_pk_bf16_f32 v48, v60, v61
	v_cvt_pk_bf16_f32 v49, v62, v63
	v_mul_f32_e32 v61, v53, v53
	v_mul_f32_e32 v63, v55, v55
	v_mul_f32_e32 v70, v57, v57
	v_mul_f32_e32 v72, v69, v69
	v_fmac_f32_e32 v50, v60, v60
	v_fmac_f32_e32 v51, v62, v62
	v_fmac_f32_e32 v61, v52, v52
	v_fmac_f32_e32 v63, v54, v54
	v_mul_f32_e32 v71, v59, v59
	v_mul_f32_e32 v73, v67, v67
	v_fmac_f32_e32 v70, v56, v56
	v_fmac_f32_e32 v72, v68, v68
	v_add_f32_e32 v50, v50, v51
	v_add_f32_e32 v51, v61, v63
	v_fmac_f32_e32 v71, v58, v58
	v_fmac_f32_e32 v73, v66, v66
	v_add_f32_e32 v50, v70, v50
	v_add_f32_e32 v51, v72, v51
	v_add_f32_e32 v50, v71, v50
	v_add_f32_e32 v51, v73, v51
	v_add_f32_e32 v60, v50, v51
	ds_bpermute_b32 v61, v156, v60
	v_cvt_pk_bf16_f32 v50, v56, v57
	v_cvt_pk_bf16_f32 v51, v58, v59
	global_store_dwordx4 v[74:75], v[48:51], off
	s_waitcnt lgkmcnt(0)
	s_nop 0
	v_add_f32_e32 v48, v60, v61
	ds_bpermute_b32 v49, v155, v48
	v_cvt_pk_bf16_f32 v50, v52, v53
	v_cvt_pk_bf16_f32 v51, v54, v55
	v_cvt_pk_bf16_f32 v52, v68, v69
	v_cvt_pk_bf16_f32 v53, v66, v67
	global_store_dwordx4 v[74:75], v[50:53], off offset:256
	s_and_saveexec_b64 s[4:5], s[6:7]
	s_cbranch_execz .LBB0_1700
	s_waitcnt lgkmcnt(0)
	v_add_f32_e32 v50, v48, v49
	v_lshlrev_b64 v[48:49], 6, v[64:65]
	v_lshl_add_u64 v[48:49], s[62:63], 0, v[48:49]
	v_lshl_add_u64 v[48:49], s[54:55], 2, v[48:49]
	s_lshl_b32 s20, s59, 2
	v_lshl_add_u64 v[48:49], v[48:49], 0, s[20:21]
	global_store_dword v[48:49], v50, off
.LBB0_1700:
	s_or_b64 exec, exec, s[4:5]
	v_add_u32_e32 v48, 0x90, v146
	s_waitcnt lgkmcnt(0)
	v_ashrrev_i32_e32 v49, 31, v48
	v_lshlrev_b64 v[50:51], 11, v[48:49]
	v_lshl_add_u64 v[50:51], s[48:49], 0, v[50:51]
	v_lshl_add_u64 v[58:59], v[144:145], 1, v[50:51]
	s_nop 1
	v_mov_b64_e32 v[50:51], v[184:185]
	v_mov_b64_e32 v[52:53], v[186:187]
	s_nop 1
	v_mov_b64_e32 v[54:55], v[188:189]
	v_mov_b64_e32 v[56:57], v[190:191]
	s_nop 1
	v_lshlrev_b32_e32 v60, 16, v50
	v_and_b32_e32 v61, 0xffff0000, v50
	v_lshlrev_b32_e32 v50, 16, v51
	v_and_b32_e32 v51, 0xffff0000, v51
	s_nop 1
	v_lshlrev_b32_e32 v64, 16, v54
	v_and_b32_e32 v65, 0xffff0000, v54
	v_lshlrev_b32_e32 v54, 16, v55
	v_and_b32_e32 v55, 0xffff0000, v55
	v_lshlrev_b32_e32 v62, 16, v52
	v_and_b32_e32 v63, 0xffff0000, v52
	v_lshlrev_b32_e32 v52, 16, v53
	v_and_b32_e32 v53, 0xffff0000, v53
	v_lshlrev_b32_e32 v66, 16, v56
	v_and_b32_e32 v67, 0xffff0000, v56
	v_lshlrev_b32_e32 v56, 16, v57
	v_and_b32_e32 v57, 0xffff0000, v57
	v_pk_add_f32 v[46:47], v[46:47], v[50:51]
	v_pk_add_f32 v[44:45], v[44:45], v[60:61]
	v_pk_add_f32 v[38:39], v[38:39], v[54:55]
	v_pk_add_f32 v[36:37], v[36:37], v[64:65]
	v_pk_add_f32 v[42:43], v[42:43], v[52:53]
	v_pk_add_f32 v[40:41], v[40:41], v[62:63]
	v_pk_add_f32 v[50:51], v[34:35], v[56:57]
	v_pk_add_f32 v[52:53], v[32:33], v[66:67]
	v_mul_f32_e32 v34, v45, v45
	v_mul_f32_e32 v35, v47, v47
	v_cvt_pk_bf16_f32 v32, v44, v45
	v_cvt_pk_bf16_f32 v33, v46, v47
	v_mul_f32_e32 v45, v37, v37
	v_mul_f32_e32 v47, v39, v39
	v_mul_f32_e32 v54, v41, v41
	v_mul_f32_e32 v56, v53, v53
	v_fmac_f32_e32 v34, v44, v44
	v_fmac_f32_e32 v35, v46, v46
	v_fmac_f32_e32 v45, v36, v36
	v_fmac_f32_e32 v47, v38, v38
	v_mul_f32_e32 v55, v43, v43
	v_mul_f32_e32 v57, v51, v51
	v_fmac_f32_e32 v54, v40, v40
	v_fmac_f32_e32 v56, v52, v52
	v_add_f32_e32 v34, v34, v35
	v_add_f32_e32 v35, v45, v47
	v_fmac_f32_e32 v55, v42, v42
	v_fmac_f32_e32 v57, v50, v50
	v_add_f32_e32 v34, v54, v34
	v_add_f32_e32 v35, v56, v35
	v_add_f32_e32 v34, v55, v34
	v_add_f32_e32 v35, v57, v35
	v_add_f32_e32 v44, v34, v35
	ds_bpermute_b32 v45, v156, v44
	v_cvt_pk_bf16_f32 v34, v40, v41
	v_cvt_pk_bf16_f32 v35, v42, v43
	global_store_dwordx4 v[58:59], v[32:35], off
	s_waitcnt lgkmcnt(0)
	s_nop 0
	v_add_f32_e32 v32, v44, v45
	ds_bpermute_b32 v33, v155, v32
	v_cvt_pk_bf16_f32 v34, v36, v37
	v_cvt_pk_bf16_f32 v35, v38, v39
	v_cvt_pk_bf16_f32 v36, v52, v53
	v_cvt_pk_bf16_f32 v37, v50, v51
	global_store_dwordx4 v[58:59], v[34:37], off offset:256
	s_and_saveexec_b64 s[4:5], s[6:7]
	s_cbranch_execz .LBB0_1702
	s_waitcnt lgkmcnt(0)
	v_add_f32_e32 v34, v32, v33
	v_lshlrev_b64 v[32:33], 6, v[48:49]
	v_lshl_add_u64 v[32:33], s[62:63], 0, v[32:33]
	v_lshl_add_u64 v[32:33], s[54:55], 2, v[32:33]
	s_lshl_b32 s20, s59, 2
	v_lshl_add_u64 v[32:33], v[32:33], 0, s[20:21]
	global_store_dword v[32:33], v34, off
.LBB0_1702:
	s_or_b64 exec, exec, s[4:5]
	v_add_u32_e32 v32, 0xa0, v146
	s_waitcnt lgkmcnt(0)
	v_ashrrev_i32_e32 v33, 31, v32
	v_lshlrev_b64 v[34:35], 11, v[32:33]
	v_lshl_add_u64 v[34:35], s[48:49], 0, v[34:35]
	v_lshl_add_u64 v[42:43], v[144:145], 1, v[34:35]
	s_nop 1
	v_mov_b64_e32 v[34:35], v[192:193]
	v_mov_b64_e32 v[36:37], v[194:195]
	s_nop 1
	v_mov_b64_e32 v[38:39], v[196:197]
	v_mov_b64_e32 v[40:41], v[198:199]
	s_nop 1
	v_lshlrev_b32_e32 v44, 16, v34
	v_and_b32_e32 v45, 0xffff0000, v34
	v_lshlrev_b32_e32 v34, 16, v35
	v_and_b32_e32 v35, 0xffff0000, v35
	s_nop 1
	v_lshlrev_b32_e32 v48, 16, v38
	v_and_b32_e32 v49, 0xffff0000, v38
	v_lshlrev_b32_e32 v38, 16, v39
	v_and_b32_e32 v39, 0xffff0000, v39
	v_lshlrev_b32_e32 v46, 16, v36
	v_and_b32_e32 v47, 0xffff0000, v36
	v_lshlrev_b32_e32 v36, 16, v37
	v_and_b32_e32 v37, 0xffff0000, v37
	v_lshlrev_b32_e32 v50, 16, v40
	v_and_b32_e32 v51, 0xffff0000, v40
	v_lshlrev_b32_e32 v40, 16, v41
	v_and_b32_e32 v41, 0xffff0000, v41
	v_pk_add_f32 v[30:31], v[30:31], v[34:35]
	v_pk_add_f32 v[28:29], v[28:29], v[44:45]
	v_pk_add_f32 v[22:23], v[22:23], v[38:39]
	v_pk_add_f32 v[20:21], v[20:21], v[48:49]
	v_pk_add_f32 v[26:27], v[26:27], v[36:37]
	v_pk_add_f32 v[24:25], v[24:25], v[46:47]
	v_pk_add_f32 v[34:35], v[18:19], v[40:41]
	v_pk_add_f32 v[36:37], v[16:17], v[50:51]
	v_mul_f32_e32 v18, v29, v29
	v_mul_f32_e32 v19, v31, v31
	v_cvt_pk_bf16_f32 v16, v28, v29
	v_cvt_pk_bf16_f32 v17, v30, v31
	v_mul_f32_e32 v29, v21, v21
	v_mul_f32_e32 v31, v23, v23
	v_mul_f32_e32 v38, v25, v25
	v_mul_f32_e32 v40, v37, v37
	v_fmac_f32_e32 v18, v28, v28
	v_fmac_f32_e32 v19, v30, v30
	v_fmac_f32_e32 v29, v20, v20
	v_fmac_f32_e32 v31, v22, v22
	v_mul_f32_e32 v39, v27, v27
	v_mul_f32_e32 v41, v35, v35
	v_fmac_f32_e32 v38, v24, v24
	v_fmac_f32_e32 v40, v36, v36
	v_add_f32_e32 v18, v18, v19
	v_add_f32_e32 v19, v29, v31
	v_fmac_f32_e32 v39, v26, v26
	v_fmac_f32_e32 v41, v34, v34
	v_add_f32_e32 v18, v38, v18
	v_add_f32_e32 v19, v40, v19
	v_add_f32_e32 v18, v39, v18
	v_add_f32_e32 v19, v41, v19
	v_add_f32_e32 v28, v18, v19
	ds_bpermute_b32 v29, v156, v28
	v_cvt_pk_bf16_f32 v18, v24, v25
	v_cvt_pk_bf16_f32 v19, v26, v27
	global_store_dwordx4 v[42:43], v[16:19], off
	s_waitcnt lgkmcnt(0)
	s_nop 0
	v_add_f32_e32 v16, v28, v29
	ds_bpermute_b32 v17, v155, v16
	v_cvt_pk_bf16_f32 v18, v20, v21
	v_cvt_pk_bf16_f32 v19, v22, v23
	v_cvt_pk_bf16_f32 v20, v36, v37
	v_cvt_pk_bf16_f32 v21, v34, v35
	global_store_dwordx4 v[42:43], v[18:21], off offset:256
	s_and_saveexec_b64 s[4:5], s[6:7]
	s_cbranch_execz .LBB0_1704
	s_waitcnt lgkmcnt(0)
	v_add_f32_e32 v18, v16, v17
	v_lshlrev_b64 v[16:17], 6, v[32:33]
	v_lshl_add_u64 v[16:17], s[62:63], 0, v[16:17]
	v_lshl_add_u64 v[16:17], s[54:55], 2, v[16:17]
	s_lshl_b32 s20, s59, 2
	v_lshl_add_u64 v[16:17], v[16:17], 0, s[20:21]
	global_store_dword v[16:17], v18, off
.LBB0_1704:
	s_or_b64 exec, exec, s[4:5]
	v_add_u32_e32 v16, 0xb0, v146
	s_waitcnt lgkmcnt(0)
	v_ashrrev_i32_e32 v17, 31, v16
	v_lshlrev_b64 v[18:19], 11, v[16:17]
	v_lshl_add_u64 v[18:19], s[48:49], 0, v[18:19]
	v_lshl_add_u64 v[26:27], v[144:145], 1, v[18:19]
	s_nop 1
	v_mov_b64_e32 v[18:19], v[204:205]
	v_mov_b64_e32 v[20:21], v[206:207]
	s_nop 1
	v_mov_b64_e32 v[22:23], v[208:209]
	v_mov_b64_e32 v[24:25], v[210:211]
	s_nop 1
	v_lshlrev_b32_e32 v28, 16, v18
	v_and_b32_e32 v29, 0xffff0000, v18
	v_lshlrev_b32_e32 v18, 16, v19
	v_and_b32_e32 v19, 0xffff0000, v19
	s_nop 1
	v_lshlrev_b32_e32 v32, 16, v22
	v_and_b32_e32 v33, 0xffff0000, v22
	v_lshlrev_b32_e32 v22, 16, v23
	v_and_b32_e32 v23, 0xffff0000, v23
	v_lshlrev_b32_e32 v30, 16, v20
	v_and_b32_e32 v31, 0xffff0000, v20
	v_lshlrev_b32_e32 v20, 16, v21
	v_and_b32_e32 v21, 0xffff0000, v21
	v_lshlrev_b32_e32 v34, 16, v24
	v_and_b32_e32 v35, 0xffff0000, v24
	v_lshlrev_b32_e32 v24, 16, v25
	v_and_b32_e32 v25, 0xffff0000, v25
	v_pk_add_f32 v[14:15], v[14:15], v[18:19]
	v_pk_add_f32 v[12:13], v[12:13], v[28:29]
	v_pk_add_f32 v[6:7], v[6:7], v[22:23]
	v_pk_add_f32 v[4:5], v[4:5], v[32:33]
	v_pk_add_f32 v[10:11], v[10:11], v[20:21]
	v_pk_add_f32 v[8:9], v[8:9], v[30:31]
	v_pk_add_f32 v[18:19], v[2:3], v[24:25]
	v_pk_add_f32 v[20:21], v[0:1], v[34:35]
	v_mul_f32_e32 v2, v13, v13
	v_mul_f32_e32 v3, v15, v15
	v_cvt_pk_bf16_f32 v0, v12, v13
	v_cvt_pk_bf16_f32 v1, v14, v15
	v_mul_f32_e32 v13, v5, v5
	v_mul_f32_e32 v15, v7, v7
	v_mul_f32_e32 v22, v9, v9
	v_mul_f32_e32 v24, v21, v21
	v_fmac_f32_e32 v2, v12, v12
	v_fmac_f32_e32 v3, v14, v14
	v_fmac_f32_e32 v13, v4, v4
	v_fmac_f32_e32 v15, v6, v6
	v_mul_f32_e32 v23, v11, v11
	v_mul_f32_e32 v25, v19, v19
	v_fmac_f32_e32 v22, v8, v8
	v_fmac_f32_e32 v24, v20, v20
	v_add_f32_e32 v2, v2, v3
	v_add_f32_e32 v3, v13, v15
	v_fmac_f32_e32 v23, v10, v10
	v_fmac_f32_e32 v25, v18, v18
	v_add_f32_e32 v2, v22, v2
	v_add_f32_e32 v3, v24, v3
	v_add_f32_e32 v2, v23, v2
	v_add_f32_e32 v3, v25, v3
	v_add_f32_e32 v12, v2, v3
	ds_bpermute_b32 v13, v156, v12
	v_cvt_pk_bf16_f32 v2, v8, v9
	v_cvt_pk_bf16_f32 v3, v10, v11
	global_store_dwordx4 v[26:27], v[0:3], off
	s_waitcnt lgkmcnt(0)
	s_nop 0
	v_add_f32_e32 v0, v12, v13
	ds_bpermute_b32 v1, v155, v0
	v_cvt_pk_bf16_f32 v2, v4, v5
	v_cvt_pk_bf16_f32 v3, v6, v7
	v_cvt_pk_bf16_f32 v4, v20, v21
	v_cvt_pk_bf16_f32 v5, v18, v19
	global_store_dwordx4 v[26:27], v[2:5], off offset:256
	s_and_saveexec_b64 s[4:5], s[6:7]
	s_cbranch_execz .LBB0_1706
	s_waitcnt lgkmcnt(0)
	v_add_f32_e32 v2, v0, v1
	v_lshlrev_b64 v[0:1], 6, v[16:17]
	v_lshl_add_u64 v[0:1], s[62:63], 0, v[0:1]
	v_lshl_add_u64 v[0:1], s[54:55], 2, v[0:1]
	s_lshl_b32 s20, s59, 2
	v_lshl_add_u64 v[0:1], v[0:1], 0, s[20:21]
	global_store_dword v[0:1], v2, off

.LBB0_1912:
	v_lshl_add_u32 v146, s54, 8, v148
	v_ashrrev_i32_e32 v147, 31, v146
	v_lshl_or_b32 v144, s20, 8, v150
	v_lshlrev_b64 v[156:157], 11, v[146:147]
	v_ashrrev_i32_e32 v145, 31, v144
	v_lshl_add_u64 v[156:157], s[48:49], 0, v[156:157]
	v_lshl_add_u64 v[166:167], v[144:145], 1, v[156:157]
	v_mov_b64_e32 v[214:215], v[166:167]
	global_load_dwordx4 v[176:179], v[166:167], off
	v_add_co_u32_e32 v212, vcc, 0x100, v166
	s_nop 1
	v_addc_co_u32_e32 v213, vcc, 0, v167, vcc
	global_load_dwordx4 v[180:183], v[212:213], off
	v_add_co_u32_e32 v212, vcc, 0x8000, v166
	s_nop 1
	v_addc_co_u32_e32 v213, vcc, 0, v167, vcc
	global_load_dwordx4 v[184:187], v[212:213], off
	v_add_co_u32_e32 v212, vcc, 0x8100, v166
	s_nop 1
	v_addc_co_u32_e32 v213, vcc, 0, v167, vcc
	global_load_dwordx4 v[188:191], v[212:213], off
	v_add_co_u32_e32 v212, vcc, 0x10000, v166
	s_nop 1
	v_addc_co_u32_e32 v213, vcc, 0, v167, vcc
	global_load_dwordx4 v[192:195], v[212:213], off
	v_add_co_u32_e32 v212, vcc, 0x10100, v166
	s_nop 1
	v_addc_co_u32_e32 v213, vcc, 0, v167, vcc
	global_load_dwordx4 v[196:199], v[212:213], off
	v_add_co_u32_e32 v212, vcc, 0x18000, v166
	s_nop 1
	v_addc_co_u32_e32 v213, vcc, 0, v167, vcc
	global_load_dwordx4 v[204:207], v[212:213], off
	v_add_co_u32_e32 v212, vcc, 0x18100, v166
	s_nop 1
	v_addc_co_u32_e32 v213, vcc, 0, v167, vcc
	global_load_dwordx4 v[208:211], v[212:213], off
	s_waitcnt vmcnt(0)
	s_nop 1
	v_mov_b64_e32 v[158:159], v[176:177]
	v_mov_b64_e32 v[160:161], v[178:179]
	s_nop 1
	v_mov_b64_e32 v[162:163], v[180:181]
	v_mov_b64_e32 v[164:165], v[182:183]
	v_and_b32_e32 v156, 64, v154
	v_xor_b32_e32 v155, 16, v154
	v_add_u32_e32 v156, 64, v156
	v_xor_b32_e32 v157, 32, v154
	v_cmp_lt_i32_e32 vcc, v155, v156
	s_lshl_b32 s54, s20, 2
	s_ashr_i32 s55, s54, 31
	v_cndmask_b32_e32 v155, v154, v155, vcc
	v_cmp_lt_i32_e32 vcc, v157, v156
	v_lshlrev_b32_e32 v156, 2, v155
	s_nop 1
	v_lshlrev_b32_e32 v168, 16, v158
	v_and_b32_e32 v169, 0xffff0000, v158
	v_lshlrev_b32_e32 v158, 16, v159
	v_and_b32_e32 v159, 0xffff0000, v159
	v_lshlrev_b32_e32 v172, 16, v162
	v_and_b32_e32 v173, 0xffff0000, v162
	v_lshlrev_b32_e32 v162, 16, v163
	v_and_b32_e32 v163, 0xffff0000, v163
	v_lshlrev_b32_e32 v170, 16, v160
	v_and_b32_e32 v171, 0xffff0000, v160
	v_lshlrev_b32_e32 v160, 16, v161
	v_and_b32_e32 v161, 0xffff0000, v161
	v_lshlrev_b32_e32 v174, 16, v164
	v_and_b32_e32 v175, 0xffff0000, v164
	v_lshlrev_b32_e32 v164, 16, v165
	v_and_b32_e32 v165, 0xffff0000, v165
	v_pk_add_f32 v[126:127], v[126:127], v[158:159]
	v_pk_add_f32 v[124:125], v[124:125], v[168:169]
	v_pk_add_f32 v[118:119], v[118:119], v[162:163]
	v_pk_add_f32 v[116:117], v[116:117], v[172:173]
	v_cndmask_b32_e32 v157, v154, v157, vcc
	v_pk_add_f32 v[122:123], v[122:123], v[160:161]
	v_pk_add_f32 v[120:121], v[120:121], v[170:171]
	v_pk_add_f32 v[158:159], v[114:115], v[164:165]
	v_pk_add_f32 v[160:161], v[112:113], v[174:175]
	v_mul_f32_e32 v114, v125, v125
	v_mul_f32_e32 v115, v127, v127
	v_cvt_pk_bf16_f32 v112, v124, v125
	v_cvt_pk_bf16_f32 v113, v126, v127
	v_mul_f32_e32 v125, v117, v117
	v_mul_f32_e32 v127, v119, v119
	v_lshlrev_b32_e32 v155, 2, v157
	v_mul_f32_e32 v157, v121, v121
	v_mul_f32_e32 v163, v161, v161
	v_fmac_f32_e32 v114, v124, v124
	v_fmac_f32_e32 v115, v126, v126
	v_fmac_f32_e32 v125, v116, v116
	v_fmac_f32_e32 v127, v118, v118
	v_mul_f32_e32 v162, v123, v123
	v_mul_f32_e32 v164, v159, v159
	v_fmac_f32_e32 v157, v120, v120
	v_fmac_f32_e32 v163, v160, v160
	v_add_f32_e32 v114, v114, v115
	v_add_f32_e32 v115, v125, v127
	v_fmac_f32_e32 v162, v122, v122
	v_fmac_f32_e32 v164, v158, v158
	v_add_f32_e32 v114, v157, v114
	v_add_f32_e32 v115, v163, v115
	v_add_f32_e32 v114, v162, v114
	v_add_f32_e32 v115, v164, v115
	v_add_f32_e32 v124, v114, v115
	ds_bpermute_b32 v125, v156, v124
	v_cvt_pk_bf16_f32 v114, v120, v121
	v_cvt_pk_bf16_f32 v115, v122, v123
	global_store_dwordx4 v[166:167], v[112:115], off
	s_waitcnt lgkmcnt(0)
	s_nop 0
	v_add_f32_e32 v112, v124, v125
	ds_bpermute_b32 v113, v155, v112
	v_cvt_pk_bf16_f32 v114, v116, v117
	v_cvt_pk_bf16_f32 v115, v118, v119
	v_cvt_pk_bf16_f32 v116, v160, v161
	v_cvt_pk_bf16_f32 v117, v158, v159
	global_store_dwordx4 v[166:167], v[114:117], off offset:256
	s_and_saveexec_b64 s[4:5], s[6:7]
	s_cbranch_execz .LBB0_1914
	s_waitcnt lgkmcnt(0)
	v_add_f32_e32 v114, v112, v113
	v_lshlrev_b64 v[112:113], 6, v[146:147]
	v_lshl_add_u64 v[112:113], s[62:63], 0, v[112:113]
	v_lshl_add_u64 v[112:113], s[54:55], 2, v[112:113]
	s_lshl_b32 s20, s57, 2
	v_lshl_add_u64 v[112:113], v[112:113], 0, s[20:21]
	global_store_dword v[112:113], v114, off
.LBB0_1914:
	s_or_b64 exec, exec, s[4:5]
	v_or_b32_e32 v112, 16, v146
	s_waitcnt lgkmcnt(0)
	v_ashrrev_i32_e32 v113, 31, v112
	v_lshlrev_b64 v[114:115], 11, v[112:113]
	v_lshl_add_u64 v[114:115], s[48:49], 0, v[114:115]
	v_lshl_add_u64 v[122:123], v[144:145], 1, v[114:115]
	s_nop 1
	v_mov_b64_e32 v[114:115], v[184:185]
	v_mov_b64_e32 v[116:117], v[186:187]
	s_nop 1
	v_mov_b64_e32 v[118:119], v[188:189]
	v_mov_b64_e32 v[120:121], v[190:191]
	s_nop 1
	v_lshlrev_b32_e32 v124, 16, v114
	v_and_b32_e32 v125, 0xffff0000, v114
	v_lshlrev_b32_e32 v114, 16, v115
	v_and_b32_e32 v115, 0xffff0000, v115
	s_nop 1
	v_lshlrev_b32_e32 v158, 16, v118
	v_and_b32_e32 v159, 0xffff0000, v118
	v_lshlrev_b32_e32 v118, 16, v119
	v_and_b32_e32 v119, 0xffff0000, v119
	v_lshlrev_b32_e32 v126, 16, v116
	v_and_b32_e32 v127, 0xffff0000, v116
	v_lshlrev_b32_e32 v116, 16, v117
	v_and_b32_e32 v117, 0xffff0000, v117
	v_lshlrev_b32_e32 v160, 16, v120
	v_and_b32_e32 v161, 0xffff0000, v120
	v_lshlrev_b32_e32 v120, 16, v121
	v_and_b32_e32 v121, 0xffff0000, v121
	v_pk_add_f32 v[110:111], v[110:111], v[114:115]
	v_pk_add_f32 v[108:109], v[108:109], v[124:125]
	v_pk_add_f32 v[102:103], v[102:103], v[118:119]
	v_pk_add_f32 v[100:101], v[100:101], v[158:159]
	v_pk_add_f32 v[106:107], v[106:107], v[116:117]
	v_pk_add_f32 v[104:105], v[104:105], v[126:127]
	v_pk_add_f32 v[114:115], v[98:99], v[120:121]
	v_pk_add_f32 v[116:117], v[96:97], v[160:161]
	v_mul_f32_e32 v98, v109, v109
	v_mul_f32_e32 v99, v111, v111
	v_cvt_pk_bf16_f32 v96, v108, v109
	v_cvt_pk_bf16_f32 v97, v110, v111
	v_mul_f32_e32 v109, v101, v101
	v_mul_f32_e32 v111, v103, v103
	v_mul_f32_e32 v118, v105, v105
	v_mul_f32_e32 v120, v117, v117
	v_fmac_f32_e32 v98, v108, v108
	v_fmac_f32_e32 v99, v110, v110
	v_fmac_f32_e32 v109, v100, v100
	v_fmac_f32_e32 v111, v102, v102
	v_mul_f32_e32 v119, v107, v107
	v_mul_f32_e32 v121, v115, v115
	v_fmac_f32_e32 v118, v104, v104
	v_fmac_f32_e32 v120, v116, v116
	v_add_f32_e32 v98, v98, v99
	v_add_f32_e32 v99, v109, v111
	v_fmac_f32_e32 v119, v106, v106
	v_fmac_f32_e32 v121, v114, v114
	v_add_f32_e32 v98, v118, v98
	v_add_f32_e32 v99, v120, v99
	v_add_f32_e32 v98, v119, v98
	v_add_f32_e32 v99, v121, v99
	v_add_f32_e32 v108, v98, v99
	ds_bpermute_b32 v109, v156, v108
	v_cvt_pk_bf16_f32 v98, v104, v105
	v_cvt_pk_bf16_f32 v99, v106, v107
	global_store_dwordx4 v[122:123], v[96:99], off
	s_waitcnt lgkmcnt(0)
	s_nop 0
	v_add_f32_e32 v96, v108, v109
	ds_bpermute_b32 v97, v155, v96
	v_cvt_pk_bf16_f32 v98, v100, v101
	v_cvt_pk_bf16_f32 v99, v102, v103
	v_cvt_pk_bf16_f32 v100, v116, v117
	v_cvt_pk_bf16_f32 v101, v114, v115
	global_store_dwordx4 v[122:123], v[98:101], off offset:256
	s_and_saveexec_b64 s[4:5], s[6:7]
	s_cbranch_execz .LBB0_1916
	s_waitcnt lgkmcnt(0)
	v_add_f32_e32 v98, v96, v97
	v_lshlrev_b64 v[96:97], 6, v[112:113]
	v_lshl_add_u64 v[96:97], s[62:63], 0, v[96:97]
	v_lshl_add_u64 v[96:97], s[54:55], 2, v[96:97]
	s_lshl_b32 s20, s57, 2
	v_lshl_add_u64 v[96:97], v[96:97], 0, s[20:21]
	global_store_dword v[96:97], v98, off
.LBB0_1916:
	s_or_b64 exec, exec, s[4:5]
	v_or_b32_e32 v96, 32, v146
	s_waitcnt lgkmcnt(0)
	v_ashrrev_i32_e32 v97, 31, v96
	v_lshlrev_b64 v[98:99], 11, v[96:97]
	v_lshl_add_u64 v[98:99], s[48:49], 0, v[98:99]
	v_lshl_add_u64 v[106:107], v[144:145], 1, v[98:99]
	s_nop 1
	v_mov_b64_e32 v[98:99], v[192:193]
	v_mov_b64_e32 v[100:101], v[194:195]
	s_nop 1
	v_mov_b64_e32 v[102:103], v[196:197]
	v_mov_b64_e32 v[104:105], v[198:199]
	s_nop 1
	v_lshlrev_b32_e32 v108, 16, v98
	v_and_b32_e32 v109, 0xffff0000, v98
	v_lshlrev_b32_e32 v98, 16, v99
	v_and_b32_e32 v99, 0xffff0000, v99
	s_nop 1
	v_lshlrev_b32_e32 v112, 16, v102
	v_and_b32_e32 v113, 0xffff0000, v102
	v_lshlrev_b32_e32 v102, 16, v103
	v_and_b32_e32 v103, 0xffff0000, v103
	v_lshlrev_b32_e32 v110, 16, v100
	v_and_b32_e32 v111, 0xffff0000, v100
	v_lshlrev_b32_e32 v100, 16, v101
	v_and_b32_e32 v101, 0xffff0000, v101
	v_lshlrev_b32_e32 v114, 16, v104
	v_and_b32_e32 v115, 0xffff0000, v104
	v_lshlrev_b32_e32 v104, 16, v105
	v_and_b32_e32 v105, 0xffff0000, v105
	v_pk_add_f32 v[94:95], v[94:95], v[98:99]
	v_pk_add_f32 v[92:93], v[92:93], v[108:109]
	v_pk_add_f32 v[86:87], v[86:87], v[102:103]
	v_pk_add_f32 v[84:85], v[84:85], v[112:113]
	v_pk_add_f32 v[90:91], v[90:91], v[100:101]
	v_pk_add_f32 v[88:89], v[88:89], v[110:111]
	v_pk_add_f32 v[98:99], v[82:83], v[104:105]
	v_pk_add_f32 v[100:101], v[80:81], v[114:115]
	v_mul_f32_e32 v82, v93, v93
	v_mul_f32_e32 v83, v95, v95
	v_cvt_pk_bf16_f32 v80, v92, v93
	v_cvt_pk_bf16_f32 v81, v94, v95
	v_mul_f32_e32 v93, v85, v85
	v_mul_f32_e32 v95, v87, v87
	v_mul_f32_e32 v102, v89, v89
	v_mul_f32_e32 v104, v101, v101
	v_fmac_f32_e32 v82, v92, v92
	v_fmac_f32_e32 v83, v94, v94
	v_fmac_f32_e32 v93, v84, v84
	v_fmac_f32_e32 v95, v86, v86
	v_mul_f32_e32 v103, v91, v91
	v_mul_f32_e32 v105, v99, v99
	v_fmac_f32_e32 v102, v88, v88
	v_fmac_f32_e32 v104, v100, v100
	v_add_f32_e32 v82, v82, v83
	v_add_f32_e32 v83, v93, v95
	v_fmac_f32_e32 v103, v90, v90
	v_fmac_f32_e32 v105, v98, v98
	v_add_f32_e32 v82, v102, v82
	v_add_f32_e32 v83, v104, v83
	v_add_f32_e32 v82, v103, v82
	v_add_f32_e32 v83, v105, v83
	v_add_f32_e32 v92, v82, v83
	ds_bpermute_b32 v93, v156, v92
	v_cvt_pk_bf16_f32 v82, v88, v89
	v_cvt_pk_bf16_f32 v83, v90, v91
	global_store_dwordx4 v[106:107], v[80:83], off
	s_waitcnt lgkmcnt(0)
	s_nop 0
	v_add_f32_e32 v80, v92, v93
	ds_bpermute_b32 v81, v155, v80
	v_cvt_pk_bf16_f32 v82, v84, v85
	v_cvt_pk_bf16_f32 v83, v86, v87
	v_cvt_pk_bf16_f32 v84, v100, v101
	v_cvt_pk_bf16_f32 v85, v98, v99
	global_store_dwordx4 v[106:107], v[82:85], off offset:256
	s_and_saveexec_b64 s[4:5], s[6:7]
	s_cbranch_execz .LBB0_1918
	s_waitcnt lgkmcnt(0)
	v_add_f32_e32 v82, v80, v81
	v_lshlrev_b64 v[80:81], 6, v[96:97]
	v_lshl_add_u64 v[80:81], s[62:63], 0, v[80:81]
	v_lshl_add_u64 v[80:81], s[54:55], 2, v[80:81]
	s_lshl_b32 s20, s57, 2
	v_lshl_add_u64 v[80:81], v[80:81], 0, s[20:21]
	global_store_dword v[80:81], v82, off
.LBB0_1918:
	s_or_b64 exec, exec, s[4:5]
	v_or_b32_e32 v80, 48, v146
	s_waitcnt lgkmcnt(0)
	v_ashrrev_i32_e32 v81, 31, v80
	v_lshlrev_b64 v[82:83], 11, v[80:81]
	v_lshl_add_u64 v[82:83], s[48:49], 0, v[82:83]
	v_lshl_add_u64 v[90:91], v[144:145], 1, v[82:83]
	s_nop 1
	v_mov_b64_e32 v[82:83], v[204:205]
	v_mov_b64_e32 v[84:85], v[206:207]
	s_nop 1
	v_mov_b64_e32 v[86:87], v[208:209]
	v_mov_b64_e32 v[88:89], v[210:211]
	s_nop 1
	v_lshlrev_b32_e32 v92, 16, v82
	v_and_b32_e32 v93, 0xffff0000, v82
	v_lshlrev_b32_e32 v82, 16, v83
	v_and_b32_e32 v83, 0xffff0000, v83
	s_nop 1
	v_lshlrev_b32_e32 v96, 16, v86
	v_and_b32_e32 v97, 0xffff0000, v86
	v_lshlrev_b32_e32 v86, 16, v87
	v_and_b32_e32 v87, 0xffff0000, v87
	v_lshlrev_b32_e32 v94, 16, v84
	v_and_b32_e32 v95, 0xffff0000, v84
	v_lshlrev_b32_e32 v84, 16, v85
	v_and_b32_e32 v85, 0xffff0000, v85
	v_lshlrev_b32_e32 v98, 16, v88
	v_and_b32_e32 v99, 0xffff0000, v88
	v_lshlrev_b32_e32 v88, 16, v89
	v_and_b32_e32 v89, 0xffff0000, v89
	v_pk_add_f32 v[78:79], v[78:79], v[82:83]
	v_pk_add_f32 v[76:77], v[76:77], v[92:93]
	v_pk_add_f32 v[70:71], v[70:71], v[86:87]
	v_pk_add_f32 v[68:69], v[68:69], v[96:97]
	v_pk_add_f32 v[74:75], v[74:75], v[84:85]
	v_pk_add_f32 v[72:73], v[72:73], v[94:95]
	v_pk_add_f32 v[82:83], v[66:67], v[88:89]
	v_pk_add_f32 v[84:85], v[64:65], v[98:99]
	v_mul_f32_e32 v66, v77, v77
	v_mul_f32_e32 v67, v79, v79
	v_cvt_pk_bf16_f32 v64, v76, v77
	v_cvt_pk_bf16_f32 v65, v78, v79
	v_mul_f32_e32 v77, v69, v69
	v_mul_f32_e32 v79, v71, v71
	v_mul_f32_e32 v86, v73, v73
	v_mul_f32_e32 v88, v85, v85
	v_fmac_f32_e32 v66, v76, v76
	v_fmac_f32_e32 v67, v78, v78
	v_fmac_f32_e32 v77, v68, v68
	v_fmac_f32_e32 v79, v70, v70
	v_mul_f32_e32 v87, v75, v75
	v_mul_f32_e32 v89, v83, v83
	v_fmac_f32_e32 v86, v72, v72
	v_fmac_f32_e32 v88, v84, v84
	v_add_f32_e32 v66, v66, v67
	v_add_f32_e32 v67, v77, v79
	v_fmac_f32_e32 v87, v74, v74
	v_fmac_f32_e32 v89, v82, v82
	v_add_f32_e32 v66, v86, v66
	v_add_f32_e32 v67, v88, v67
	v_add_f32_e32 v66, v87, v66
	v_add_f32_e32 v67, v89, v67
	v_add_f32_e32 v76, v66, v67
	ds_bpermute_b32 v77, v156, v76
	v_cvt_pk_bf16_f32 v66, v72, v73
	v_cvt_pk_bf16_f32 v67, v74, v75
	global_store_dwordx4 v[90:91], v[64:67], off
	s_waitcnt lgkmcnt(0)
	s_nop 0
	v_add_f32_e32 v64, v76, v77
	ds_bpermute_b32 v65, v155, v64
	v_cvt_pk_bf16_f32 v66, v68, v69
	v_cvt_pk_bf16_f32 v67, v70, v71
	v_cvt_pk_bf16_f32 v68, v84, v85
	v_cvt_pk_bf16_f32 v69, v82, v83
	global_store_dwordx4 v[90:91], v[66:69], off offset:256
	s_and_saveexec_b64 s[4:5], s[6:7]
	s_cbranch_execz .LBB0_1920
	s_waitcnt lgkmcnt(0)
	v_add_f32_e32 v66, v64, v65
	v_lshlrev_b64 v[64:65], 6, v[80:81]
	v_lshl_add_u64 v[64:65], s[62:63], 0, v[64:65]
	v_lshl_add_u64 v[64:65], s[54:55], 2, v[64:65]
	s_lshl_b32 s20, s57, 2
	v_lshl_add_u64 v[64:65], v[64:65], 0, s[20:21]
	global_store_dword v[64:65], v66, off
.LBB0_1920:
	s_or_b64 exec, exec, s[4:5]
	v_add_u32_e32 v64, 0x80, v146
	s_waitcnt lgkmcnt(0)
	v_ashrrev_i32_e32 v65, 31, v64
	v_lshlrev_b64 v[66:67], 11, v[64:65]
	v_lshl_add_u64 v[66:67], s[48:49], 0, v[66:67]
	v_lshl_add_u64 v[74:75], v[144:145], 1, v[66:67]
	v_add_co_u32_e32 v212, vcc, 0x40000, v214
	s_nop 1
	v_addc_co_u32_e32 v213, vcc, 0, v215, vcc
	global_load_dwordx4 v[176:179], v[212:213], off
	v_add_co_u32_e32 v212, vcc, 0x40100, v214
	s_nop 1
	v_addc_co_u32_e32 v213, vcc, 0, v215, vcc
	global_load_dwordx4 v[180:183], v[212:213], off
	v_add_co_u32_e32 v212, vcc, 0x48000, v214
	s_nop 1
	v_addc_co_u32_e32 v213, vcc, 0, v215, vcc
	global_load_dwordx4 v[184:187], v[212:213], off
	v_add_co_u32_e32 v212, vcc, 0x48100, v214
	s_nop 1
	v_addc_co_u32_e32 v213, vcc, 0, v215, vcc
	global_load_dwordx4 v[188:191], v[212:213], off
	v_add_co_u32_e32 v212, vcc, 0x50000, v214
	s_nop 1
	v_addc_co_u32_e32 v213, vcc, 0, v215, vcc
	global_load_dwordx4 v[192:195], v[212:213], off
	v_add_co_u32_e32 v212, vcc, 0x50100, v214
	s_nop 1
	v_addc_co_u32_e32 v213, vcc, 0, v215, vcc
	global_load_dwordx4 v[196:199], v[212:213], off
	v_add_co_u32_e32 v212, vcc, 0x58000, v214
	s_nop 1
	v_addc_co_u32_e32 v213, vcc, 0, v215, vcc
	global_load_dwordx4 v[204:207], v[212:213], off
	v_add_co_u32_e32 v212, vcc, 0x58100, v214
	s_nop 1
	v_addc_co_u32_e32 v213, vcc, 0, v215, vcc
	global_load_dwordx4 v[208:211], v[212:213], off
	s_waitcnt vmcnt(0)
	s_nop 1
	v_mov_b64_e32 v[66:67], v[176:177]
	v_mov_b64_e32 v[68:69], v[178:179]
	s_nop 1
	v_mov_b64_e32 v[70:71], v[180:181]
	v_mov_b64_e32 v[72:73], v[182:183]
	s_nop 1
	v_lshlrev_b32_e32 v76, 16, v66
	v_and_b32_e32 v77, 0xffff0000, v66
	v_lshlrev_b32_e32 v66, 16, v67
	v_and_b32_e32 v67, 0xffff0000, v67
	s_nop 1
	v_lshlrev_b32_e32 v80, 16, v70
	v_and_b32_e32 v81, 0xffff0000, v70
	v_lshlrev_b32_e32 v70, 16, v71
	v_and_b32_e32 v71, 0xffff0000, v71
	v_lshlrev_b32_e32 v78, 16, v68
	v_and_b32_e32 v79, 0xffff0000, v68
	v_lshlrev_b32_e32 v68, 16, v69
	v_and_b32_e32 v69, 0xffff0000, v69
	v_lshlrev_b32_e32 v82, 16, v72
	v_and_b32_e32 v83, 0xffff0000, v72
	v_lshlrev_b32_e32 v72, 16, v73
	v_and_b32_e32 v73, 0xffff0000, v73
	v_pk_add_f32 v[62:63], v[62:63], v[66:67]
	v_pk_add_f32 v[60:61], v[60:61], v[76:77]
	v_pk_add_f32 v[54:55], v[54:55], v[70:71]
	v_pk_add_f32 v[52:53], v[52:53], v[80:81]
	v_pk_add_f32 v[58:59], v[58:59], v[68:69]
	v_pk_add_f32 v[56:57], v[56:57], v[78:79]
	v_pk_add_f32 v[66:67], v[50:51], v[72:73]
	v_pk_add_f32 v[68:69], v[48:49], v[82:83]
	v_mul_f32_e32 v50, v61, v61
	v_mul_f32_e32 v51, v63, v63
	v_cvt_pk_bf16_f32 v48, v60, v61
	v_cvt_pk_bf16_f32 v49, v62, v63
	v_mul_f32_e32 v61, v53, v53
	v_mul_f32_e32 v63, v55, v55
	v_mul_f32_e32 v70, v57, v57
	v_mul_f32_e32 v72, v69, v69
	v_fmac_f32_e32 v50, v60, v60
	v_fmac_f32_e32 v51, v62, v62
	v_fmac_f32_e32 v61, v52, v52
	v_fmac_f32_e32 v63, v54, v54
	v_mul_f32_e32 v71, v59, v59
	v_mul_f32_e32 v73, v67, v67
	v_fmac_f32_e32 v70, v56, v56
	v_fmac_f32_e32 v72, v68, v68
	v_add_f32_e32 v50, v50, v51
	v_add_f32_e32 v51, v61, v63
	v_fmac_f32_e32 v71, v58, v58
	v_fmac_f32_e32 v73, v66, v66
	v_add_f32_e32 v50, v70, v50
	v_add_f32_e32 v51, v72, v51
	v_add_f32_e32 v50, v71, v50
	v_add_f32_e32 v51, v73, v51
	v_add_f32_e32 v60, v50, v51
	ds_bpermute_b32 v61, v156, v60
	v_cvt_pk_bf16_f32 v50, v56, v57
	v_cvt_pk_bf16_f32 v51, v58, v59
	global_store_dwordx4 v[74:75], v[48:51], off
	s_waitcnt lgkmcnt(0)
	s_nop 0
	v_add_f32_e32 v48, v60, v61
	ds_bpermute_b32 v49, v155, v48
	v_cvt_pk_bf16_f32 v50, v52, v53
	v_cvt_pk_bf16_f32 v51, v54, v55
	v_cvt_pk_bf16_f32 v52, v68, v69
	v_cvt_pk_bf16_f32 v53, v66, v67
	global_store_dwordx4 v[74:75], v[50:53], off offset:256
	s_and_saveexec_b64 s[4:5], s[6:7]
	s_cbranch_execz .LBB0_1922
	s_waitcnt lgkmcnt(0)
	v_add_f32_e32 v50, v48, v49
	v_lshlrev_b64 v[48:49], 6, v[64:65]
	v_lshl_add_u64 v[48:49], s[62:63], 0, v[48:49]
	v_lshl_add_u64 v[48:49], s[54:55], 2, v[48:49]
	s_lshl_b32 s20, s57, 2
	v_lshl_add_u64 v[48:49], v[48:49], 0, s[20:21]
	global_store_dword v[48:49], v50, off
.LBB0_1922:
	s_or_b64 exec, exec, s[4:5]
	v_add_u32_e32 v48, 0x90, v146
	s_waitcnt lgkmcnt(0)
	v_ashrrev_i32_e32 v49, 31, v48
	v_lshlrev_b64 v[50:51], 11, v[48:49]
	v_lshl_add_u64 v[50:51], s[48:49], 0, v[50:51]
	v_lshl_add_u64 v[58:59], v[144:145], 1, v[50:51]
	s_nop 1
	v_mov_b64_e32 v[50:51], v[184:185]
	v_mov_b64_e32 v[52:53], v[186:187]
	s_nop 1
	v_mov_b64_e32 v[54:55], v[188:189]
	v_mov_b64_e32 v[56:57], v[190:191]
	s_nop 1
	v_lshlrev_b32_e32 v60, 16, v50
	v_and_b32_e32 v61, 0xffff0000, v50
	v_lshlrev_b32_e32 v50, 16, v51
	v_and_b32_e32 v51, 0xffff0000, v51
	s_nop 1
	v_lshlrev_b32_e32 v64, 16, v54
	v_and_b32_e32 v65, 0xffff0000, v54
	v_lshlrev_b32_e32 v54, 16, v55
	v_and_b32_e32 v55, 0xffff0000, v55
	v_lshlrev_b32_e32 v62, 16, v52
	v_and_b32_e32 v63, 0xffff0000, v52
	v_lshlrev_b32_e32 v52, 16, v53
	v_and_b32_e32 v53, 0xffff0000, v53
	v_lshlrev_b32_e32 v66, 16, v56
	v_and_b32_e32 v67, 0xffff0000, v56
	v_lshlrev_b32_e32 v56, 16, v57
	v_and_b32_e32 v57, 0xffff0000, v57
	v_pk_add_f32 v[46:47], v[46:47], v[50:51]
	v_pk_add_f32 v[44:45], v[44:45], v[60:61]
	v_pk_add_f32 v[38:39], v[38:39], v[54:55]
	v_pk_add_f32 v[36:37], v[36:37], v[64:65]
	v_pk_add_f32 v[42:43], v[42:43], v[52:53]
	v_pk_add_f32 v[40:41], v[40:41], v[62:63]
	v_pk_add_f32 v[50:51], v[34:35], v[56:57]
	v_pk_add_f32 v[52:53], v[32:33], v[66:67]
	v_mul_f32_e32 v34, v45, v45
	v_mul_f32_e32 v35, v47, v47
	v_cvt_pk_bf16_f32 v32, v44, v45
	v_cvt_pk_bf16_f32 v33, v46, v47
	v_mul_f32_e32 v45, v37, v37
	v_mul_f32_e32 v47, v39, v39
	v_mul_f32_e32 v54, v41, v41
	v_mul_f32_e32 v56, v53, v53
	v_fmac_f32_e32 v34, v44, v44
	v_fmac_f32_e32 v35, v46, v46
	v_fmac_f32_e32 v45, v36, v36
	v_fmac_f32_e32 v47, v38, v38
	v_mul_f32_e32 v55, v43, v43
	v_mul_f32_e32 v57, v51, v51
	v_fmac_f32_e32 v54, v40, v40
	v_fmac_f32_e32 v56, v52, v52
	v_add_f32_e32 v34, v34, v35
	v_add_f32_e32 v35, v45, v47
	v_fmac_f32_e32 v55, v42, v42
	v_fmac_f32_e32 v57, v50, v50
	v_add_f32_e32 v34, v54, v34
	v_add_f32_e32 v35, v56, v35
	v_add_f32_e32 v34, v55, v34
	v_add_f32_e32 v35, v57, v35
	v_add_f32_e32 v44, v34, v35
	ds_bpermute_b32 v45, v156, v44
	v_cvt_pk_bf16_f32 v34, v40, v41
	v_cvt_pk_bf16_f32 v35, v42, v43
	global_store_dwordx4 v[58:59], v[32:35], off
	s_waitcnt lgkmcnt(0)
	s_nop 0
	v_add_f32_e32 v32, v44, v45
	ds_bpermute_b32 v33, v155, v32
	v_cvt_pk_bf16_f32 v34, v36, v37
	v_cvt_pk_bf16_f32 v35, v38, v39
	v_cvt_pk_bf16_f32 v36, v52, v53
	v_cvt_pk_bf16_f32 v37, v50, v51
	global_store_dwordx4 v[58:59], v[34:37], off offset:256
	s_and_saveexec_b64 s[4:5], s[6:7]
	s_cbranch_execz .LBB0_1924
	s_waitcnt lgkmcnt(0)
	v_add_f32_e32 v34, v32, v33
	v_lshlrev_b64 v[32:33], 6, v[48:49]
	v_lshl_add_u64 v[32:33], s[62:63], 0, v[32:33]
	v_lshl_add_u64 v[32:33], s[54:55], 2, v[32:33]
	s_lshl_b32 s20, s57, 2
	v_lshl_add_u64 v[32:33], v[32:33], 0, s[20:21]
	global_store_dword v[32:33], v34, off
.LBB0_1924:
	s_or_b64 exec, exec, s[4:5]
	v_add_u32_e32 v32, 0xa0, v146
	s_waitcnt lgkmcnt(0)
	v_ashrrev_i32_e32 v33, 31, v32
	v_lshlrev_b64 v[34:35], 11, v[32:33]
	v_lshl_add_u64 v[34:35], s[48:49], 0, v[34:35]
	v_lshl_add_u64 v[42:43], v[144:145], 1, v[34:35]
	s_nop 1
	v_mov_b64_e32 v[34:35], v[192:193]
	v_mov_b64_e32 v[36:37], v[194:195]
	s_nop 1
	v_mov_b64_e32 v[38:39], v[196:197]
	v_mov_b64_e32 v[40:41], v[198:199]
	s_nop 1
	v_lshlrev_b32_e32 v44, 16, v34
	v_and_b32_e32 v45, 0xffff0000, v34
	v_lshlrev_b32_e32 v34, 16, v35
	v_and_b32_e32 v35, 0xffff0000, v35
	s_nop 1
	v_lshlrev_b32_e32 v48, 16, v38
	v_and_b32_e32 v49, 0xffff0000, v38
	v_lshlrev_b32_e32 v38, 16, v39
	v_and_b32_e32 v39, 0xffff0000, v39
	v_lshlrev_b32_e32 v46, 16, v36
	v_and_b32_e32 v47, 0xffff0000, v36
	v_lshlrev_b32_e32 v36, 16, v37
	v_and_b32_e32 v37, 0xffff0000, v37
	v_lshlrev_b32_e32 v50, 16, v40
	v_and_b32_e32 v51, 0xffff0000, v40
	v_lshlrev_b32_e32 v40, 16, v41
	v_and_b32_e32 v41, 0xffff0000, v41
	v_pk_add_f32 v[30:31], v[30:31], v[34:35]
	v_pk_add_f32 v[28:29], v[28:29], v[44:45]
	v_pk_add_f32 v[22:23], v[22:23], v[38:39]
	v_pk_add_f32 v[20:21], v[20:21], v[48:49]
	v_pk_add_f32 v[26:27], v[26:27], v[36:37]
	v_pk_add_f32 v[24:25], v[24:25], v[46:47]
	v_pk_add_f32 v[34:35], v[18:19], v[40:41]
	v_pk_add_f32 v[36:37], v[16:17], v[50:51]
	v_mul_f32_e32 v18, v29, v29
	v_mul_f32_e32 v19, v31, v31
	v_cvt_pk_bf16_f32 v16, v28, v29
	v_cvt_pk_bf16_f32 v17, v30, v31
	v_mul_f32_e32 v29, v21, v21
	v_mul_f32_e32 v31, v23, v23
	v_mul_f32_e32 v38, v25, v25
	v_mul_f32_e32 v40, v37, v37
	v_fmac_f32_e32 v18, v28, v28
	v_fmac_f32_e32 v19, v30, v30
	v_fmac_f32_e32 v29, v20, v20
	v_fmac_f32_e32 v31, v22, v22
	v_mul_f32_e32 v39, v27, v27
	v_mul_f32_e32 v41, v35, v35
	v_fmac_f32_e32 v38, v24, v24
	v_fmac_f32_e32 v40, v36, v36
	v_add_f32_e32 v18, v18, v19
	v_add_f32_e32 v19, v29, v31
	v_fmac_f32_e32 v39, v26, v26
	v_fmac_f32_e32 v41, v34, v34
	v_add_f32_e32 v18, v38, v18
	v_add_f32_e32 v19, v40, v19
	v_add_f32_e32 v18, v39, v18
	v_add_f32_e32 v19, v41, v19
	v_add_f32_e32 v28, v18, v19
	ds_bpermute_b32 v29, v156, v28
	v_cvt_pk_bf16_f32 v18, v24, v25
	v_cvt_pk_bf16_f32 v19, v26, v27
	global_store_dwordx4 v[42:43], v[16:19], off
	s_waitcnt lgkmcnt(0)
	s_nop 0
	v_add_f32_e32 v16, v28, v29
	ds_bpermute_b32 v17, v155, v16
	v_cvt_pk_bf16_f32 v18, v20, v21
	v_cvt_pk_bf16_f32 v19, v22, v23
	v_cvt_pk_bf16_f32 v20, v36, v37
	v_cvt_pk_bf16_f32 v21, v34, v35
	global_store_dwordx4 v[42:43], v[18:21], off offset:256
	s_and_saveexec_b64 s[4:5], s[6:7]
	s_cbranch_execz .LBB0_1926
	s_waitcnt lgkmcnt(0)
	v_add_f32_e32 v18, v16, v17
	v_lshlrev_b64 v[16:17], 6, v[32:33]
	v_lshl_add_u64 v[16:17], s[62:63], 0, v[16:17]
	v_lshl_add_u64 v[16:17], s[54:55], 2, v[16:17]
	s_lshl_b32 s20, s57, 2
	v_lshl_add_u64 v[16:17], v[16:17], 0, s[20:21]
	global_store_dword v[16:17], v18, off
.LBB0_1926:
	s_or_b64 exec, exec, s[4:5]
	v_add_u32_e32 v16, 0xb0, v146
	s_waitcnt lgkmcnt(0)
	v_ashrrev_i32_e32 v17, 31, v16
	v_lshlrev_b64 v[18:19], 11, v[16:17]
	v_lshl_add_u64 v[18:19], s[48:49], 0, v[18:19]
	v_lshl_add_u64 v[26:27], v[144:145], 1, v[18:19]
	s_nop 1
	v_mov_b64_e32 v[18:19], v[204:205]
	v_mov_b64_e32 v[20:21], v[206:207]
	s_nop 1
	v_mov_b64_e32 v[22:23], v[208:209]
	v_mov_b64_e32 v[24:25], v[210:211]
	s_nop 1
	v_lshlrev_b32_e32 v28, 16, v18
	v_and_b32_e32 v29, 0xffff0000, v18
	v_lshlrev_b32_e32 v18, 16, v19
	v_and_b32_e32 v19, 0xffff0000, v19
	s_nop 1
	v_lshlrev_b32_e32 v32, 16, v22
	v_and_b32_e32 v33, 0xffff0000, v22
	v_lshlrev_b32_e32 v22, 16, v23
	v_and_b32_e32 v23, 0xffff0000, v23
	v_lshlrev_b32_e32 v30, 16, v20
	v_and_b32_e32 v31, 0xffff0000, v20
	v_lshlrev_b32_e32 v20, 16, v21
	v_and_b32_e32 v21, 0xffff0000, v21
	v_lshlrev_b32_e32 v34, 16, v24
	v_and_b32_e32 v35, 0xffff0000, v24
	v_lshlrev_b32_e32 v24, 16, v25
	v_and_b32_e32 v25, 0xffff0000, v25
	v_pk_add_f32 v[14:15], v[14:15], v[18:19]
	v_pk_add_f32 v[12:13], v[12:13], v[28:29]
	v_pk_add_f32 v[6:7], v[6:7], v[22:23]
	v_pk_add_f32 v[4:5], v[4:5], v[32:33]
	v_pk_add_f32 v[10:11], v[10:11], v[20:21]
	v_pk_add_f32 v[8:9], v[8:9], v[30:31]
	v_pk_add_f32 v[18:19], v[2:3], v[24:25]
	v_pk_add_f32 v[20:21], v[0:1], v[34:35]
	v_mul_f32_e32 v2, v13, v13
	v_mul_f32_e32 v3, v15, v15
	v_cvt_pk_bf16_f32 v0, v12, v13
	v_cvt_pk_bf16_f32 v1, v14, v15
	v_mul_f32_e32 v13, v5, v5
	v_mul_f32_e32 v15, v7, v7
	v_mul_f32_e32 v22, v9, v9
	v_mul_f32_e32 v24, v21, v21
	v_fmac_f32_e32 v2, v12, v12
	v_fmac_f32_e32 v3, v14, v14
	v_fmac_f32_e32 v13, v4, v4
	v_fmac_f32_e32 v15, v6, v6
	v_mul_f32_e32 v23, v11, v11
	v_mul_f32_e32 v25, v19, v19
	v_fmac_f32_e32 v22, v8, v8
	v_fmac_f32_e32 v24, v20, v20
	v_add_f32_e32 v2, v2, v3
	v_add_f32_e32 v3, v13, v15
	v_fmac_f32_e32 v23, v10, v10
	v_fmac_f32_e32 v25, v18, v18
	v_add_f32_e32 v2, v22, v2
	v_add_f32_e32 v3, v24, v3
	v_add_f32_e32 v2, v23, v2
	v_add_f32_e32 v3, v25, v3
	v_add_f32_e32 v12, v2, v3
	ds_bpermute_b32 v13, v156, v12
	v_cvt_pk_bf16_f32 v2, v8, v9
	v_cvt_pk_bf16_f32 v3, v10, v11
	global_store_dwordx4 v[26:27], v[0:3], off
	s_waitcnt lgkmcnt(0)
	s_nop 0
	v_add_f32_e32 v0, v12, v13
	ds_bpermute_b32 v1, v155, v0
	v_cvt_pk_bf16_f32 v2, v4, v5
	v_cvt_pk_bf16_f32 v3, v6, v7
	v_cvt_pk_bf16_f32 v4, v20, v21
	v_cvt_pk_bf16_f32 v5, v18, v19
	global_store_dwordx4 v[26:27], v[2:5], off offset:256
	s_and_saveexec_b64 s[4:5], s[6:7]
	s_cbranch_execz .LBB0_1928
	s_waitcnt lgkmcnt(0)
	v_add_f32_e32 v2, v0, v1
	v_lshlrev_b64 v[0:1], 6, v[16:17]
	v_lshl_add_u64 v[0:1], s[62:63], 0, v[0:1]
	v_lshl_add_u64 v[0:1], s[54:55], 2, v[0:1]
	s_lshl_b32 s20, s57, 2
	v_lshl_add_u64 v[0:1], v[0:1], 0, s[20:21]
	global_store_dword v[0:1], v2, off

.LBB0_2243:
	v_lshl_add_u32 v146, s36, 8, v148
	v_ashrrev_i32_e32 v147, 31, v146
	v_lshl_or_b32 v144, s10, 8, v150
	v_lshlrev_b64 v[156:157], 11, v[146:147]
	v_ashrrev_i32_e32 v145, 31, v144
	v_lshl_add_u64 v[156:157], s[48:49], 0, v[156:157]
	v_lshl_add_u64 v[166:167], v[144:145], 1, v[156:157]
	v_mov_b64_e32 v[214:215], v[166:167]
	global_load_dwordx4 v[176:179], v[166:167], off
	v_add_co_u32_e32 v212, vcc, 0x100, v166
	s_nop 1
	v_addc_co_u32_e32 v213, vcc, 0, v167, vcc
	global_load_dwordx4 v[180:183], v[212:213], off
	v_add_co_u32_e32 v212, vcc, 0x8000, v166
	s_nop 1
	v_addc_co_u32_e32 v213, vcc, 0, v167, vcc
	global_load_dwordx4 v[184:187], v[212:213], off
	v_add_co_u32_e32 v212, vcc, 0x8100, v166
	s_nop 1
	v_addc_co_u32_e32 v213, vcc, 0, v167, vcc
	global_load_dwordx4 v[188:191], v[212:213], off
	v_add_co_u32_e32 v212, vcc, 0x10000, v166
	s_nop 1
	v_addc_co_u32_e32 v213, vcc, 0, v167, vcc
	global_load_dwordx4 v[192:195], v[212:213], off
	v_add_co_u32_e32 v212, vcc, 0x10100, v166
	s_nop 1
	v_addc_co_u32_e32 v213, vcc, 0, v167, vcc
	global_load_dwordx4 v[196:199], v[212:213], off
	v_add_co_u32_e32 v212, vcc, 0x18000, v166
	s_nop 1
	v_addc_co_u32_e32 v213, vcc, 0, v167, vcc
	global_load_dwordx4 v[204:207], v[212:213], off
	v_add_co_u32_e32 v212, vcc, 0x18100, v166
	s_nop 1
	v_addc_co_u32_e32 v213, vcc, 0, v167, vcc
	global_load_dwordx4 v[208:211], v[212:213], off
	s_waitcnt vmcnt(0)
	s_nop 1
	v_mov_b64_e32 v[158:159], v[176:177]
	v_mov_b64_e32 v[160:161], v[178:179]
	s_nop 1
	v_mov_b64_e32 v[162:163], v[180:181]
	v_mov_b64_e32 v[164:165], v[182:183]
	v_and_b32_e32 v156, 64, v154
	v_xor_b32_e32 v155, 16, v154
	v_add_u32_e32 v156, 64, v156
	v_xor_b32_e32 v157, 32, v154
	v_cmp_lt_i32_e32 vcc, v155, v156
	s_lshl_b32 s36, s10, 2
	s_ashr_i32 s37, s36, 31
	v_cndmask_b32_e32 v155, v154, v155, vcc
	v_cmp_lt_i32_e32 vcc, v157, v156
	v_lshlrev_b32_e32 v156, 2, v155
	s_nop 1
	v_lshlrev_b32_e32 v168, 16, v158
	v_and_b32_e32 v169, 0xffff0000, v158
	v_lshlrev_b32_e32 v158, 16, v159
	v_and_b32_e32 v159, 0xffff0000, v159
	v_lshlrev_b32_e32 v172, 16, v162
	v_and_b32_e32 v173, 0xffff0000, v162
	v_lshlrev_b32_e32 v162, 16, v163
	v_and_b32_e32 v163, 0xffff0000, v163
	v_lshlrev_b32_e32 v170, 16, v160
	v_and_b32_e32 v171, 0xffff0000, v160
	v_lshlrev_b32_e32 v160, 16, v161
	v_and_b32_e32 v161, 0xffff0000, v161
	v_lshlrev_b32_e32 v174, 16, v164
	v_and_b32_e32 v175, 0xffff0000, v164
	v_lshlrev_b32_e32 v164, 16, v165
	v_and_b32_e32 v165, 0xffff0000, v165
	v_pk_add_f32 v[126:127], v[126:127], v[158:159]
	v_pk_add_f32 v[124:125], v[124:125], v[168:169]
	v_pk_add_f32 v[118:119], v[118:119], v[162:163]
	v_pk_add_f32 v[116:117], v[116:117], v[172:173]
	v_cndmask_b32_e32 v157, v154, v157, vcc
	v_pk_add_f32 v[122:123], v[122:123], v[160:161]
	v_pk_add_f32 v[120:121], v[120:121], v[170:171]
	v_pk_add_f32 v[158:159], v[114:115], v[164:165]
	v_pk_add_f32 v[160:161], v[112:113], v[174:175]
	v_mul_f32_e32 v114, v125, v125
	v_mul_f32_e32 v115, v127, v127
	v_cvt_pk_bf16_f32 v112, v124, v125
	v_cvt_pk_bf16_f32 v113, v126, v127
	v_mul_f32_e32 v125, v117, v117
	v_mul_f32_e32 v127, v119, v119
	v_lshlrev_b32_e32 v155, 2, v157
	v_mul_f32_e32 v157, v121, v121
	v_mul_f32_e32 v163, v161, v161
	v_fmac_f32_e32 v114, v124, v124
	v_fmac_f32_e32 v115, v126, v126
	v_fmac_f32_e32 v125, v116, v116
	v_fmac_f32_e32 v127, v118, v118
	v_mul_f32_e32 v162, v123, v123
	v_mul_f32_e32 v164, v159, v159
	v_fmac_f32_e32 v157, v120, v120
	v_fmac_f32_e32 v163, v160, v160
	v_add_f32_e32 v114, v114, v115
	v_add_f32_e32 v115, v125, v127
	v_fmac_f32_e32 v162, v122, v122
	v_fmac_f32_e32 v164, v158, v158
	v_add_f32_e32 v114, v157, v114
	v_add_f32_e32 v115, v163, v115
	v_add_f32_e32 v114, v162, v114
	v_add_f32_e32 v115, v164, v115
	v_add_f32_e32 v124, v114, v115
	ds_bpermute_b32 v125, v156, v124
	v_cvt_pk_bf16_f32 v114, v120, v121
	v_cvt_pk_bf16_f32 v115, v122, v123
	global_store_dwordx4 v[166:167], v[112:115], off
	s_waitcnt lgkmcnt(0)
	s_nop 0
	v_add_f32_e32 v112, v124, v125
	ds_bpermute_b32 v113, v155, v112
	v_cvt_pk_bf16_f32 v114, v116, v117
	v_cvt_pk_bf16_f32 v115, v118, v119
	v_cvt_pk_bf16_f32 v116, v160, v161
	v_cvt_pk_bf16_f32 v117, v158, v159
	global_store_dwordx4 v[166:167], v[114:117], off offset:256
	s_and_saveexec_b64 s[4:5], s[6:7]
	s_cbranch_execz .LBB0_2245
	s_waitcnt lgkmcnt(0)
	v_add_f32_e32 v114, v112, v113
	v_lshlrev_b64 v[112:113], 6, v[146:147]
	v_lshl_add_u64 v[112:113], s[62:63], 0, v[112:113]
	v_lshl_add_u64 v[112:113], s[36:37], 2, v[112:113]
	s_lshl_b32 s10, s50, 2
	v_lshl_add_u64 v[112:113], v[112:113], 0, s[10:11]
	global_store_dword v[112:113], v114, off
.LBB0_2245:
	s_or_b64 exec, exec, s[4:5]
	v_or_b32_e32 v112, 16, v146
	s_waitcnt lgkmcnt(0)
	v_ashrrev_i32_e32 v113, 31, v112
	v_lshlrev_b64 v[114:115], 11, v[112:113]
	v_lshl_add_u64 v[114:115], s[48:49], 0, v[114:115]
	v_lshl_add_u64 v[122:123], v[144:145], 1, v[114:115]
	s_nop 1
	v_mov_b64_e32 v[114:115], v[184:185]
	v_mov_b64_e32 v[116:117], v[186:187]
	s_nop 1
	v_mov_b64_e32 v[118:119], v[188:189]
	v_mov_b64_e32 v[120:121], v[190:191]
	s_nop 1
	v_lshlrev_b32_e32 v124, 16, v114
	v_and_b32_e32 v125, 0xffff0000, v114
	v_lshlrev_b32_e32 v114, 16, v115
	v_and_b32_e32 v115, 0xffff0000, v115
	s_nop 1
	v_lshlrev_b32_e32 v158, 16, v118
	v_and_b32_e32 v159, 0xffff0000, v118
	v_lshlrev_b32_e32 v118, 16, v119
	v_and_b32_e32 v119, 0xffff0000, v119
	v_lshlrev_b32_e32 v126, 16, v116
	v_and_b32_e32 v127, 0xffff0000, v116
	v_lshlrev_b32_e32 v116, 16, v117
	v_and_b32_e32 v117, 0xffff0000, v117
	v_lshlrev_b32_e32 v160, 16, v120
	v_and_b32_e32 v161, 0xffff0000, v120
	v_lshlrev_b32_e32 v120, 16, v121
	v_and_b32_e32 v121, 0xffff0000, v121
	v_pk_add_f32 v[110:111], v[110:111], v[114:115]
	v_pk_add_f32 v[108:109], v[108:109], v[124:125]
	v_pk_add_f32 v[102:103], v[102:103], v[118:119]
	v_pk_add_f32 v[100:101], v[100:101], v[158:159]
	v_pk_add_f32 v[106:107], v[106:107], v[116:117]
	v_pk_add_f32 v[104:105], v[104:105], v[126:127]
	v_pk_add_f32 v[114:115], v[98:99], v[120:121]
	v_pk_add_f32 v[116:117], v[96:97], v[160:161]
	v_mul_f32_e32 v98, v109, v109
	v_mul_f32_e32 v99, v111, v111
	v_cvt_pk_bf16_f32 v96, v108, v109
	v_cvt_pk_bf16_f32 v97, v110, v111
	v_mul_f32_e32 v109, v101, v101
	v_mul_f32_e32 v111, v103, v103
	v_mul_f32_e32 v118, v105, v105
	v_mul_f32_e32 v120, v117, v117
	v_fmac_f32_e32 v98, v108, v108
	v_fmac_f32_e32 v99, v110, v110
	v_fmac_f32_e32 v109, v100, v100
	v_fmac_f32_e32 v111, v102, v102
	v_mul_f32_e32 v119, v107, v107
	v_mul_f32_e32 v121, v115, v115
	v_fmac_f32_e32 v118, v104, v104
	v_fmac_f32_e32 v120, v116, v116
	v_add_f32_e32 v98, v98, v99
	v_add_f32_e32 v99, v109, v111
	v_fmac_f32_e32 v119, v106, v106
	v_fmac_f32_e32 v121, v114, v114
	v_add_f32_e32 v98, v118, v98
	v_add_f32_e32 v99, v120, v99
	v_add_f32_e32 v98, v119, v98
	v_add_f32_e32 v99, v121, v99
	v_add_f32_e32 v108, v98, v99
	ds_bpermute_b32 v109, v156, v108
	v_cvt_pk_bf16_f32 v98, v104, v105
	v_cvt_pk_bf16_f32 v99, v106, v107
	global_store_dwordx4 v[122:123], v[96:99], off
	s_waitcnt lgkmcnt(0)
	s_nop 0
	v_add_f32_e32 v96, v108, v109
	ds_bpermute_b32 v97, v155, v96
	v_cvt_pk_bf16_f32 v98, v100, v101
	v_cvt_pk_bf16_f32 v99, v102, v103
	v_cvt_pk_bf16_f32 v100, v116, v117
	v_cvt_pk_bf16_f32 v101, v114, v115
	global_store_dwordx4 v[122:123], v[98:101], off offset:256
	s_and_saveexec_b64 s[4:5], s[6:7]
	s_cbranch_execz .LBB0_2247
	s_waitcnt lgkmcnt(0)
	v_add_f32_e32 v98, v96, v97
	v_lshlrev_b64 v[96:97], 6, v[112:113]
	v_lshl_add_u64 v[96:97], s[62:63], 0, v[96:97]
	v_lshl_add_u64 v[96:97], s[36:37], 2, v[96:97]
	s_lshl_b32 s10, s50, 2
	v_lshl_add_u64 v[96:97], v[96:97], 0, s[10:11]
	global_store_dword v[96:97], v98, off
.LBB0_2247:
	s_or_b64 exec, exec, s[4:5]
	v_or_b32_e32 v96, 32, v146
	s_waitcnt lgkmcnt(0)
	v_ashrrev_i32_e32 v97, 31, v96
	v_lshlrev_b64 v[98:99], 11, v[96:97]
	v_lshl_add_u64 v[98:99], s[48:49], 0, v[98:99]
	v_lshl_add_u64 v[106:107], v[144:145], 1, v[98:99]
	s_nop 1
	v_mov_b64_e32 v[98:99], v[192:193]
	v_mov_b64_e32 v[100:101], v[194:195]
	s_nop 1
	v_mov_b64_e32 v[102:103], v[196:197]
	v_mov_b64_e32 v[104:105], v[198:199]
	s_nop 1
	v_lshlrev_b32_e32 v108, 16, v98
	v_and_b32_e32 v109, 0xffff0000, v98
	v_lshlrev_b32_e32 v98, 16, v99
	v_and_b32_e32 v99, 0xffff0000, v99
	s_nop 1
	v_lshlrev_b32_e32 v112, 16, v102
	v_and_b32_e32 v113, 0xffff0000, v102
	v_lshlrev_b32_e32 v102, 16, v103
	v_and_b32_e32 v103, 0xffff0000, v103
	v_lshlrev_b32_e32 v110, 16, v100
	v_and_b32_e32 v111, 0xffff0000, v100
	v_lshlrev_b32_e32 v100, 16, v101
	v_and_b32_e32 v101, 0xffff0000, v101
	v_lshlrev_b32_e32 v114, 16, v104
	v_and_b32_e32 v115, 0xffff0000, v104
	v_lshlrev_b32_e32 v104, 16, v105
	v_and_b32_e32 v105, 0xffff0000, v105
	v_pk_add_f32 v[94:95], v[94:95], v[98:99]
	v_pk_add_f32 v[92:93], v[92:93], v[108:109]
	v_pk_add_f32 v[86:87], v[86:87], v[102:103]
	v_pk_add_f32 v[84:85], v[84:85], v[112:113]
	v_pk_add_f32 v[90:91], v[90:91], v[100:101]
	v_pk_add_f32 v[88:89], v[88:89], v[110:111]
	v_pk_add_f32 v[98:99], v[82:83], v[104:105]
	v_pk_add_f32 v[100:101], v[80:81], v[114:115]
	v_mul_f32_e32 v82, v93, v93
	v_mul_f32_e32 v83, v95, v95
	v_cvt_pk_bf16_f32 v80, v92, v93
	v_cvt_pk_bf16_f32 v81, v94, v95
	v_mul_f32_e32 v93, v85, v85
	v_mul_f32_e32 v95, v87, v87
	v_mul_f32_e32 v102, v89, v89
	v_mul_f32_e32 v104, v101, v101
	v_fmac_f32_e32 v82, v92, v92
	v_fmac_f32_e32 v83, v94, v94
	v_fmac_f32_e32 v93, v84, v84
	v_fmac_f32_e32 v95, v86, v86
	v_mul_f32_e32 v103, v91, v91
	v_mul_f32_e32 v105, v99, v99
	v_fmac_f32_e32 v102, v88, v88
	v_fmac_f32_e32 v104, v100, v100
	v_add_f32_e32 v82, v82, v83
	v_add_f32_e32 v83, v93, v95
	v_fmac_f32_e32 v103, v90, v90
	v_fmac_f32_e32 v105, v98, v98
	v_add_f32_e32 v82, v102, v82
	v_add_f32_e32 v83, v104, v83
	v_add_f32_e32 v82, v103, v82
	v_add_f32_e32 v83, v105, v83
	v_add_f32_e32 v92, v82, v83
	ds_bpermute_b32 v93, v156, v92
	v_cvt_pk_bf16_f32 v82, v88, v89
	v_cvt_pk_bf16_f32 v83, v90, v91
	global_store_dwordx4 v[106:107], v[80:83], off
	s_waitcnt lgkmcnt(0)
	s_nop 0
	v_add_f32_e32 v80, v92, v93
	ds_bpermute_b32 v81, v155, v80
	v_cvt_pk_bf16_f32 v82, v84, v85
	v_cvt_pk_bf16_f32 v83, v86, v87
	v_cvt_pk_bf16_f32 v84, v100, v101
	v_cvt_pk_bf16_f32 v85, v98, v99
	global_store_dwordx4 v[106:107], v[82:85], off offset:256
	s_and_saveexec_b64 s[4:5], s[6:7]
	s_cbranch_execz .LBB0_2249
	s_waitcnt lgkmcnt(0)
	v_add_f32_e32 v82, v80, v81
	v_lshlrev_b64 v[80:81], 6, v[96:97]
	v_lshl_add_u64 v[80:81], s[62:63], 0, v[80:81]
	v_lshl_add_u64 v[80:81], s[36:37], 2, v[80:81]
	s_lshl_b32 s10, s50, 2
	v_lshl_add_u64 v[80:81], v[80:81], 0, s[10:11]
	global_store_dword v[80:81], v82, off
.LBB0_2249:
	s_or_b64 exec, exec, s[4:5]
	v_or_b32_e32 v80, 48, v146
	s_waitcnt lgkmcnt(0)
	v_ashrrev_i32_e32 v81, 31, v80
	v_lshlrev_b64 v[82:83], 11, v[80:81]
	v_lshl_add_u64 v[82:83], s[48:49], 0, v[82:83]
	v_lshl_add_u64 v[90:91], v[144:145], 1, v[82:83]
	s_nop 1
	v_mov_b64_e32 v[82:83], v[204:205]
	v_mov_b64_e32 v[84:85], v[206:207]
	s_nop 1
	v_mov_b64_e32 v[86:87], v[208:209]
	v_mov_b64_e32 v[88:89], v[210:211]
	s_nop 1
	v_lshlrev_b32_e32 v92, 16, v82
	v_and_b32_e32 v93, 0xffff0000, v82
	v_lshlrev_b32_e32 v82, 16, v83
	v_and_b32_e32 v83, 0xffff0000, v83
	s_nop 1
	v_lshlrev_b32_e32 v96, 16, v86
	v_and_b32_e32 v97, 0xffff0000, v86
	v_lshlrev_b32_e32 v86, 16, v87
	v_and_b32_e32 v87, 0xffff0000, v87
	v_lshlrev_b32_e32 v94, 16, v84
	v_and_b32_e32 v95, 0xffff0000, v84
	v_lshlrev_b32_e32 v84, 16, v85
	v_and_b32_e32 v85, 0xffff0000, v85
	v_lshlrev_b32_e32 v98, 16, v88
	v_and_b32_e32 v99, 0xffff0000, v88
	v_lshlrev_b32_e32 v88, 16, v89
	v_and_b32_e32 v89, 0xffff0000, v89
	v_pk_add_f32 v[78:79], v[78:79], v[82:83]
	v_pk_add_f32 v[76:77], v[76:77], v[92:93]
	v_pk_add_f32 v[70:71], v[70:71], v[86:87]
	v_pk_add_f32 v[68:69], v[68:69], v[96:97]
	v_pk_add_f32 v[74:75], v[74:75], v[84:85]
	v_pk_add_f32 v[72:73], v[72:73], v[94:95]
	v_pk_add_f32 v[82:83], v[66:67], v[88:89]
	v_pk_add_f32 v[84:85], v[64:65], v[98:99]
	v_mul_f32_e32 v66, v77, v77
	v_mul_f32_e32 v67, v79, v79
	v_cvt_pk_bf16_f32 v64, v76, v77
	v_cvt_pk_bf16_f32 v65, v78, v79
	v_mul_f32_e32 v77, v69, v69
	v_mul_f32_e32 v79, v71, v71
	v_mul_f32_e32 v86, v73, v73
	v_mul_f32_e32 v88, v85, v85
	v_fmac_f32_e32 v66, v76, v76
	v_fmac_f32_e32 v67, v78, v78
	v_fmac_f32_e32 v77, v68, v68
	v_fmac_f32_e32 v79, v70, v70
	v_mul_f32_e32 v87, v75, v75
	v_mul_f32_e32 v89, v83, v83
	v_fmac_f32_e32 v86, v72, v72
	v_fmac_f32_e32 v88, v84, v84
	v_add_f32_e32 v66, v66, v67
	v_add_f32_e32 v67, v77, v79
	v_fmac_f32_e32 v87, v74, v74
	v_fmac_f32_e32 v89, v82, v82
	v_add_f32_e32 v66, v86, v66
	v_add_f32_e32 v67, v88, v67
	v_add_f32_e32 v66, v87, v66
	v_add_f32_e32 v67, v89, v67
	v_add_f32_e32 v76, v66, v67
	ds_bpermute_b32 v77, v156, v76
	v_cvt_pk_bf16_f32 v66, v72, v73
	v_cvt_pk_bf16_f32 v67, v74, v75
	global_store_dwordx4 v[90:91], v[64:67], off
	s_waitcnt lgkmcnt(0)
	s_nop 0
	v_add_f32_e32 v64, v76, v77
	ds_bpermute_b32 v65, v155, v64
	v_cvt_pk_bf16_f32 v66, v68, v69
	v_cvt_pk_bf16_f32 v67, v70, v71
	v_cvt_pk_bf16_f32 v68, v84, v85
	v_cvt_pk_bf16_f32 v69, v82, v83
	global_store_dwordx4 v[90:91], v[66:69], off offset:256
	s_and_saveexec_b64 s[4:5], s[6:7]
	s_cbranch_execz .LBB0_2251
	s_waitcnt lgkmcnt(0)
	v_add_f32_e32 v66, v64, v65
	v_lshlrev_b64 v[64:65], 6, v[80:81]
	v_lshl_add_u64 v[64:65], s[62:63], 0, v[64:65]
	v_lshl_add_u64 v[64:65], s[36:37], 2, v[64:65]
	s_lshl_b32 s10, s50, 2
	v_lshl_add_u64 v[64:65], v[64:65], 0, s[10:11]
	global_store_dword v[64:65], v66, off
.LBB0_2251:
	s_or_b64 exec, exec, s[4:5]
	v_add_u32_e32 v64, 0x80, v146
	s_waitcnt lgkmcnt(0)
	v_ashrrev_i32_e32 v65, 31, v64
	v_lshlrev_b64 v[66:67], 11, v[64:65]
	v_lshl_add_u64 v[66:67], s[48:49], 0, v[66:67]
	v_lshl_add_u64 v[74:75], v[144:145], 1, v[66:67]
	v_add_co_u32_e32 v212, vcc, 0x40000, v214
	s_nop 1
	v_addc_co_u32_e32 v213, vcc, 0, v215, vcc
	global_load_dwordx4 v[176:179], v[212:213], off
	v_add_co_u32_e32 v212, vcc, 0x40100, v214
	s_nop 1
	v_addc_co_u32_e32 v213, vcc, 0, v215, vcc
	global_load_dwordx4 v[180:183], v[212:213], off
	v_add_co_u32_e32 v212, vcc, 0x48000, v214
	s_nop 1
	v_addc_co_u32_e32 v213, vcc, 0, v215, vcc
	global_load_dwordx4 v[184:187], v[212:213], off
	v_add_co_u32_e32 v212, vcc, 0x48100, v214
	s_nop 1
	v_addc_co_u32_e32 v213, vcc, 0, v215, vcc
	global_load_dwordx4 v[188:191], v[212:213], off
	v_add_co_u32_e32 v212, vcc, 0x50000, v214
	s_nop 1
	v_addc_co_u32_e32 v213, vcc, 0, v215, vcc
	global_load_dwordx4 v[192:195], v[212:213], off
	v_add_co_u32_e32 v212, vcc, 0x50100, v214
	s_nop 1
	v_addc_co_u32_e32 v213, vcc, 0, v215, vcc
	global_load_dwordx4 v[196:199], v[212:213], off
	v_add_co_u32_e32 v212, vcc, 0x58000, v214
	s_nop 1
	v_addc_co_u32_e32 v213, vcc, 0, v215, vcc
	global_load_dwordx4 v[204:207], v[212:213], off
	v_add_co_u32_e32 v212, vcc, 0x58100, v214
	s_nop 1
	v_addc_co_u32_e32 v213, vcc, 0, v215, vcc
	global_load_dwordx4 v[208:211], v[212:213], off
	s_waitcnt vmcnt(0)
	s_nop 1
	v_mov_b64_e32 v[66:67], v[176:177]
	v_mov_b64_e32 v[68:69], v[178:179]
	s_nop 1
	v_mov_b64_e32 v[70:71], v[180:181]
	v_mov_b64_e32 v[72:73], v[182:183]
	s_nop 1
	v_lshlrev_b32_e32 v76, 16, v66
	v_and_b32_e32 v77, 0xffff0000, v66
	v_lshlrev_b32_e32 v66, 16, v67
	v_and_b32_e32 v67, 0xffff0000, v67
	s_nop 1
	v_lshlrev_b32_e32 v80, 16, v70
	v_and_b32_e32 v81, 0xffff0000, v70
	v_lshlrev_b32_e32 v70, 16, v71
	v_and_b32_e32 v71, 0xffff0000, v71
	v_lshlrev_b32_e32 v78, 16, v68
	v_and_b32_e32 v79, 0xffff0000, v68
	v_lshlrev_b32_e32 v68, 16, v69
	v_and_b32_e32 v69, 0xffff0000, v69
	v_lshlrev_b32_e32 v82, 16, v72
	v_and_b32_e32 v83, 0xffff0000, v72
	v_lshlrev_b32_e32 v72, 16, v73
	v_and_b32_e32 v73, 0xffff0000, v73
	v_pk_add_f32 v[62:63], v[62:63], v[66:67]
	v_pk_add_f32 v[60:61], v[60:61], v[76:77]
	v_pk_add_f32 v[54:55], v[54:55], v[70:71]
	v_pk_add_f32 v[52:53], v[52:53], v[80:81]
	v_pk_add_f32 v[58:59], v[58:59], v[68:69]
	v_pk_add_f32 v[56:57], v[56:57], v[78:79]
	v_pk_add_f32 v[66:67], v[50:51], v[72:73]
	v_pk_add_f32 v[68:69], v[48:49], v[82:83]
	v_mul_f32_e32 v50, v61, v61
	v_mul_f32_e32 v51, v63, v63
	v_cvt_pk_bf16_f32 v48, v60, v61
	v_cvt_pk_bf16_f32 v49, v62, v63
	v_mul_f32_e32 v61, v53, v53
	v_mul_f32_e32 v63, v55, v55
	v_mul_f32_e32 v70, v57, v57
	v_mul_f32_e32 v72, v69, v69
	v_fmac_f32_e32 v50, v60, v60
	v_fmac_f32_e32 v51, v62, v62
	v_fmac_f32_e32 v61, v52, v52
	v_fmac_f32_e32 v63, v54, v54
	v_mul_f32_e32 v71, v59, v59
	v_mul_f32_e32 v73, v67, v67
	v_fmac_f32_e32 v70, v56, v56
	v_fmac_f32_e32 v72, v68, v68
	v_add_f32_e32 v50, v50, v51
	v_add_f32_e32 v51, v61, v63
	v_fmac_f32_e32 v71, v58, v58
	v_fmac_f32_e32 v73, v66, v66
	v_add_f32_e32 v50, v70, v50
	v_add_f32_e32 v51, v72, v51
	v_add_f32_e32 v50, v71, v50
	v_add_f32_e32 v51, v73, v51
	v_add_f32_e32 v60, v50, v51
	ds_bpermute_b32 v61, v156, v60
	v_cvt_pk_bf16_f32 v50, v56, v57
	v_cvt_pk_bf16_f32 v51, v58, v59
	global_store_dwordx4 v[74:75], v[48:51], off
	s_waitcnt lgkmcnt(0)
	s_nop 0
	v_add_f32_e32 v48, v60, v61
	ds_bpermute_b32 v49, v155, v48
	v_cvt_pk_bf16_f32 v50, v52, v53
	v_cvt_pk_bf16_f32 v51, v54, v55
	v_cvt_pk_bf16_f32 v52, v68, v69
	v_cvt_pk_bf16_f32 v53, v66, v67
	global_store_dwordx4 v[74:75], v[50:53], off offset:256
	s_and_saveexec_b64 s[4:5], s[6:7]
	s_cbranch_execz .LBB0_2253
	s_waitcnt lgkmcnt(0)
	v_add_f32_e32 v50, v48, v49
	v_lshlrev_b64 v[48:49], 6, v[64:65]
	v_lshl_add_u64 v[48:49], s[62:63], 0, v[48:49]
	v_lshl_add_u64 v[48:49], s[36:37], 2, v[48:49]
	s_lshl_b32 s10, s50, 2
	v_lshl_add_u64 v[48:49], v[48:49], 0, s[10:11]
	global_store_dword v[48:49], v50, off
.LBB0_2253:
	s_or_b64 exec, exec, s[4:5]
	v_add_u32_e32 v48, 0x90, v146
	s_waitcnt lgkmcnt(0)
	v_ashrrev_i32_e32 v49, 31, v48
	v_lshlrev_b64 v[50:51], 11, v[48:49]
	v_lshl_add_u64 v[50:51], s[48:49], 0, v[50:51]
	v_lshl_add_u64 v[58:59], v[144:145], 1, v[50:51]
	s_nop 1
	v_mov_b64_e32 v[50:51], v[184:185]
	v_mov_b64_e32 v[52:53], v[186:187]
	s_nop 1
	v_mov_b64_e32 v[54:55], v[188:189]
	v_mov_b64_e32 v[56:57], v[190:191]
	s_nop 1
	v_lshlrev_b32_e32 v60, 16, v50
	v_and_b32_e32 v61, 0xffff0000, v50
	v_lshlrev_b32_e32 v50, 16, v51
	v_and_b32_e32 v51, 0xffff0000, v51
	s_nop 1
	v_lshlrev_b32_e32 v64, 16, v54
	v_and_b32_e32 v65, 0xffff0000, v54
	v_lshlrev_b32_e32 v54, 16, v55
	v_and_b32_e32 v55, 0xffff0000, v55
	v_lshlrev_b32_e32 v62, 16, v52
	v_and_b32_e32 v63, 0xffff0000, v52
	v_lshlrev_b32_e32 v52, 16, v53
	v_and_b32_e32 v53, 0xffff0000, v53
	v_lshlrev_b32_e32 v66, 16, v56
	v_and_b32_e32 v67, 0xffff0000, v56
	v_lshlrev_b32_e32 v56, 16, v57
	v_and_b32_e32 v57, 0xffff0000, v57
	v_pk_add_f32 v[46:47], v[46:47], v[50:51]
	v_pk_add_f32 v[44:45], v[44:45], v[60:61]
	v_pk_add_f32 v[38:39], v[38:39], v[54:55]
	v_pk_add_f32 v[36:37], v[36:37], v[64:65]
	v_pk_add_f32 v[42:43], v[42:43], v[52:53]
	v_pk_add_f32 v[40:41], v[40:41], v[62:63]
	v_pk_add_f32 v[50:51], v[34:35], v[56:57]
	v_pk_add_f32 v[52:53], v[32:33], v[66:67]
	v_mul_f32_e32 v34, v45, v45
	v_mul_f32_e32 v35, v47, v47
	v_cvt_pk_bf16_f32 v32, v44, v45
	v_cvt_pk_bf16_f32 v33, v46, v47
	v_mul_f32_e32 v45, v37, v37
	v_mul_f32_e32 v47, v39, v39
	v_mul_f32_e32 v54, v41, v41
	v_mul_f32_e32 v56, v53, v53
	v_fmac_f32_e32 v34, v44, v44
	v_fmac_f32_e32 v35, v46, v46
	v_fmac_f32_e32 v45, v36, v36
	v_fmac_f32_e32 v47, v38, v38
	v_mul_f32_e32 v55, v43, v43
	v_mul_f32_e32 v57, v51, v51
	v_fmac_f32_e32 v54, v40, v40
	v_fmac_f32_e32 v56, v52, v52
	v_add_f32_e32 v34, v34, v35
	v_add_f32_e32 v35, v45, v47
	v_fmac_f32_e32 v55, v42, v42
	v_fmac_f32_e32 v57, v50, v50
	v_add_f32_e32 v34, v54, v34
	v_add_f32_e32 v35, v56, v35
	v_add_f32_e32 v34, v55, v34
	v_add_f32_e32 v35, v57, v35
	v_add_f32_e32 v44, v34, v35
	ds_bpermute_b32 v45, v156, v44
	v_cvt_pk_bf16_f32 v34, v40, v41
	v_cvt_pk_bf16_f32 v35, v42, v43
	global_store_dwordx4 v[58:59], v[32:35], off
	s_waitcnt lgkmcnt(0)
	s_nop 0
	v_add_f32_e32 v32, v44, v45
	ds_bpermute_b32 v33, v155, v32
	v_cvt_pk_bf16_f32 v34, v36, v37
	v_cvt_pk_bf16_f32 v35, v38, v39
	v_cvt_pk_bf16_f32 v36, v52, v53
	v_cvt_pk_bf16_f32 v37, v50, v51
	global_store_dwordx4 v[58:59], v[34:37], off offset:256
	s_and_saveexec_b64 s[4:5], s[6:7]
	s_cbranch_execz .LBB0_2255
	s_waitcnt lgkmcnt(0)
	v_add_f32_e32 v34, v32, v33
	v_lshlrev_b64 v[32:33], 6, v[48:49]
	v_lshl_add_u64 v[32:33], s[62:63], 0, v[32:33]
	v_lshl_add_u64 v[32:33], s[36:37], 2, v[32:33]
	s_lshl_b32 s10, s50, 2
	v_lshl_add_u64 v[32:33], v[32:33], 0, s[10:11]
	global_store_dword v[32:33], v34, off
.LBB0_2255:
	s_or_b64 exec, exec, s[4:5]
	v_add_u32_e32 v32, 0xa0, v146
	s_waitcnt lgkmcnt(0)
	v_ashrrev_i32_e32 v33, 31, v32
	v_lshlrev_b64 v[34:35], 11, v[32:33]
	v_lshl_add_u64 v[34:35], s[48:49], 0, v[34:35]
	v_lshl_add_u64 v[42:43], v[144:145], 1, v[34:35]
	s_nop 1
	v_mov_b64_e32 v[34:35], v[192:193]
	v_mov_b64_e32 v[36:37], v[194:195]
	s_nop 1
	v_mov_b64_e32 v[38:39], v[196:197]
	v_mov_b64_e32 v[40:41], v[198:199]
	s_nop 1
	v_lshlrev_b32_e32 v44, 16, v34
	v_and_b32_e32 v45, 0xffff0000, v34
	v_lshlrev_b32_e32 v34, 16, v35
	v_and_b32_e32 v35, 0xffff0000, v35
	s_nop 1
	v_lshlrev_b32_e32 v48, 16, v38
	v_and_b32_e32 v49, 0xffff0000, v38
	v_lshlrev_b32_e32 v38, 16, v39
	v_and_b32_e32 v39, 0xffff0000, v39
	v_lshlrev_b32_e32 v46, 16, v36
	v_and_b32_e32 v47, 0xffff0000, v36
	v_lshlrev_b32_e32 v36, 16, v37
	v_and_b32_e32 v37, 0xffff0000, v37
	v_lshlrev_b32_e32 v50, 16, v40
	v_and_b32_e32 v51, 0xffff0000, v40
	v_lshlrev_b32_e32 v40, 16, v41
	v_and_b32_e32 v41, 0xffff0000, v41
	v_pk_add_f32 v[30:31], v[30:31], v[34:35]
	v_pk_add_f32 v[28:29], v[28:29], v[44:45]
	v_pk_add_f32 v[22:23], v[22:23], v[38:39]
	v_pk_add_f32 v[20:21], v[20:21], v[48:49]
	v_pk_add_f32 v[26:27], v[26:27], v[36:37]
	v_pk_add_f32 v[24:25], v[24:25], v[46:47]
	v_pk_add_f32 v[34:35], v[18:19], v[40:41]
	v_pk_add_f32 v[36:37], v[16:17], v[50:51]
	v_mul_f32_e32 v18, v29, v29
	v_mul_f32_e32 v19, v31, v31
	v_cvt_pk_bf16_f32 v16, v28, v29
	v_cvt_pk_bf16_f32 v17, v30, v31
	v_mul_f32_e32 v29, v21, v21
	v_mul_f32_e32 v31, v23, v23
	v_mul_f32_e32 v38, v25, v25
	v_mul_f32_e32 v40, v37, v37
	v_fmac_f32_e32 v18, v28, v28
	v_fmac_f32_e32 v19, v30, v30
	v_fmac_f32_e32 v29, v20, v20
	v_fmac_f32_e32 v31, v22, v22
	v_mul_f32_e32 v39, v27, v27
	v_mul_f32_e32 v41, v35, v35
	v_fmac_f32_e32 v38, v24, v24
	v_fmac_f32_e32 v40, v36, v36
	v_add_f32_e32 v18, v18, v19
	v_add_f32_e32 v19, v29, v31
	v_fmac_f32_e32 v39, v26, v26
	v_fmac_f32_e32 v41, v34, v34
	v_add_f32_e32 v18, v38, v18
	v_add_f32_e32 v19, v40, v19
	v_add_f32_e32 v18, v39, v18
	v_add_f32_e32 v19, v41, v19
	v_add_f32_e32 v28, v18, v19
	ds_bpermute_b32 v29, v156, v28
	v_cvt_pk_bf16_f32 v18, v24, v25
	v_cvt_pk_bf16_f32 v19, v26, v27
	global_store_dwordx4 v[42:43], v[16:19], off
	s_waitcnt lgkmcnt(0)
	s_nop 0
	v_add_f32_e32 v16, v28, v29
	ds_bpermute_b32 v17, v155, v16
	v_cvt_pk_bf16_f32 v18, v20, v21
	v_cvt_pk_bf16_f32 v19, v22, v23
	v_cvt_pk_bf16_f32 v20, v36, v37
	v_cvt_pk_bf16_f32 v21, v34, v35
	global_store_dwordx4 v[42:43], v[18:21], off offset:256
	s_and_saveexec_b64 s[4:5], s[6:7]
	s_cbranch_execz .LBB0_2257
	s_waitcnt lgkmcnt(0)
	v_add_f32_e32 v18, v16, v17
	v_lshlrev_b64 v[16:17], 6, v[32:33]
	v_lshl_add_u64 v[16:17], s[62:63], 0, v[16:17]
	v_lshl_add_u64 v[16:17], s[36:37], 2, v[16:17]
	s_lshl_b32 s10, s50, 2
	v_lshl_add_u64 v[16:17], v[16:17], 0, s[10:11]
	global_store_dword v[16:17], v18, off
.LBB0_2257:
	s_or_b64 exec, exec, s[4:5]
	v_add_u32_e32 v16, 0xb0, v146
	s_waitcnt lgkmcnt(0)
	v_ashrrev_i32_e32 v17, 31, v16
	v_lshlrev_b64 v[18:19], 11, v[16:17]
	v_lshl_add_u64 v[18:19], s[48:49], 0, v[18:19]
	v_lshl_add_u64 v[26:27], v[144:145], 1, v[18:19]
	s_nop 1
	v_mov_b64_e32 v[18:19], v[204:205]
	v_mov_b64_e32 v[20:21], v[206:207]
	s_nop 1
	v_mov_b64_e32 v[22:23], v[208:209]
	v_mov_b64_e32 v[24:25], v[210:211]
	s_nop 1
	v_lshlrev_b32_e32 v28, 16, v18
	v_and_b32_e32 v29, 0xffff0000, v18
	v_lshlrev_b32_e32 v18, 16, v19
	v_and_b32_e32 v19, 0xffff0000, v19
	s_nop 1
	v_lshlrev_b32_e32 v32, 16, v22
	v_and_b32_e32 v33, 0xffff0000, v22
	v_lshlrev_b32_e32 v22, 16, v23
	v_and_b32_e32 v23, 0xffff0000, v23
	v_lshlrev_b32_e32 v30, 16, v20
	v_and_b32_e32 v31, 0xffff0000, v20
	v_lshlrev_b32_e32 v20, 16, v21
	v_and_b32_e32 v21, 0xffff0000, v21
	v_lshlrev_b32_e32 v34, 16, v24
	v_and_b32_e32 v35, 0xffff0000, v24
	v_lshlrev_b32_e32 v24, 16, v25
	v_and_b32_e32 v25, 0xffff0000, v25
	v_pk_add_f32 v[14:15], v[14:15], v[18:19]
	v_pk_add_f32 v[12:13], v[12:13], v[28:29]
	v_pk_add_f32 v[6:7], v[6:7], v[22:23]
	v_pk_add_f32 v[4:5], v[4:5], v[32:33]
	v_pk_add_f32 v[10:11], v[10:11], v[20:21]
	v_pk_add_f32 v[8:9], v[8:9], v[30:31]
	v_pk_add_f32 v[18:19], v[2:3], v[24:25]
	v_pk_add_f32 v[20:21], v[0:1], v[34:35]
	v_mul_f32_e32 v2, v13, v13
	v_mul_f32_e32 v3, v15, v15
	v_cvt_pk_bf16_f32 v0, v12, v13
	v_cvt_pk_bf16_f32 v1, v14, v15
	v_mul_f32_e32 v13, v5, v5
	v_mul_f32_e32 v15, v7, v7
	v_mul_f32_e32 v22, v9, v9
	v_mul_f32_e32 v24, v21, v21
	v_fmac_f32_e32 v2, v12, v12
	v_fmac_f32_e32 v3, v14, v14
	v_fmac_f32_e32 v13, v4, v4
	v_fmac_f32_e32 v15, v6, v6
	v_mul_f32_e32 v23, v11, v11
	v_mul_f32_e32 v25, v19, v19
	v_fmac_f32_e32 v22, v8, v8
	v_fmac_f32_e32 v24, v20, v20
	v_add_f32_e32 v2, v2, v3
	v_add_f32_e32 v3, v13, v15
	v_fmac_f32_e32 v23, v10, v10
	v_fmac_f32_e32 v25, v18, v18
	v_add_f32_e32 v2, v22, v2
	v_add_f32_e32 v3, v24, v3
	v_add_f32_e32 v2, v23, v2
	v_add_f32_e32 v3, v25, v3
	v_add_f32_e32 v12, v2, v3
	ds_bpermute_b32 v13, v156, v12
	v_cvt_pk_bf16_f32 v2, v8, v9
	v_cvt_pk_bf16_f32 v3, v10, v11
	global_store_dwordx4 v[26:27], v[0:3], off
	s_waitcnt lgkmcnt(0)
	s_nop 0
	v_add_f32_e32 v0, v12, v13
	ds_bpermute_b32 v1, v155, v0
	v_cvt_pk_bf16_f32 v2, v4, v5
	v_cvt_pk_bf16_f32 v3, v6, v7
	v_cvt_pk_bf16_f32 v4, v20, v21
	v_cvt_pk_bf16_f32 v5, v18, v19
	global_store_dwordx4 v[26:27], v[2:5], off offset:256
	s_and_saveexec_b64 s[4:5], s[6:7]
	s_cbranch_execz .LBB0_2259
	s_waitcnt lgkmcnt(0)
	v_add_f32_e32 v2, v0, v1
	v_lshlrev_b64 v[0:1], 6, v[16:17]
	v_lshl_add_u64 v[0:1], s[62:63], 0, v[0:1]
	v_lshl_add_u64 v[0:1], s[36:37], 2, v[0:1]
	s_lshl_b32 s10, s50, 2
	v_lshl_add_u64 v[0:1], v[0:1], 0, s[10:11]
	global_store_dword v[0:1], v2, off

.LBB0_2465:
	v_lshl_add_u32 v146, s4, 8, v154
	v_lshl_or_b32 v144, s8, 8, v156
	v_ashrrev_i32_e32 v147, 31, v146
	v_ashrrev_i32_e32 v145, 31, v144
	v_lshlrev_b64 v[148:149], 10, v[146:147]
	v_lshl_add_u64 v[148:149], v[148:149], 0, v[144:145]
	v_lshl_add_u64 v[150:151], v[148:149], 1, s[48:49]
	v_mov_b64_e32 v[206:207], v[150:151]
	global_load_dwordx4 v[172:175], v[150:151], off
	v_add_co_u32_e32 v204, vcc, 0x100, v150
	s_nop 1
	v_addc_co_u32_e32 v205, vcc, 0, v151, vcc
	global_load_dwordx4 v[176:179], v[204:205], off
	v_add_co_u32_e32 v204, vcc, 0x8000, v150
	s_nop 1
	v_addc_co_u32_e32 v205, vcc, 0, v151, vcc
	global_load_dwordx4 v[180:183], v[204:205], off
	v_add_co_u32_e32 v204, vcc, 0x8100, v150
	s_nop 1
	v_addc_co_u32_e32 v205, vcc, 0, v151, vcc
	global_load_dwordx4 v[184:187], v[204:205], off
	v_add_co_u32_e32 v204, vcc, 0x10000, v150
	s_nop 1
	v_addc_co_u32_e32 v205, vcc, 0, v151, vcc
	global_load_dwordx4 v[188:191], v[204:205], off
	v_add_co_u32_e32 v204, vcc, 0x10100, v150
	s_nop 1
	v_addc_co_u32_e32 v205, vcc, 0, v151, vcc
	global_load_dwordx4 v[192:195], v[204:205], off
	v_add_co_u32_e32 v204, vcc, 0x18000, v150
	s_nop 1
	v_addc_co_u32_e32 v205, vcc, 0, v151, vcc
	global_load_dwordx4 v[196:199], v[204:205], off
	v_add_co_u32_e32 v204, vcc, 0x18100, v150
	s_nop 1
	v_addc_co_u32_e32 v205, vcc, 0, v151, vcc
	global_load_dwordx4 v[200:203], v[204:205], off
	s_waitcnt vmcnt(0)
	s_nop 1
	v_mov_b64_e32 v[162:163], v[172:173]
	v_mov_b64_e32 v[164:165], v[174:175]
	v_cndmask_b32_e64 v152, 0, 1, s[18:19]
	v_cmp_ne_u32_e64 s[4:5], 1, v152
	s_andn2_b64 vcc, exec, s[18:19]
	s_nop 1
	v_lshlrev_b32_e32 v152, 16, v162
	v_and_b32_e32 v153, 0xffff0000, v162
	v_lshlrev_b32_e32 v162, 16, v163
	v_and_b32_e32 v163, 0xffff0000, v163
	v_lshlrev_b32_e32 v166, 16, v164
	v_and_b32_e32 v167, 0xffff0000, v164
	v_lshlrev_b32_e32 v164, 16, v165
	v_and_b32_e32 v165, 0xffff0000, v165
	v_pk_add_f32 v[126:127], v[126:127], v[162:163]
	v_pk_add_f32 v[124:125], v[124:125], v[152:153]
	v_pk_add_f32 v[122:123], v[122:123], v[164:165]
	v_pk_add_f32 v[120:121], v[120:121], v[166:167]
	v_lshl_add_u64 v[152:153], v[148:149], 2, s[60:61]
	s_cbranch_vccnz .LBB0_2467
	global_store_dwordx4 v[152:153], v[124:127], off
	global_store_dwordx4 v[152:153], v[120:123], off offset:16
.LBB0_2467:
	v_lshlrev_b64 v[148:149], 1, v[148:149]
	v_or_b32_e32 v148, 0x100, v148
	v_lshl_add_u64 v[148:149], s[48:49], 0, v[148:149]
	s_nop 1
	v_mov_b64_e32 v[162:163], v[176:177]
	v_mov_b64_e32 v[164:165], v[178:179]
	v_cvt_pk_bf16_f32 v166, v124, v125
	v_cvt_pk_bf16_f32 v167, v126, v127
	v_cvt_pk_bf16_f32 v168, v120, v121
	v_cvt_pk_bf16_f32 v169, v122, v123
	global_store_dwordx4 v[150:151], v[166:169], off
	s_and_b64 vcc, exec, s[4:5]
	s_nop 1
	v_lshlrev_b32_e32 v150, 16, v162
	v_and_b32_e32 v151, 0xffff0000, v162
	v_lshlrev_b32_e32 v162, 16, v163
	v_and_b32_e32 v163, 0xffff0000, v163
	v_lshlrev_b32_e32 v166, 16, v164
	v_and_b32_e32 v167, 0xffff0000, v164
	v_lshlrev_b32_e32 v164, 16, v165
	v_and_b32_e32 v165, 0xffff0000, v165
	v_pk_add_f32 v[118:119], v[118:119], v[162:163]
	v_pk_add_f32 v[116:117], v[116:117], v[150:151]
	v_pk_add_f32 v[114:115], v[114:115], v[164:165]
	v_pk_add_f32 v[112:113], v[112:113], v[166:167]
	s_cbranch_vccnz .LBB0_2469
	global_store_dwordx4 v[152:153], v[116:119], off offset:512
	global_store_dwordx4 v[152:153], v[112:115], off offset:528

.LBB0_2471:
	s_or_b64 exec, exec, s[30:31]
	v_or_b32_e32 v112, 16, v146
	v_ashrrev_i32_e32 v113, 31, v112
	v_lshlrev_b64 v[114:115], 10, v[112:113]
	s_waitcnt lgkmcnt(0)
	v_lshl_add_u64 v[116:117], v[114:115], 0, v[144:145]
	v_lshl_add_u64 v[114:115], v[116:117], 1, s[48:49]
	s_nop 1
	v_mov_b64_e32 v[122:123], v[180:181]
	v_mov_b64_e32 v[124:125], v[182:183]
	s_and_b64 vcc, exec, s[4:5]
	s_nop 1
	v_lshlrev_b32_e32 v118, 16, v122
	v_and_b32_e32 v119, 0xffff0000, v122
	v_lshlrev_b32_e32 v122, 16, v123
	v_and_b32_e32 v123, 0xffff0000, v123
	v_lshlrev_b32_e32 v126, 16, v124
	v_and_b32_e32 v127, 0xffff0000, v124
	v_lshlrev_b32_e32 v124, 16, v125
	v_and_b32_e32 v125, 0xffff0000, v125
	v_pk_add_f32 v[110:111], v[110:111], v[122:123]
	v_pk_add_f32 v[108:109], v[108:109], v[118:119]
	v_pk_add_f32 v[106:107], v[106:107], v[124:125]
	v_pk_add_f32 v[104:105], v[104:105], v[126:127]
	v_lshl_add_u64 v[118:119], v[116:117], 2, s[60:61]
	s_cbranch_vccnz .LBB0_2473
	global_store_dwordx4 v[118:119], v[108:111], off
	global_store_dwordx4 v[118:119], v[104:107], off offset:16
.LBB0_2473:
	v_lshlrev_b64 v[116:117], 1, v[116:117]
	v_or_b32_e32 v116, 0x100, v116
	v_lshl_add_u64 v[116:117], s[48:49], 0, v[116:117]
	s_nop 1
	v_mov_b64_e32 v[122:123], v[184:185]
	v_mov_b64_e32 v[124:125], v[186:187]
	v_cvt_pk_bf16_f32 v148, v108, v109
	v_cvt_pk_bf16_f32 v149, v110, v111
	v_cvt_pk_bf16_f32 v150, v104, v105
	v_cvt_pk_bf16_f32 v151, v106, v107
	global_store_dwordx4 v[114:115], v[148:151], off
	s_and_b64 vcc, exec, s[4:5]
	s_nop 1
	v_lshlrev_b32_e32 v114, 16, v122
	v_and_b32_e32 v115, 0xffff0000, v122
	v_lshlrev_b32_e32 v122, 16, v123
	v_and_b32_e32 v123, 0xffff0000, v123
	v_lshlrev_b32_e32 v126, 16, v124
	v_and_b32_e32 v127, 0xffff0000, v124
	v_lshlrev_b32_e32 v124, 16, v125
	v_and_b32_e32 v125, 0xffff0000, v125
	v_pk_add_f32 v[102:103], v[102:103], v[122:123]
	v_pk_add_f32 v[100:101], v[100:101], v[114:115]
	v_pk_add_f32 v[98:99], v[98:99], v[124:125]
	v_pk_add_f32 v[96:97], v[96:97], v[126:127]
	s_cbranch_vccnz .LBB0_2475
	global_store_dwordx4 v[118:119], v[100:103], off offset:512
	global_store_dwordx4 v[118:119], v[96:99], off offset:528

.LBB0_2477:
	s_or_b64 exec, exec, s[30:31]
	v_or_b32_e32 v96, 32, v146
	v_ashrrev_i32_e32 v97, 31, v96
	v_lshlrev_b64 v[98:99], 10, v[96:97]
	s_waitcnt lgkmcnt(0)
	v_lshl_add_u64 v[100:101], v[98:99], 0, v[144:145]
	v_lshl_add_u64 v[98:99], v[100:101], 1, s[48:49]
	s_nop 1
	v_mov_b64_e32 v[102:103], v[188:189]
	v_mov_b64_e32 v[104:105], v[190:191]
	s_and_b64 vcc, exec, s[4:5]
	s_nop 1
	v_lshlrev_b32_e32 v106, 16, v102
	v_and_b32_e32 v107, 0xffff0000, v102
	v_lshlrev_b32_e32 v102, 16, v103
	v_and_b32_e32 v103, 0xffff0000, v103
	v_lshlrev_b32_e32 v108, 16, v104
	v_and_b32_e32 v109, 0xffff0000, v104
	v_lshlrev_b32_e32 v104, 16, v105
	v_and_b32_e32 v105, 0xffff0000, v105
	v_pk_add_f32 v[94:95], v[94:95], v[102:103]
	v_pk_add_f32 v[92:93], v[92:93], v[106:107]
	v_pk_add_f32 v[90:91], v[90:91], v[104:105]
	v_pk_add_f32 v[88:89], v[88:89], v[108:109]
	v_lshl_add_u64 v[102:103], v[100:101], 2, s[60:61]
	s_cbranch_vccnz .LBB0_2479
	global_store_dwordx4 v[102:103], v[92:95], off
	global_store_dwordx4 v[102:103], v[88:91], off offset:16
.LBB0_2479:
	v_lshlrev_b64 v[100:101], 1, v[100:101]
	v_or_b32_e32 v100, 0x100, v100
	v_lshl_add_u64 v[100:101], s[48:49], 0, v[100:101]
	s_nop 1
	v_mov_b64_e32 v[104:105], v[192:193]
	v_mov_b64_e32 v[106:107], v[194:195]
	v_cvt_pk_bf16_f32 v108, v92, v93
	v_cvt_pk_bf16_f32 v109, v94, v95
	v_cvt_pk_bf16_f32 v110, v88, v89
	v_cvt_pk_bf16_f32 v111, v90, v91
	global_store_dwordx4 v[98:99], v[108:111], off
	s_and_b64 vcc, exec, s[4:5]
	s_nop 1
	v_lshlrev_b32_e32 v98, 16, v104
	v_and_b32_e32 v99, 0xffff0000, v104
	v_lshlrev_b32_e32 v104, 16, v105
	v_and_b32_e32 v105, 0xffff0000, v105
	v_lshlrev_b32_e32 v108, 16, v106
	v_and_b32_e32 v109, 0xffff0000, v106
	v_lshlrev_b32_e32 v106, 16, v107
	v_and_b32_e32 v107, 0xffff0000, v107
	v_pk_add_f32 v[86:87], v[86:87], v[104:105]
	v_pk_add_f32 v[84:85], v[84:85], v[98:99]
	v_pk_add_f32 v[82:83], v[82:83], v[106:107]
	v_pk_add_f32 v[80:81], v[80:81], v[108:109]
	s_cbranch_vccnz .LBB0_2481
	global_store_dwordx4 v[102:103], v[84:87], off offset:512
	global_store_dwordx4 v[102:103], v[80:83], off offset:528

.LBB0_2483:
	s_or_b64 exec, exec, s[30:31]
	v_or_b32_e32 v80, 48, v146
	v_ashrrev_i32_e32 v81, 31, v80
	v_lshlrev_b64 v[82:83], 10, v[80:81]
	s_waitcnt lgkmcnt(0)
	v_lshl_add_u64 v[84:85], v[82:83], 0, v[144:145]
	v_lshl_add_u64 v[82:83], v[84:85], 1, s[48:49]
	s_nop 1
	v_mov_b64_e32 v[86:87], v[196:197]
	v_mov_b64_e32 v[88:89], v[198:199]
	s_and_b64 vcc, exec, s[4:5]
	s_nop 1
	v_lshlrev_b32_e32 v90, 16, v86
	v_and_b32_e32 v91, 0xffff0000, v86
	v_lshlrev_b32_e32 v86, 16, v87
	v_and_b32_e32 v87, 0xffff0000, v87
	v_lshlrev_b32_e32 v92, 16, v88
	v_and_b32_e32 v93, 0xffff0000, v88
	v_lshlrev_b32_e32 v88, 16, v89
	v_and_b32_e32 v89, 0xffff0000, v89
	v_pk_add_f32 v[78:79], v[78:79], v[86:87]
	v_pk_add_f32 v[76:77], v[76:77], v[90:91]
	v_pk_add_f32 v[74:75], v[74:75], v[88:89]
	v_pk_add_f32 v[72:73], v[72:73], v[92:93]
	v_lshl_add_u64 v[86:87], v[84:85], 2, s[60:61]
	s_cbranch_vccnz .LBB0_2485
	global_store_dwordx4 v[86:87], v[76:79], off
	global_store_dwordx4 v[86:87], v[72:75], off offset:16
.LBB0_2485:
	v_lshlrev_b64 v[84:85], 1, v[84:85]
	v_or_b32_e32 v84, 0x100, v84
	v_lshl_add_u64 v[84:85], s[48:49], 0, v[84:85]
	s_nop 1
	v_mov_b64_e32 v[88:89], v[200:201]
	v_mov_b64_e32 v[90:91], v[202:203]
	v_cvt_pk_bf16_f32 v92, v76, v77
	v_cvt_pk_bf16_f32 v93, v78, v79
	v_cvt_pk_bf16_f32 v94, v72, v73
	v_cvt_pk_bf16_f32 v95, v74, v75
	global_store_dwordx4 v[82:83], v[92:95], off
	s_and_b64 vcc, exec, s[4:5]
	s_nop 1
	v_lshlrev_b32_e32 v82, 16, v88
	v_and_b32_e32 v83, 0xffff0000, v88
	v_lshlrev_b32_e32 v88, 16, v89
	v_and_b32_e32 v89, 0xffff0000, v89
	v_lshlrev_b32_e32 v92, 16, v90
	v_and_b32_e32 v93, 0xffff0000, v90
	v_lshlrev_b32_e32 v90, 16, v91
	v_and_b32_e32 v91, 0xffff0000, v91
	v_pk_add_f32 v[70:71], v[70:71], v[88:89]
	v_pk_add_f32 v[68:69], v[68:69], v[82:83]
	v_pk_add_f32 v[66:67], v[66:67], v[90:91]
	v_pk_add_f32 v[64:65], v[64:65], v[92:93]
	s_cbranch_vccnz .LBB0_2487
	global_store_dwordx4 v[86:87], v[68:71], off offset:512
	global_store_dwordx4 v[86:87], v[64:67], off offset:528

.LBB0_2489:
	s_or_b64 exec, exec, s[30:31]
	v_add_u32_e32 v64, 0x80, v146
	v_ashrrev_i32_e32 v65, 31, v64
	v_lshlrev_b64 v[66:67], 10, v[64:65]
	s_waitcnt lgkmcnt(0)
	v_lshl_add_u64 v[68:69], v[66:67], 0, v[144:145]
	v_lshl_add_u64 v[66:67], v[68:69], 1, s[48:49]
	v_add_co_u32_e32 v204, vcc, 0x40000, v206
	s_nop 1
	v_addc_co_u32_e32 v205, vcc, 0, v207, vcc
	global_load_dwordx4 v[172:175], v[204:205], off
	v_add_co_u32_e32 v204, vcc, 0x40100, v206
	s_nop 1
	v_addc_co_u32_e32 v205, vcc, 0, v207, vcc
	global_load_dwordx4 v[176:179], v[204:205], off
	v_add_co_u32_e32 v204, vcc, 0x48000, v206
	s_nop 1
	v_addc_co_u32_e32 v205, vcc, 0, v207, vcc
	global_load_dwordx4 v[180:183], v[204:205], off
	v_add_co_u32_e32 v204, vcc, 0x48100, v206
	s_nop 1
	v_addc_co_u32_e32 v205, vcc, 0, v207, vcc
	global_load_dwordx4 v[184:187], v[204:205], off
	v_add_co_u32_e32 v204, vcc, 0x50000, v206
	s_nop 1
	v_addc_co_u32_e32 v205, vcc, 0, v207, vcc
	global_load_dwordx4 v[188:191], v[204:205], off
	v_add_co_u32_e32 v204, vcc, 0x50100, v206
	s_nop 1
	v_addc_co_u32_e32 v205, vcc, 0, v207, vcc
	global_load_dwordx4 v[192:195], v[204:205], off
	v_add_co_u32_e32 v204, vcc, 0x58000, v206
	s_nop 1
	v_addc_co_u32_e32 v205, vcc, 0, v207, vcc
	global_load_dwordx4 v[196:199], v[204:205], off
	v_add_co_u32_e32 v204, vcc, 0x58100, v206
	s_nop 1
	v_addc_co_u32_e32 v205, vcc, 0, v207, vcc
	global_load_dwordx4 v[200:203], v[204:205], off
	s_waitcnt vmcnt(0)
	s_nop 1
	v_mov_b64_e32 v[70:71], v[172:173]
	v_mov_b64_e32 v[72:73], v[174:175]
	s_and_b64 vcc, exec, s[4:5]
	s_nop 1
	v_lshlrev_b32_e32 v74, 16, v70
	v_and_b32_e32 v75, 0xffff0000, v70
	v_lshlrev_b32_e32 v70, 16, v71
	v_and_b32_e32 v71, 0xffff0000, v71
	v_lshlrev_b32_e32 v76, 16, v72
	v_and_b32_e32 v77, 0xffff0000, v72
	v_lshlrev_b32_e32 v72, 16, v73
	v_and_b32_e32 v73, 0xffff0000, v73
	v_pk_add_f32 v[62:63], v[62:63], v[70:71]
	v_pk_add_f32 v[60:61], v[60:61], v[74:75]
	v_pk_add_f32 v[58:59], v[58:59], v[72:73]
	v_pk_add_f32 v[56:57], v[56:57], v[76:77]
	v_lshl_add_u64 v[70:71], v[68:69], 2, s[60:61]
	s_cbranch_vccnz .LBB0_2491
	global_store_dwordx4 v[70:71], v[60:63], off
	global_store_dwordx4 v[70:71], v[56:59], off offset:16
.LBB0_2491:
	v_lshlrev_b64 v[68:69], 1, v[68:69]
	v_or_b32_e32 v68, 0x100, v68
	v_lshl_add_u64 v[68:69], s[48:49], 0, v[68:69]
	s_nop 1
	v_mov_b64_e32 v[72:73], v[176:177]
	v_mov_b64_e32 v[74:75], v[178:179]
	v_cvt_pk_bf16_f32 v76, v60, v61
	v_cvt_pk_bf16_f32 v77, v62, v63
	v_cvt_pk_bf16_f32 v78, v56, v57
	v_cvt_pk_bf16_f32 v79, v58, v59
	global_store_dwordx4 v[66:67], v[76:79], off
	s_and_b64 vcc, exec, s[4:5]
	s_nop 1
	v_lshlrev_b32_e32 v66, 16, v72
	v_and_b32_e32 v67, 0xffff0000, v72
	v_lshlrev_b32_e32 v72, 16, v73
	v_and_b32_e32 v73, 0xffff0000, v73
	v_lshlrev_b32_e32 v76, 16, v74
	v_and_b32_e32 v77, 0xffff0000, v74
	v_lshlrev_b32_e32 v74, 16, v75
	v_and_b32_e32 v75, 0xffff0000, v75
	v_pk_add_f32 v[54:55], v[54:55], v[72:73]
	v_pk_add_f32 v[52:53], v[52:53], v[66:67]
	v_pk_add_f32 v[50:51], v[50:51], v[74:75]
	v_pk_add_f32 v[48:49], v[48:49], v[76:77]
	s_cbranch_vccnz .LBB0_2493
	global_store_dwordx4 v[70:71], v[52:55], off offset:512
	global_store_dwordx4 v[70:71], v[48:51], off offset:528

.LBB0_2495:
	s_or_b64 exec, exec, s[30:31]
	v_add_u32_e32 v48, 0x90, v146
	v_ashrrev_i32_e32 v49, 31, v48
	v_lshlrev_b64 v[50:51], 10, v[48:49]
	s_waitcnt lgkmcnt(0)
	v_lshl_add_u64 v[52:53], v[50:51], 0, v[144:145]
	v_lshl_add_u64 v[50:51], v[52:53], 1, s[48:49]
	s_nop 1
	v_mov_b64_e32 v[54:55], v[180:181]
	v_mov_b64_e32 v[56:57], v[182:183]
	s_and_b64 vcc, exec, s[4:5]
	s_nop 1
	v_lshlrev_b32_e32 v58, 16, v54
	v_and_b32_e32 v59, 0xffff0000, v54
	v_lshlrev_b32_e32 v54, 16, v55
	v_and_b32_e32 v55, 0xffff0000, v55
	v_lshlrev_b32_e32 v60, 16, v56
	v_and_b32_e32 v61, 0xffff0000, v56
	v_lshlrev_b32_e32 v56, 16, v57
	v_and_b32_e32 v57, 0xffff0000, v57
	v_pk_add_f32 v[46:47], v[46:47], v[54:55]
	v_pk_add_f32 v[44:45], v[44:45], v[58:59]
	v_pk_add_f32 v[42:43], v[42:43], v[56:57]
	v_pk_add_f32 v[40:41], v[40:41], v[60:61]
	v_lshl_add_u64 v[54:55], v[52:53], 2, s[60:61]
	s_cbranch_vccnz .LBB0_2497
	global_store_dwordx4 v[54:55], v[44:47], off
	global_store_dwordx4 v[54:55], v[40:43], off offset:16
.LBB0_2497:
	v_lshlrev_b64 v[52:53], 1, v[52:53]
	v_or_b32_e32 v52, 0x100, v52
	v_lshl_add_u64 v[52:53], s[48:49], 0, v[52:53]
	s_nop 1
	v_mov_b64_e32 v[56:57], v[184:185]
	v_mov_b64_e32 v[58:59], v[186:187]
	v_cvt_pk_bf16_f32 v60, v44, v45
	v_cvt_pk_bf16_f32 v61, v46, v47
	v_cvt_pk_bf16_f32 v62, v40, v41
	v_cvt_pk_bf16_f32 v63, v42, v43
	global_store_dwordx4 v[50:51], v[60:63], off
	s_and_b64 vcc, exec, s[4:5]
	s_nop 1
	v_lshlrev_b32_e32 v50, 16, v56
	v_and_b32_e32 v51, 0xffff0000, v56
	v_lshlrev_b32_e32 v56, 16, v57
	v_and_b32_e32 v57, 0xffff0000, v57
	v_lshlrev_b32_e32 v60, 16, v58
	v_and_b32_e32 v61, 0xffff0000, v58
	v_lshlrev_b32_e32 v58, 16, v59
	v_and_b32_e32 v59, 0xffff0000, v59
	v_pk_add_f32 v[38:39], v[38:39], v[56:57]
	v_pk_add_f32 v[36:37], v[36:37], v[50:51]
	v_pk_add_f32 v[34:35], v[34:35], v[58:59]
	v_pk_add_f32 v[32:33], v[32:33], v[60:61]
	s_cbranch_vccnz .LBB0_2499
	global_store_dwordx4 v[54:55], v[36:39], off offset:512
	global_store_dwordx4 v[54:55], v[32:35], off offset:528

.LBB0_2501:
	s_or_b64 exec, exec, s[30:31]
	v_add_u32_e32 v32, 0xa0, v146
	v_ashrrev_i32_e32 v33, 31, v32
	v_lshlrev_b64 v[34:35], 10, v[32:33]
	s_waitcnt lgkmcnt(0)
	v_lshl_add_u64 v[36:37], v[34:35], 0, v[144:145]
	v_lshl_add_u64 v[34:35], v[36:37], 1, s[48:49]
	s_nop 1
	v_mov_b64_e32 v[38:39], v[188:189]
	v_mov_b64_e32 v[40:41], v[190:191]
	s_and_b64 vcc, exec, s[4:5]
	s_nop 1
	v_lshlrev_b32_e32 v42, 16, v38
	v_and_b32_e32 v43, 0xffff0000, v38
	v_lshlrev_b32_e32 v38, 16, v39
	v_and_b32_e32 v39, 0xffff0000, v39
	v_lshlrev_b32_e32 v44, 16, v40
	v_and_b32_e32 v45, 0xffff0000, v40
	v_lshlrev_b32_e32 v40, 16, v41
	v_and_b32_e32 v41, 0xffff0000, v41
	v_pk_add_f32 v[30:31], v[30:31], v[38:39]
	v_pk_add_f32 v[28:29], v[28:29], v[42:43]
	v_pk_add_f32 v[26:27], v[26:27], v[40:41]
	v_pk_add_f32 v[24:25], v[24:25], v[44:45]
	v_lshl_add_u64 v[38:39], v[36:37], 2, s[60:61]
	s_cbranch_vccnz .LBB0_2503
	global_store_dwordx4 v[38:39], v[28:31], off
	global_store_dwordx4 v[38:39], v[24:27], off offset:16
.LBB0_2503:
	v_lshlrev_b64 v[36:37], 1, v[36:37]
	v_or_b32_e32 v36, 0x100, v36
	v_lshl_add_u64 v[36:37], s[48:49], 0, v[36:37]
	s_nop 1
	v_mov_b64_e32 v[40:41], v[192:193]
	v_mov_b64_e32 v[42:43], v[194:195]
	v_cvt_pk_bf16_f32 v44, v28, v29
	v_cvt_pk_bf16_f32 v45, v30, v31
	v_cvt_pk_bf16_f32 v46, v24, v25
	v_cvt_pk_bf16_f32 v47, v26, v27
	global_store_dwordx4 v[34:35], v[44:47], off
	s_and_b64 vcc, exec, s[4:5]
	s_nop 1
	v_lshlrev_b32_e32 v34, 16, v40
	v_and_b32_e32 v35, 0xffff0000, v40
	v_lshlrev_b32_e32 v40, 16, v41
	v_and_b32_e32 v41, 0xffff0000, v41
	v_lshlrev_b32_e32 v44, 16, v42
	v_and_b32_e32 v45, 0xffff0000, v42
	v_lshlrev_b32_e32 v42, 16, v43
	v_and_b32_e32 v43, 0xffff0000, v43
	v_pk_add_f32 v[22:23], v[22:23], v[40:41]
	v_pk_add_f32 v[20:21], v[20:21], v[34:35]
	v_pk_add_f32 v[18:19], v[18:19], v[42:43]
	v_pk_add_f32 v[16:17], v[16:17], v[44:45]
	s_cbranch_vccnz .LBB0_2505
	global_store_dwordx4 v[38:39], v[20:23], off offset:512
	global_store_dwordx4 v[38:39], v[16:19], off offset:528

.LBB0_2507:
	s_or_b64 exec, exec, s[30:31]
	v_add_u32_e32 v16, 0xb0, v146
	v_ashrrev_i32_e32 v17, 31, v16
	v_lshlrev_b64 v[18:19], 10, v[16:17]
	s_waitcnt lgkmcnt(0)
	v_lshl_add_u64 v[20:21], v[18:19], 0, v[144:145]
	v_lshl_add_u64 v[18:19], v[20:21], 1, s[48:49]
	s_nop 1
	v_mov_b64_e32 v[22:23], v[196:197]
	v_mov_b64_e32 v[24:25], v[198:199]
	s_and_b64 vcc, exec, s[4:5]
	s_nop 1
	v_lshlrev_b32_e32 v26, 16, v22
	v_and_b32_e32 v27, 0xffff0000, v22
	v_lshlrev_b32_e32 v22, 16, v23
	v_and_b32_e32 v23, 0xffff0000, v23
	v_lshlrev_b32_e32 v28, 16, v24
	v_and_b32_e32 v29, 0xffff0000, v24
	v_lshlrev_b32_e32 v24, 16, v25
	v_and_b32_e32 v25, 0xffff0000, v25
	v_pk_add_f32 v[14:15], v[14:15], v[22:23]
	v_pk_add_f32 v[12:13], v[12:13], v[26:27]
	v_pk_add_f32 v[10:11], v[10:11], v[24:25]
	v_pk_add_f32 v[8:9], v[8:9], v[28:29]
	v_lshl_add_u64 v[22:23], v[20:21], 2, s[60:61]
	s_cbranch_vccnz .LBB0_2509
	global_store_dwordx4 v[22:23], v[12:15], off
	global_store_dwordx4 v[22:23], v[8:11], off offset:16
.LBB0_2509:
	v_lshlrev_b64 v[20:21], 1, v[20:21]
	v_or_b32_e32 v20, 0x100, v20
	v_lshl_add_u64 v[20:21], s[48:49], 0, v[20:21]
	s_nop 1
	v_mov_b64_e32 v[24:25], v[200:201]
	v_mov_b64_e32 v[26:27], v[202:203]
	v_cvt_pk_bf16_f32 v28, v12, v13
	v_cvt_pk_bf16_f32 v29, v14, v15
	v_cvt_pk_bf16_f32 v30, v8, v9
	v_cvt_pk_bf16_f32 v31, v10, v11
	global_store_dwordx4 v[18:19], v[28:31], off
	s_and_b64 vcc, exec, s[4:5]
	s_nop 1
	v_lshlrev_b32_e32 v18, 16, v24
	v_and_b32_e32 v19, 0xffff0000, v24
	v_lshlrev_b32_e32 v24, 16, v25
	v_and_b32_e32 v25, 0xffff0000, v25
	v_lshlrev_b32_e32 v28, 16, v26
	v_and_b32_e32 v29, 0xffff0000, v26
	v_lshlrev_b32_e32 v26, 16, v27
	v_and_b32_e32 v27, 0xffff0000, v27
	v_pk_add_f32 v[6:7], v[6:7], v[24:25]
	v_pk_add_f32 v[4:5], v[4:5], v[18:19]
	v_pk_add_f32 v[2:3], v[2:3], v[26:27]
	v_pk_add_f32 v[0:1], v[0:1], v[28:29]
	s_cbranch_vccnz .LBB0_2511
	global_store_dwordx4 v[22:23], v[4:7], off offset:512
	global_store_dwordx4 v[22:23], v[0:3], off offset:528
